# scan: the 16 per-step y lane-partials of a chunk are reduced together by a masked-DPP reduce-scatter (33 ops + 1 LDS write instead of 64 DPP + 16 LDS writes per chunk)
# speedup vs baseline: 1.0153x; 1.0153x over previous
.LBB0_380:
	global_load_dword v39, v[152:153], off
	v_add_u32_e32 v87, 16, v87
	v_add_u32_e32 v85, 16, v85
	v_add_u32_e32 v83, 16, v83
	v_add_u32_e32 v88, -16, v88
	v_add_u32_e32 v86, -16, v86
	v_add_u32_e32 v84, -16, v84
	v_add_u32_e32 v142, s55, v87
	v_cmp_lt_i32_e32 vcc, s2, v142
	s_nop 1
	v_cndmask_b32_e32 v143, v196, v197, vcc
	v_add_u32_e32 v143, v143, v88
	v_cndmask_b32_e64 v142, v143, v142, s[44:45]
	v_ashrrev_i32_e32 v143, 31, v142
	v_lshl_add_u64 v[142:143], v[142:143], 0, s[88:89]
	v_lshlrev_b64 v[142:143], 9, v[142:143]
	v_lshl_add_u64 v[140:141], v[152:153], 0, v[142:143]
	global_load_dwordx4 v[140:143], v[140:141], off
	v_add_u32_e32 v146, s55, v85
	v_cmp_lt_i32_e32 vcc, s2, v146
	s_nop 1
	v_cndmask_b32_e32 v147, v196, v197, vcc
	v_add_u32_e32 v147, v147, v86
	v_cndmask_b32_e64 v146, v147, v146, s[44:45]
	v_ashrrev_i32_e32 v147, 31, v146
	v_lshl_add_u64 v[146:147], v[146:147], 0, s[88:89]
	v_lshlrev_b64 v[146:147], 9, v[146:147]
	v_lshl_add_u64 v[144:145], v[154:155], 0, v[146:147]
	global_load_dwordx4 v[144:147], v[144:145], off
	v_add_u32_e32 v150, s55, v83
	v_cmp_lt_i32_e32 vcc, s2, v150
	s_nop 1
	v_cndmask_b32_e32 v151, v196, v197, vcc
	v_add_u32_e32 v151, v151, v84
	v_cndmask_b32_e64 v150, v151, v150, s[44:45]
	v_ashrrev_i32_e32 v151, 31, v150
	v_lshl_add_u64 v[150:151], v[150:151], 0, s[88:89]
	v_lshlrev_b64 v[150:151], 9, v[150:151]
	v_lshl_add_u64 v[148:149], v[156:157], 0, v[150:151]
	global_load_dwordx4 v[148:151], v[148:149], off
	global_load_dword v39, v[152:153], off
	v_add_u32_e32 v87, 16, v87
	v_add_u32_e32 v85, 16, v85
	v_add_u32_e32 v83, 16, v83
	v_add_u32_e32 v88, -16, v88
	v_add_u32_e32 v86, -16, v86
	v_add_u32_e32 v84, -16, v84
	v_add_u32_e32 v126, s55, v87
	v_cmp_lt_i32_e32 vcc, s2, v126
	s_nop 1
	v_cndmask_b32_e32 v127, v196, v197, vcc
	v_add_u32_e32 v127, v127, v88
	v_cndmask_b32_e64 v126, v127, v126, s[44:45]
	v_ashrrev_i32_e32 v127, 31, v126
	v_lshl_add_u64 v[126:127], v[126:127], 0, s[88:89]
	v_lshlrev_b64 v[126:127], 9, v[126:127]
	v_lshl_add_u64 v[124:125], v[152:153], 0, v[126:127]
	global_load_dwordx4 v[124:127], v[124:125], off
	v_add_u32_e32 v130, s55, v85
	v_cmp_lt_i32_e32 vcc, s2, v130
	s_nop 1
	v_cndmask_b32_e32 v131, v196, v197, vcc
	v_add_u32_e32 v131, v131, v86
	v_cndmask_b32_e64 v130, v131, v130, s[44:45]
	v_ashrrev_i32_e32 v131, 31, v130
	v_lshl_add_u64 v[130:131], v[130:131], 0, s[88:89]
	v_lshlrev_b64 v[130:131], 9, v[130:131]
	v_lshl_add_u64 v[128:129], v[154:155], 0, v[130:131]
	global_load_dwordx4 v[128:131], v[128:129], off
	v_add_u32_e32 v134, s55, v83
	v_cmp_lt_i32_e32 vcc, s2, v134
	s_nop 1
	v_cndmask_b32_e32 v135, v196, v197, vcc
	v_add_u32_e32 v135, v135, v84
	v_cndmask_b32_e64 v134, v135, v134, s[44:45]
	v_ashrrev_i32_e32 v135, 31, v134
	v_lshl_add_u64 v[134:135], v[134:135], 0, s[88:89]
	v_lshlrev_b64 v[134:135], 9, v[134:135]
	v_lshl_add_u64 v[132:133], v[156:157], 0, v[134:135]
	global_load_dwordx4 v[132:135], v[132:133], off
	global_load_dword v39, v[152:153], off
	v_add_u32_e32 v87, 16, v87
	v_add_u32_e32 v85, 16, v85
	v_add_u32_e32 v83, 16, v83
	v_add_u32_e32 v88, -16, v88
	v_add_u32_e32 v86, -16, v86
	v_add_u32_e32 v84, -16, v84
	v_add_u32_e32 v230, s55, v88
	v_cndmask_b32_e64 v230, v230, v87, s[44:45]
	v_ashrrev_i32_e32 v231, 31, v230
	v_lshl_add_u64 v[230:231], v[230:231], 0, s[88:89]
	v_lshlrev_b64 v[230:231], 9, v[230:231]
	v_lshl_add_u64 v[224:225], v[152:153], 0, v[230:231]
	v_add_u32_e32 v230, s55, v86
	v_cndmask_b32_e64 v230, v230, v85, s[44:45]
	v_ashrrev_i32_e32 v231, 31, v230
	v_lshl_add_u64 v[230:231], v[230:231], 0, s[88:89]
	v_lshlrev_b64 v[230:231], 9, v[230:231]
	v_lshl_add_u64 v[226:227], v[154:155], 0, v[230:231]
	v_add_u32_e32 v230, s55, v84
	v_cndmask_b32_e64 v230, v230, v83, s[44:45]
	v_ashrrev_i32_e32 v231, 31, v230
	v_lshl_add_u64 v[230:231], v[230:231], 0, s[88:89]
	v_lshlrev_b64 v[230:231], 9, v[230:231]
	v_lshl_add_u64 v[228:229], v[156:157], 0, v[230:231]
	v_lshlrev_b32_e32 v172, 6, v73
	v_lshl_add_u32 v172, v72, 2, v172

; __device__ __forceinline__ void rwkv_scan_unit(const Params& p, int unit, char* smem) {
;     ...
;         const char* lb = smem + st + ks * 16;
;         const char* vb = smem + st + 1280 + rl * 4;
;         float* yl = (float*)(smem + YOFF + (ci & 1) * 1024) + rl;
;         f32x4 e4 = *(const f32x4*)(lb), kd4 = *(const f32x4*)(lb + 256), ka4 = *(const f32x4*)(lb + 512), r4 = *(const f32x4*)(lb + 768), kk4 = *(const f32x4*)(lb + 1024);
;         float vv = *(const float*)vb;
;         f32x2 sA = {s0, s1}, sB = {s2, s3};
;         float c;
;         { const f32x2 cv = sA * (f32x2){kk4[0], kk4[1]} + sB * (f32x2){kk4[2], kk4[3]}; c = red16(cv[0] + cv[1]); }
; #pragma unroll
;         for (int u = 0; u < SCH; ++u) {
;             f32x4 ne = e4, nkd = kd4, nka = ka4, nr = r4, nkk = kk4; float nv = vv;
;             if (u + 1 < SCH) { const char* q = lb + (u + 1) * STEPB;
;                 ne = *(const f32x4*)(q); nkd = *(const f32x4*)(q + 256); nka = *(const f32x4*)(q + 512); nr = *(const f32x4*)(q + 768); nkk = *(const f32x4*)(q + 1024);
;                 nv = *(const float*)(vb + (u + 1) * STEPB); }
;             const f32x2 v2 = {vv, vv}, c2 = {c, c};
;             const f32x2 tA = __builtin_elementwise_fma(v2, (f32x2){kd4[0], kd4[1]}, __builtin_elementwise_fma(-sA, (f32x2){e4[0], e4[1]}, sA));
;             const f32x2 tB = __builtin_elementwise_fma(v2, (f32x2){kd4[2], kd4[3]}, __builtin_elementwise_fma(-sB, (f32x2){e4[2], e4[3]}, sB));
;             sA = __builtin_elementwise_fma(-c2, (f32x2){ka4[0], ka4[1]}, tA);
;             sB = __builtin_elementwise_fma(-c2, (f32x2){ka4[2], ka4[3]}, tB);
;             const f32x2 yv = __builtin_elementwise_fma(sB, (f32x2){r4[2], r4[3]}, sA * (f32x2){r4[0], r4[1]});
;             float y = yv[0] + yv[1];
;             if (u + 1 < SCH) {
;                 const f32x2 cv = __builtin_elementwise_fma(sB, (f32x2){nkk[2], nkk[3]}, sA * (f32x2){nkk[0], nkk[1]});
;                 float cn = cv[0] + cv[1];
;                 cn = DPP_ADD(cn, 0xB1);  y = DPP_ADD(y, 0xB1);
;                 cn = DPP_ADD(cn, 0x4E);  y = DPP_ADD(y, 0x4E);
;                 cn = DPP_ADD(cn, 0x141); y = DPP_ADD(y, 0x141);
;                 cn = DPP_ADD(cn, 0x140); y = DPP_ADD(y, 0x140);
;                 c = cn;
;             } else y = red16(y);
;             if (ks == 0) yl[u * 16] = y;
.Lsc_p0_body:
	s_add_i32 s30, s64, -1
	s_and_b32 s30, s30, 1
	s_mul_i32 s52, s30, 0x5400
	v_or_b32_e32 v91, s52, v80
	v_add_u32_e32 v92, s52, v81
	ds_read_b128 v[32:35], v91 offset:1024
	ds_read_b128 v[12:15], v91 offset:0
	ds_read_b128 v[16:19], v91 offset:256
	ds_read_b32 v36, v92 offset:1280
	ds_read_b128 v[24:27], v91 offset:512
	ds_read_b128 v[28:31], v91 offset:768
	ds_read_b128 v[40:43], v91 offset:1344
	ds_read_b128 v[60:63], v91 offset:1856
	ds_read_b128 v[44:47], v91 offset:1600
	ds_read_b128 v[94:97], v91 offset:2368
	ds_read_b32 v38, v92 offset:2624
	ds_read_b128 v[64:67], v91 offset:2112
	s_lshl_b32 s52, s30, 10
	s_waitcnt lgkmcnt(11)
	v_pk_mul_f32 v[32:33], v[20:21], v[32:33]
	s_waitcnt lgkmcnt(10)
	v_pk_fma_f32 v[12:13], v[20:21], v[12:13], v[20:21] neg_lo:[1,0,0] neg_hi:[1,0,0]
	v_pk_fma_f32 v[32:33], v[22:23], v[34:35], v[32:33]
	v_pk_fma_f32 v[14:15], v[22:23], v[14:15], v[22:23] neg_lo:[1,0,0] neg_hi:[1,0,0]
	v_add_f32_e32 v34, v32, v33
	s_waitcnt lgkmcnt(8)
	v_pk_fma_f32 v[12:13], v[36:37], v[16:17], v[12:13] op_sel_hi:[0,1,1]
	v_pk_fma_f32 v[14:15], v[36:37], v[18:19], v[14:15] op_sel_hi:[0,1,1]
	v_add_f32_dpp v35, v34, v34 quad_perm:[1,0,3,2] row_mask:0xf bank_mask:0xf bound_ctrl:1
	s_nop 1
	v_add_f32_dpp v34, v35, v35 quad_perm:[2,3,0,1] row_mask:0xf bank_mask:0xf bound_ctrl:1
	s_nop 1
	v_add_f32_dpp v35, v34, v34 row_half_mirror row_mask:0xf bank_mask:0xf bound_ctrl:1
	s_nop 1
	v_add_f32_dpp v90, v35, v35 row_mirror row_mask:0xf bank_mask:0xf bound_ctrl:1
	ds_read_b128 v[16:19], v91 offset:2944
	ds_read_b128 v[32:35], v91 offset:3712
	ds_read_b32 v36, v92 offset:3968
	s_waitcnt lgkmcnt(10)
	v_pk_fma_f32 v[20:21], v[90:91], v[24:25], v[12:13] op_sel_hi:[0,1,1] neg_lo:[1,0,0] neg_hi:[1,0,0]
	v_pk_fma_f32 v[22:23], v[90:91], v[26:27], v[14:15] op_sel_hi:[0,1,1] neg_lo:[1,0,0] neg_hi:[1,0,0]
	ds_read_b128 v[12:15], v91 offset:2688
	ds_read_b128 v[24:27], v91 offset:3200
	s_waitcnt lgkmcnt(7)
	v_pk_mul_f32 v[94:95], v[20:21], v[94:95]
	v_pk_mul_f32 v[28:29], v[20:21], v[28:29]
	v_pk_fma_f32 v[94:95], v[22:23], v[96:97], v[94:95]
	v_pk_fma_f32 v[28:29], v[22:23], v[30:31], v[28:29]
	v_add_f32_e32 v96, v94, v95
	v_add_f32_e32 v232, v28, v29
	v_pk_fma_f32 v[40:41], v[20:21], v[40:41], v[20:21] neg_lo:[1,0,0] neg_hi:[1,0,0]
	v_add_f32_dpp v97, v96, v96 quad_perm:[1,0,3,2] row_mask:0xf bank_mask:0xf bound_ctrl:1
	v_pk_fma_f32 v[42:43], v[22:23], v[42:43], v[22:23] neg_lo:[1,0,0] neg_hi:[1,0,0]
	s_nop 0
	v_add_f32_dpp v96, v97, v97 quad_perm:[2,3,0,1] row_mask:0xf bank_mask:0xf bound_ctrl:1
	s_waitcnt lgkmcnt(6)
	v_pk_fma_f32 v[40:41], v[38:39], v[44:45], v[40:41] op_sel_hi:[0,1,1]
	s_nop 0
	v_add_f32_dpp v97, v96, v96 row_half_mirror row_mask:0xf bank_mask:0xf bound_ctrl:1
	v_pk_fma_f32 v[42:43], v[38:39], v[46:47], v[42:43] op_sel_hi:[0,1,1]
	s_nop 0
	v_add_f32_dpp v90, v97, v97 row_mirror row_mask:0xf bank_mask:0xf bound_ctrl:1
	ds_read_b128 v[28:31], v91 offset:3456
	v_pk_fma_f32 v[20:21], v[90:91], v[60:61], v[40:41] op_sel_hi:[0,1,1] neg_lo:[1,0,0] neg_hi:[1,0,0]
	v_pk_fma_f32 v[22:23], v[90:91], v[62:63], v[42:43] op_sel_hi:[0,1,1] neg_lo:[1,0,0] neg_hi:[1,0,0]
	ds_read_b128 v[40:43], v91 offset:4032
	ds_read_b128 v[60:63], v91 offset:4544
	s_waitcnt lgkmcnt(4)
	v_pk_mul_f32 v[32:33], v[20:21], v[32:33]
	v_pk_mul_f32 v[64:65], v[20:21], v[64:65]
	v_pk_fma_f32 v[32:33], v[22:23], v[34:35], v[32:33]
	v_pk_fma_f32 v[64:65], v[22:23], v[66:67], v[64:65]
	v_add_f32_e32 v34, v32, v33
	v_add_f32_e32 v233, v64, v65
	v_pk_fma_f32 v[12:13], v[20:21], v[12:13], v[20:21] neg_lo:[1,0,0] neg_hi:[1,0,0]
	v_add_f32_dpp v35, v34, v34 quad_perm:[1,0,3,2] row_mask:0xf bank_mask:0xf bound_ctrl:1
	v_pk_fma_f32 v[14:15], v[22:23], v[14:15], v[22:23] neg_lo:[1,0,0] neg_hi:[1,0,0]
	ds_read_b128 v[44:47], v91 offset:4288
	v_add_f32_dpp v34, v35, v35 quad_perm:[2,3,0,1] row_mask:0xf bank_mask:0xf bound_ctrl:1
	v_pk_fma_f32 v[12:13], v[36:37], v[16:17], v[12:13] op_sel_hi:[0,1,1]
	ds_read_b128 v[94:97], v91 offset:5056
	v_add_f32_dpp v35, v34, v34 row_half_mirror row_mask:0xf bank_mask:0xf bound_ctrl:1
	v_pk_fma_f32 v[14:15], v[36:37], v[18:19], v[14:15] op_sel_hi:[0,1,1]
	ds_read_b32 v38, v92 offset:5312
	v_add_f32_dpp v90, v35, v35 row_mirror row_mask:0xf bank_mask:0xf bound_ctrl:1
	ds_read_b128 v[64:67], v91 offset:4800
	s_waitcnt lgkmcnt(7)
	v_pk_fma_f32 v[20:21], v[90:91], v[24:25], v[12:13] op_sel_hi:[0,1,1] neg_lo:[1,0,0] neg_hi:[1,0,0]
	v_pk_fma_f32 v[22:23], v[90:91], v[26:27], v[14:15] op_sel_hi:[0,1,1] neg_lo:[1,0,0] neg_hi:[1,0,0]
	ds_read_b128 v[12:15], v91 offset:5376
	ds_read_b128 v[24:27], v91 offset:5888
	s_waitcnt lgkmcnt(3)
	v_pk_mul_f32 v[94:95], v[20:21], v[94:95]
	v_pk_mul_f32 v[28:29], v[20:21], v[28:29]
	v_pk_fma_f32 v[94:95], v[22:23], v[96:97], v[94:95]
	v_pk_fma_f32 v[28:29], v[22:23], v[30:31], v[28:29]
	v_add_f32_e32 v96, v94, v95
	v_add_f32_e32 v234, v28, v29
	v_pk_fma_f32 v[40:41], v[20:21], v[40:41], v[20:21] neg_lo:[1,0,0] neg_hi:[1,0,0]
	v_add_f32_dpp v97, v96, v96 quad_perm:[1,0,3,2] row_mask:0xf bank_mask:0xf bound_ctrl:1
	v_pk_fma_f32 v[42:43], v[22:23], v[42:43], v[22:23] neg_lo:[1,0,0] neg_hi:[1,0,0]
	ds_read_b128 v[16:19], v91 offset:5632
	v_add_f32_dpp v96, v97, v97 quad_perm:[2,3,0,1] row_mask:0xf bank_mask:0xf bound_ctrl:1
	v_pk_fma_f32 v[40:41], v[38:39], v[44:45], v[40:41] op_sel_hi:[0,1,1]
	ds_read_b128 v[32:35], v91 offset:6400
	v_add_f32_dpp v97, v96, v96 row_half_mirror row_mask:0xf bank_mask:0xf bound_ctrl:1
	v_pk_fma_f32 v[42:43], v[38:39], v[46:47], v[42:43] op_sel_hi:[0,1,1]
	ds_read_b32 v36, v92 offset:6656
	v_add_f32_dpp v90, v97, v97 row_mirror row_mask:0xf bank_mask:0xf bound_ctrl:1
	ds_read_b128 v[28:31], v91 offset:6144
	v_pk_fma_f32 v[20:21], v[90:91], v[60:61], v[40:41] op_sel_hi:[0,1,1] neg_lo:[1,0,0] neg_hi:[1,0,0]
	v_pk_fma_f32 v[22:23], v[90:91], v[62:63], v[42:43] op_sel_hi:[0,1,1] neg_lo:[1,0,0] neg_hi:[1,0,0]
	ds_read_b128 v[40:43], v91 offset:6720
	ds_read_b128 v[60:63], v91 offset:7232
	s_waitcnt lgkmcnt(3)
; __device__ __forceinline__ void rwkv_scan_unit(const Params& p, int unit, char* smem) {
;     ...
;         const char* lb = smem + st + ks * 16;
;         const char* vb = smem + st + 1280 + rl * 4;
;         float* yl = (float*)(smem + YOFF + (ci & 1) * 1024) + rl;
;         f32x4 e4 = *(const f32x4*)(lb), kd4 = *(const f32x4*)(lb + 256), ka4 = *(const f32x4*)(lb + 512), r4 = *(const f32x4*)(lb + 768), kk4 = *(const f32x4*)(lb + 1024);
;         float vv = *(const float*)vb;
;         f32x2 sA = {s0, s1}, sB = {s2, s3};
;         float c;
;         { const f32x2 cv = sA * (f32x2){kk4[0], kk4[1]} + sB * (f32x2){kk4[2], kk4[3]}; c = red16(cv[0] + cv[1]); }
; #pragma unroll
;         for (int u = 0; u < SCH; ++u) {
;             f32x4 ne = e4, nkd = kd4, nka = ka4, nr = r4, nkk = kk4; float nv = vv;
;             if (u + 1 < SCH) { const char* q = lb + (u + 1) * STEPB;
;                 ne = *(const f32x4*)(q); nkd = *(const f32x4*)(q + 256); nka = *(const f32x4*)(q + 512); nr = *(const f32x4*)(q + 768); nkk = *(const f32x4*)(q + 1024);
;                 nv = *(const float*)(vb + (u + 1) * STEPB); }
;             const f32x2 v2 = {vv, vv}, c2 = {c, c};
;             const f32x2 tA = __builtin_elementwise_fma(v2, (f32x2){kd4[0], kd4[1]}, __builtin_elementwise_fma(-sA, (f32x2){e4[0], e4[1]}, sA));
;             const f32x2 tB = __builtin_elementwise_fma(v2, (f32x2){kd4[2], kd4[3]}, __builtin_elementwise_fma(-sB, (f32x2){e4[2], e4[3]}, sB));
;             sA = __builtin_elementwise_fma(-c2, (f32x2){ka4[0], ka4[1]}, tA);
;             sB = __builtin_elementwise_fma(-c2, (f32x2){ka4[2], ka4[3]}, tB);
;             const f32x2 yv = __builtin_elementwise_fma(sB, (f32x2){r4[2], r4[3]}, sA * (f32x2){r4[0], r4[1]});
;             float y = yv[0] + yv[1];
;             if (u + 1 < SCH) {
;                 const f32x2 cv = __builtin_elementwise_fma(sB, (f32x2){nkk[2], nkk[3]}, sA * (f32x2){nkk[0], nkk[1]});
;                 float cn = cv[0] + cv[1];
;                 cn = DPP_ADD(cn, 0xB1);  y = DPP_ADD(y, 0xB1);
;                 cn = DPP_ADD(cn, 0x4E);  y = DPP_ADD(y, 0x4E);
;                 cn = DPP_ADD(cn, 0x141); y = DPP_ADD(y, 0x141);
;                 cn = DPP_ADD(cn, 0x140); y = DPP_ADD(y, 0x140);
;                 c = cn;
;             } else y = red16(y);
;             if (ks == 0) yl[u * 16] = y;
	v_pk_mul_f32 v[32:33], v[20:21], v[32:33]
	v_pk_mul_f32 v[64:65], v[20:21], v[64:65]
	v_pk_fma_f32 v[32:33], v[22:23], v[34:35], v[32:33]
	v_pk_fma_f32 v[64:65], v[22:23], v[66:67], v[64:65]
	v_add_f32_e32 v34, v32, v33
	v_add_f32_e32 v235, v64, v65
	v_pk_fma_f32 v[12:13], v[20:21], v[12:13], v[20:21] neg_lo:[1,0,0] neg_hi:[1,0,0]
	v_add_f32_dpp v35, v34, v34 quad_perm:[1,0,3,2] row_mask:0xf bank_mask:0xf bound_ctrl:1
	v_pk_fma_f32 v[14:15], v[22:23], v[14:15], v[22:23] neg_lo:[1,0,0] neg_hi:[1,0,0]
	ds_read_b128 v[44:47], v91 offset:6976
	v_add_f32_dpp v34, v35, v35 quad_perm:[2,3,0,1] row_mask:0xf bank_mask:0xf bound_ctrl:1
	v_pk_fma_f32 v[12:13], v[36:37], v[16:17], v[12:13] op_sel_hi:[0,1,1]
	ds_read_b128 v[94:97], v91 offset:7744
	v_add_f32_dpp v35, v34, v34 row_half_mirror row_mask:0xf bank_mask:0xf bound_ctrl:1
	v_pk_fma_f32 v[14:15], v[36:37], v[18:19], v[14:15] op_sel_hi:[0,1,1]
	ds_read_b32 v38, v92 offset:8000
	v_add_f32_dpp v90, v35, v35 row_mirror row_mask:0xf bank_mask:0xf bound_ctrl:1
	ds_read_b128 v[64:67], v91 offset:7488
	v_pk_fma_f32 v[20:21], v[90:91], v[24:25], v[12:13] op_sel_hi:[0,1,1] neg_lo:[1,0,0] neg_hi:[1,0,0]
	v_pk_fma_f32 v[22:23], v[90:91], v[26:27], v[14:15] op_sel_hi:[0,1,1] neg_lo:[1,0,0] neg_hi:[1,0,0]
	ds_read_b128 v[12:15], v91 offset:8064
	ds_read_b128 v[24:27], v91 offset:8576
	s_waitcnt lgkmcnt(3)
	v_pk_mul_f32 v[94:95], v[20:21], v[94:95]
	v_pk_mul_f32 v[28:29], v[20:21], v[28:29]
	v_pk_fma_f32 v[94:95], v[22:23], v[96:97], v[94:95]
	v_pk_fma_f32 v[28:29], v[22:23], v[30:31], v[28:29]
	v_add_f32_e32 v96, v94, v95
	v_add_f32_e32 v236, v28, v29
	v_pk_fma_f32 v[40:41], v[20:21], v[40:41], v[20:21] neg_lo:[1,0,0] neg_hi:[1,0,0]
	v_add_f32_dpp v97, v96, v96 quad_perm:[1,0,3,2] row_mask:0xf bank_mask:0xf bound_ctrl:1
	v_pk_fma_f32 v[42:43], v[22:23], v[42:43], v[22:23] neg_lo:[1,0,0] neg_hi:[1,0,0]
	ds_read_b128 v[16:19], v91 offset:8320
	v_add_f32_dpp v96, v97, v97 quad_perm:[2,3,0,1] row_mask:0xf bank_mask:0xf bound_ctrl:1
	v_pk_fma_f32 v[40:41], v[38:39], v[44:45], v[40:41] op_sel_hi:[0,1,1]
	ds_read_b128 v[32:35], v91 offset:9088
	v_add_f32_dpp v97, v96, v96 row_half_mirror row_mask:0xf bank_mask:0xf bound_ctrl:1
	v_pk_fma_f32 v[42:43], v[38:39], v[46:47], v[42:43] op_sel_hi:[0,1,1]
	ds_read_b32 v36, v92 offset:9344
	v_add_f32_dpp v90, v97, v97 row_mirror row_mask:0xf bank_mask:0xf bound_ctrl:1
	ds_read_b128 v[28:31], v91 offset:8832
	v_pk_fma_f32 v[20:21], v[90:91], v[60:61], v[40:41] op_sel_hi:[0,1,1] neg_lo:[1,0,0] neg_hi:[1,0,0]
	v_pk_fma_f32 v[22:23], v[90:91], v[62:63], v[42:43] op_sel_hi:[0,1,1] neg_lo:[1,0,0] neg_hi:[1,0,0]
	ds_read_b128 v[40:43], v91 offset:9408
	ds_read_b128 v[60:63], v91 offset:9920
	s_waitcnt lgkmcnt(3)
	v_pk_mul_f32 v[32:33], v[20:21], v[32:33]
	v_pk_mul_f32 v[64:65], v[20:21], v[64:65]
	v_pk_fma_f32 v[32:33], v[22:23], v[34:35], v[32:33]
	v_pk_fma_f32 v[64:65], v[22:23], v[66:67], v[64:65]
	v_add_f32_e32 v34, v32, v33
	v_add_f32_e32 v237, v64, v65
	v_pk_fma_f32 v[12:13], v[20:21], v[12:13], v[20:21] neg_lo:[1,0,0] neg_hi:[1,0,0]
	v_add_f32_dpp v35, v34, v34 quad_perm:[1,0,3,2] row_mask:0xf bank_mask:0xf bound_ctrl:1
	v_pk_fma_f32 v[14:15], v[22:23], v[14:15], v[22:23] neg_lo:[1,0,0] neg_hi:[1,0,0]
	ds_read_b128 v[44:47], v91 offset:9664
	v_add_f32_dpp v34, v35, v35 quad_perm:[2,3,0,1] row_mask:0xf bank_mask:0xf bound_ctrl:1
	v_pk_fma_f32 v[12:13], v[36:37], v[16:17], v[12:13] op_sel_hi:[0,1,1]
	ds_read_b128 v[94:97], v91 offset:10432
	v_add_f32_dpp v35, v34, v34 row_half_mirror row_mask:0xf bank_mask:0xf bound_ctrl:1
	v_pk_fma_f32 v[14:15], v[36:37], v[18:19], v[14:15] op_sel_hi:[0,1,1]
	ds_read_b32 v38, v92 offset:10688
	v_add_f32_dpp v90, v35, v35 row_mirror row_mask:0xf bank_mask:0xf bound_ctrl:1
	ds_read_b128 v[64:67], v91 offset:10176
	v_pk_fma_f32 v[20:21], v[90:91], v[24:25], v[12:13] op_sel_hi:[0,1,1] neg_lo:[1,0,0] neg_hi:[1,0,0]
	v_pk_fma_f32 v[22:23], v[90:91], v[26:27], v[14:15] op_sel_hi:[0,1,1] neg_lo:[1,0,0] neg_hi:[1,0,0]
	ds_read_b128 v[12:15], v91 offset:10752
	ds_read_b128 v[24:27], v91 offset:11264
	s_waitcnt lgkmcnt(3)
	v_pk_mul_f32 v[94:95], v[20:21], v[94:95]
	v_pk_mul_f32 v[28:29], v[20:21], v[28:29]
	v_pk_fma_f32 v[94:95], v[22:23], v[96:97], v[94:95]
	v_pk_fma_f32 v[28:29], v[22:23], v[30:31], v[28:29]
	v_add_f32_e32 v96, v94, v95
	v_add_f32_e32 v238, v28, v29
	v_pk_fma_f32 v[40:41], v[20:21], v[40:41], v[20:21] neg_lo:[1,0,0] neg_hi:[1,0,0]
	v_add_f32_dpp v97, v96, v96 quad_perm:[1,0,3,2] row_mask:0xf bank_mask:0xf bound_ctrl:1
	v_pk_fma_f32 v[42:43], v[22:23], v[42:43], v[22:23] neg_lo:[1,0,0] neg_hi:[1,0,0]
	ds_read_b128 v[16:19], v91 offset:11008
	v_add_f32_dpp v96, v97, v97 quad_perm:[2,3,0,1] row_mask:0xf bank_mask:0xf bound_ctrl:1
	v_pk_fma_f32 v[40:41], v[38:39], v[44:45], v[40:41] op_sel_hi:[0,1,1]
	ds_read_b128 v[32:35], v91 offset:11776
	v_add_f32_dpp v97, v96, v96 row_half_mirror row_mask:0xf bank_mask:0xf bound_ctrl:1
	v_pk_fma_f32 v[42:43], v[38:39], v[46:47], v[42:43] op_sel_hi:[0,1,1]
	ds_read_b32 v36, v92 offset:12032
	v_add_f32_dpp v90, v97, v97 row_mirror row_mask:0xf bank_mask:0xf bound_ctrl:1
	ds_read_b128 v[28:31], v91 offset:11520
	v_pk_fma_f32 v[20:21], v[90:91], v[60:61], v[40:41] op_sel_hi:[0,1,1] neg_lo:[1,0,0] neg_hi:[1,0,0]
	v_pk_fma_f32 v[22:23], v[90:91], v[62:63], v[42:43] op_sel_hi:[0,1,1] neg_lo:[1,0,0] neg_hi:[1,0,0]
	ds_read_b128 v[40:43], v91 offset:12096
	ds_read_b128 v[60:63], v91 offset:12608
	s_waitcnt lgkmcnt(3)
; __device__ __forceinline__ void rwkv_scan_unit(const Params& p, int unit, char* smem) {
;     ...
;         const char* lb = smem + st + ks * 16;
;         const char* vb = smem + st + 1280 + rl * 4;
;         float* yl = (float*)(smem + YOFF + (ci & 1) * 1024) + rl;
;         f32x4 e4 = *(const f32x4*)(lb), kd4 = *(const f32x4*)(lb + 256), ka4 = *(const f32x4*)(lb + 512), r4 = *(const f32x4*)(lb + 768), kk4 = *(const f32x4*)(lb + 1024);
;         float vv = *(const float*)vb;
;         f32x2 sA = {s0, s1}, sB = {s2, s3};
;         float c;
;         { const f32x2 cv = sA * (f32x2){kk4[0], kk4[1]} + sB * (f32x2){kk4[2], kk4[3]}; c = red16(cv[0] + cv[1]); }
; #pragma unroll
;         for (int u = 0; u < SCH; ++u) {
;             f32x4 ne = e4, nkd = kd4, nka = ka4, nr = r4, nkk = kk4; float nv = vv;
;             if (u + 1 < SCH) { const char* q = lb + (u + 1) * STEPB;
;                 ne = *(const f32x4*)(q); nkd = *(const f32x4*)(q + 256); nka = *(const f32x4*)(q + 512); nr = *(const f32x4*)(q + 768); nkk = *(const f32x4*)(q + 1024);
;                 nv = *(const float*)(vb + (u + 1) * STEPB); }
;             const f32x2 v2 = {vv, vv}, c2 = {c, c};
;             const f32x2 tA = __builtin_elementwise_fma(v2, (f32x2){kd4[0], kd4[1]}, __builtin_elementwise_fma(-sA, (f32x2){e4[0], e4[1]}, sA));
;             const f32x2 tB = __builtin_elementwise_fma(v2, (f32x2){kd4[2], kd4[3]}, __builtin_elementwise_fma(-sB, (f32x2){e4[2], e4[3]}, sB));
;             sA = __builtin_elementwise_fma(-c2, (f32x2){ka4[0], ka4[1]}, tA);
;             sB = __builtin_elementwise_fma(-c2, (f32x2){ka4[2], ka4[3]}, tB);
;             const f32x2 yv = __builtin_elementwise_fma(sB, (f32x2){r4[2], r4[3]}, sA * (f32x2){r4[0], r4[1]});
;             float y = yv[0] + yv[1];
;             if (u + 1 < SCH) {
;                 const f32x2 cv = __builtin_elementwise_fma(sB, (f32x2){nkk[2], nkk[3]}, sA * (f32x2){nkk[0], nkk[1]});
;                 float cn = cv[0] + cv[1];
;                 cn = DPP_ADD(cn, 0xB1);  y = DPP_ADD(y, 0xB1);
;                 cn = DPP_ADD(cn, 0x4E);  y = DPP_ADD(y, 0x4E);
;                 cn = DPP_ADD(cn, 0x141); y = DPP_ADD(y, 0x141);
;                 cn = DPP_ADD(cn, 0x140); y = DPP_ADD(y, 0x140);
;                 c = cn;
;             } else y = red16(y);
;             if (ks == 0) yl[u * 16] = y;
	v_pk_mul_f32 v[32:33], v[20:21], v[32:33]
	v_pk_mul_f32 v[64:65], v[20:21], v[64:65]
	v_pk_fma_f32 v[32:33], v[22:23], v[34:35], v[32:33]
	v_pk_fma_f32 v[64:65], v[22:23], v[66:67], v[64:65]
	v_add_f32_e32 v34, v32, v33
	v_add_f32_e32 v239, v64, v65
	v_pk_fma_f32 v[12:13], v[20:21], v[12:13], v[20:21] neg_lo:[1,0,0] neg_hi:[1,0,0]
	v_add_f32_dpp v35, v34, v34 quad_perm:[1,0,3,2] row_mask:0xf bank_mask:0xf bound_ctrl:1
	v_pk_fma_f32 v[14:15], v[22:23], v[14:15], v[22:23] neg_lo:[1,0,0] neg_hi:[1,0,0]
	ds_read_b128 v[44:47], v91 offset:12352
	v_add_f32_dpp v34, v35, v35 quad_perm:[2,3,0,1] row_mask:0xf bank_mask:0xf bound_ctrl:1
	v_pk_fma_f32 v[12:13], v[36:37], v[16:17], v[12:13] op_sel_hi:[0,1,1]
	ds_read_b128 v[94:97], v91 offset:13120
	v_add_f32_dpp v35, v34, v34 row_half_mirror row_mask:0xf bank_mask:0xf bound_ctrl:1
	v_pk_fma_f32 v[14:15], v[36:37], v[18:19], v[14:15] op_sel_hi:[0,1,1]
	ds_read_b32 v38, v92 offset:13376
	v_add_f32_dpp v90, v35, v35 row_mirror row_mask:0xf bank_mask:0xf bound_ctrl:1
	ds_read_b128 v[64:67], v91 offset:12864
	v_pk_fma_f32 v[20:21], v[90:91], v[24:25], v[12:13] op_sel_hi:[0,1,1] neg_lo:[1,0,0] neg_hi:[1,0,0]
	v_pk_fma_f32 v[22:23], v[90:91], v[26:27], v[14:15] op_sel_hi:[0,1,1] neg_lo:[1,0,0] neg_hi:[1,0,0]
	ds_read_b128 v[12:15], v91 offset:13440
	ds_read_b128 v[24:27], v91 offset:13952
	s_waitcnt lgkmcnt(3)
	v_pk_mul_f32 v[94:95], v[20:21], v[94:95]
	v_pk_mul_f32 v[28:29], v[20:21], v[28:29]
	v_pk_fma_f32 v[94:95], v[22:23], v[96:97], v[94:95]
	v_pk_fma_f32 v[28:29], v[22:23], v[30:31], v[28:29]
	v_add_f32_e32 v96, v94, v95
	v_add_f32_e32 v240, v28, v29
	v_pk_fma_f32 v[40:41], v[20:21], v[40:41], v[20:21] neg_lo:[1,0,0] neg_hi:[1,0,0]
	v_add_f32_dpp v97, v96, v96 quad_perm:[1,0,3,2] row_mask:0xf bank_mask:0xf bound_ctrl:1
	v_pk_fma_f32 v[42:43], v[22:23], v[42:43], v[22:23] neg_lo:[1,0,0] neg_hi:[1,0,0]
	ds_read_b128 v[16:19], v91 offset:13696
	v_add_f32_dpp v96, v97, v97 quad_perm:[2,3,0,1] row_mask:0xf bank_mask:0xf bound_ctrl:1
	v_pk_fma_f32 v[40:41], v[38:39], v[44:45], v[40:41] op_sel_hi:[0,1,1]
	ds_read_b128 v[32:35], v91 offset:14464
	v_add_f32_dpp v97, v96, v96 row_half_mirror row_mask:0xf bank_mask:0xf bound_ctrl:1
	v_pk_fma_f32 v[42:43], v[38:39], v[46:47], v[42:43] op_sel_hi:[0,1,1]
	ds_read_b32 v36, v92 offset:14720
	v_add_f32_dpp v90, v97, v97 row_mirror row_mask:0xf bank_mask:0xf bound_ctrl:1
	ds_read_b128 v[28:31], v91 offset:14208
	v_pk_fma_f32 v[20:21], v[90:91], v[60:61], v[40:41] op_sel_hi:[0,1,1] neg_lo:[1,0,0] neg_hi:[1,0,0]
	v_pk_fma_f32 v[22:23], v[90:91], v[62:63], v[42:43] op_sel_hi:[0,1,1] neg_lo:[1,0,0] neg_hi:[1,0,0]
	ds_read_b128 v[40:43], v91 offset:14784
	ds_read_b128 v[60:63], v91 offset:15296
	s_waitcnt lgkmcnt(3)
	v_pk_mul_f32 v[32:33], v[20:21], v[32:33]
	v_pk_mul_f32 v[64:65], v[20:21], v[64:65]
	v_pk_fma_f32 v[32:33], v[22:23], v[34:35], v[32:33]
	v_pk_fma_f32 v[64:65], v[22:23], v[66:67], v[64:65]
	v_add_f32_e32 v34, v32, v33
	v_add_f32_e32 v241, v64, v65
	v_pk_fma_f32 v[12:13], v[20:21], v[12:13], v[20:21] neg_lo:[1,0,0] neg_hi:[1,0,0]
	v_add_f32_dpp v35, v34, v34 quad_perm:[1,0,3,2] row_mask:0xf bank_mask:0xf bound_ctrl:1
	v_pk_fma_f32 v[14:15], v[22:23], v[14:15], v[22:23] neg_lo:[1,0,0] neg_hi:[1,0,0]
	ds_read_b128 v[44:47], v91 offset:15040
	v_add_f32_dpp v34, v35, v35 quad_perm:[2,3,0,1] row_mask:0xf bank_mask:0xf bound_ctrl:1
	v_pk_fma_f32 v[12:13], v[36:37], v[16:17], v[12:13] op_sel_hi:[0,1,1]
	ds_read_b128 v[94:97], v91 offset:15808
	v_add_f32_dpp v35, v34, v34 row_half_mirror row_mask:0xf bank_mask:0xf bound_ctrl:1
	v_pk_fma_f32 v[14:15], v[36:37], v[18:19], v[14:15] op_sel_hi:[0,1,1]
	ds_read_b32 v38, v92 offset:16064
	v_add_f32_dpp v90, v35, v35 row_mirror row_mask:0xf bank_mask:0xf bound_ctrl:1
	ds_read_b128 v[64:67], v91 offset:15552
	v_pk_fma_f32 v[20:21], v[90:91], v[24:25], v[12:13] op_sel_hi:[0,1,1] neg_lo:[1,0,0] neg_hi:[1,0,0]
	v_pk_fma_f32 v[22:23], v[90:91], v[26:27], v[14:15] op_sel_hi:[0,1,1] neg_lo:[1,0,0] neg_hi:[1,0,0]
	ds_read_b128 v[12:15], v91 offset:16128
	ds_read_b128 v[24:27], v91 offset:16640
	s_waitcnt lgkmcnt(3)
	v_pk_mul_f32 v[94:95], v[20:21], v[94:95]
	v_pk_mul_f32 v[28:29], v[20:21], v[28:29]
	v_pk_fma_f32 v[94:95], v[22:23], v[96:97], v[94:95]
	v_pk_fma_f32 v[28:29], v[22:23], v[30:31], v[28:29]
	v_add_f32_e32 v96, v94, v95
	v_add_f32_e32 v242, v28, v29
	v_pk_fma_f32 v[40:41], v[20:21], v[40:41], v[20:21] neg_lo:[1,0,0] neg_hi:[1,0,0]
	v_add_f32_dpp v97, v96, v96 quad_perm:[1,0,3,2] row_mask:0xf bank_mask:0xf bound_ctrl:1
	v_pk_fma_f32 v[42:43], v[22:23], v[42:43], v[22:23] neg_lo:[1,0,0] neg_hi:[1,0,0]
	ds_read_b128 v[16:19], v91 offset:16384
	v_add_f32_dpp v96, v97, v97 quad_perm:[2,3,0,1] row_mask:0xf bank_mask:0xf bound_ctrl:1
	v_pk_fma_f32 v[40:41], v[38:39], v[44:45], v[40:41] op_sel_hi:[0,1,1]
	ds_read_b128 v[32:35], v91 offset:17152
	v_add_f32_dpp v97, v96, v96 row_half_mirror row_mask:0xf bank_mask:0xf bound_ctrl:1
	v_pk_fma_f32 v[42:43], v[38:39], v[46:47], v[42:43] op_sel_hi:[0,1,1]
	ds_read_b32 v36, v92 offset:17408
	v_add_f32_dpp v90, v97, v97 row_mirror row_mask:0xf bank_mask:0xf bound_ctrl:1
	ds_read_b128 v[28:31], v91 offset:16896
	v_pk_fma_f32 v[20:21], v[90:91], v[60:61], v[40:41] op_sel_hi:[0,1,1] neg_lo:[1,0,0] neg_hi:[1,0,0]
	v_pk_fma_f32 v[22:23], v[90:91], v[62:63], v[42:43] op_sel_hi:[0,1,1] neg_lo:[1,0,0] neg_hi:[1,0,0]
	ds_read_b128 v[40:43], v91 offset:17472
	ds_read_b128 v[60:63], v91 offset:17984
	s_waitcnt lgkmcnt(3)
; __device__ __forceinline__ void rwkv_scan_unit(const Params& p, int unit, char* smem) {
;     ...
;         const char* lb = smem + st + ks * 16;
;         const char* vb = smem + st + 1280 + rl * 4;
;         float* yl = (float*)(smem + YOFF + (ci & 1) * 1024) + rl;
;         f32x4 e4 = *(const f32x4*)(lb), kd4 = *(const f32x4*)(lb + 256), ka4 = *(const f32x4*)(lb + 512), r4 = *(const f32x4*)(lb + 768), kk4 = *(const f32x4*)(lb + 1024);
;         float vv = *(const float*)vb;
;         f32x2 sA = {s0, s1}, sB = {s2, s3};
;         float c;
;         { const f32x2 cv = sA * (f32x2){kk4[0], kk4[1]} + sB * (f32x2){kk4[2], kk4[3]}; c = red16(cv[0] + cv[1]); }
; #pragma unroll
;         for (int u = 0; u < SCH; ++u) {
;             f32x4 ne = e4, nkd = kd4, nka = ka4, nr = r4, nkk = kk4; float nv = vv;
;             if (u + 1 < SCH) { const char* q = lb + (u + 1) * STEPB;
;                 ne = *(const f32x4*)(q); nkd = *(const f32x4*)(q + 256); nka = *(const f32x4*)(q + 512); nr = *(const f32x4*)(q + 768); nkk = *(const f32x4*)(q + 1024);
;                 nv = *(const float*)(vb + (u + 1) * STEPB); }
;             const f32x2 v2 = {vv, vv}, c2 = {c, c};
;             const f32x2 tA = __builtin_elementwise_fma(v2, (f32x2){kd4[0], kd4[1]}, __builtin_elementwise_fma(-sA, (f32x2){e4[0], e4[1]}, sA));
;             const f32x2 tB = __builtin_elementwise_fma(v2, (f32x2){kd4[2], kd4[3]}, __builtin_elementwise_fma(-sB, (f32x2){e4[2], e4[3]}, sB));
;             sA = __builtin_elementwise_fma(-c2, (f32x2){ka4[0], ka4[1]}, tA);
;             sB = __builtin_elementwise_fma(-c2, (f32x2){ka4[2], ka4[3]}, tB);
;             const f32x2 yv = __builtin_elementwise_fma(sB, (f32x2){r4[2], r4[3]}, sA * (f32x2){r4[0], r4[1]});
;             float y = yv[0] + yv[1];
;             if (u + 1 < SCH) {
;                 const f32x2 cv = __builtin_elementwise_fma(sB, (f32x2){nkk[2], nkk[3]}, sA * (f32x2){nkk[0], nkk[1]});
;                 float cn = cv[0] + cv[1];
;                 cn = DPP_ADD(cn, 0xB1);  y = DPP_ADD(y, 0xB1);
;                 cn = DPP_ADD(cn, 0x4E);  y = DPP_ADD(y, 0x4E);
;                 cn = DPP_ADD(cn, 0x141); y = DPP_ADD(y, 0x141);
;                 cn = DPP_ADD(cn, 0x140); y = DPP_ADD(y, 0x140);
;                 c = cn;
;             } else y = red16(y);
;             if (ks == 0) yl[u * 16] = y;
	v_pk_mul_f32 v[32:33], v[20:21], v[32:33]
	v_pk_mul_f32 v[64:65], v[20:21], v[64:65]
	v_pk_fma_f32 v[32:33], v[22:23], v[34:35], v[32:33]
	v_pk_fma_f32 v[64:65], v[22:23], v[66:67], v[64:65]
	v_add_f32_e32 v34, v32, v33
	v_add_f32_e32 v243, v64, v65
	v_pk_fma_f32 v[12:13], v[20:21], v[12:13], v[20:21] neg_lo:[1,0,0] neg_hi:[1,0,0]
	v_add_f32_dpp v35, v34, v34 quad_perm:[1,0,3,2] row_mask:0xf bank_mask:0xf bound_ctrl:1
	v_pk_fma_f32 v[14:15], v[22:23], v[14:15], v[22:23] neg_lo:[1,0,0] neg_hi:[1,0,0]
	ds_read_b128 v[44:47], v91 offset:17728
	v_add_f32_dpp v34, v35, v35 quad_perm:[2,3,0,1] row_mask:0xf bank_mask:0xf bound_ctrl:1
	v_pk_fma_f32 v[12:13], v[36:37], v[16:17], v[12:13] op_sel_hi:[0,1,1]
	ds_read_b128 v[94:97], v91 offset:18496
	v_add_f32_dpp v35, v34, v34 row_half_mirror row_mask:0xf bank_mask:0xf bound_ctrl:1
	v_pk_fma_f32 v[14:15], v[36:37], v[18:19], v[14:15] op_sel_hi:[0,1,1]
	ds_read_b32 v38, v92 offset:18752
	v_add_f32_dpp v90, v35, v35 row_mirror row_mask:0xf bank_mask:0xf bound_ctrl:1
	ds_read_b128 v[64:67], v91 offset:18240
	v_pk_fma_f32 v[20:21], v[90:91], v[24:25], v[12:13] op_sel_hi:[0,1,1] neg_lo:[1,0,0] neg_hi:[1,0,0]
	v_pk_fma_f32 v[22:23], v[90:91], v[26:27], v[14:15] op_sel_hi:[0,1,1] neg_lo:[1,0,0] neg_hi:[1,0,0]
	ds_read_b128 v[12:15], v91 offset:18816
	ds_read_b128 v[24:27], v91 offset:19328
	s_waitcnt lgkmcnt(3)
	v_pk_mul_f32 v[94:95], v[20:21], v[94:95]
	v_pk_mul_f32 v[28:29], v[20:21], v[28:29]
	v_pk_fma_f32 v[94:95], v[22:23], v[96:97], v[94:95]
	v_pk_fma_f32 v[28:29], v[22:23], v[30:31], v[28:29]
	v_add_f32_e32 v96, v94, v95
	v_add_f32_e32 v244, v28, v29
	v_pk_fma_f32 v[40:41], v[20:21], v[40:41], v[20:21] neg_lo:[1,0,0] neg_hi:[1,0,0]
	v_add_f32_dpp v97, v96, v96 quad_perm:[1,0,3,2] row_mask:0xf bank_mask:0xf bound_ctrl:1
	v_pk_fma_f32 v[42:43], v[22:23], v[42:43], v[22:23] neg_lo:[1,0,0] neg_hi:[1,0,0]
	ds_read_b128 v[16:19], v91 offset:19072
	v_add_f32_dpp v96, v97, v97 quad_perm:[2,3,0,1] row_mask:0xf bank_mask:0xf bound_ctrl:1
	v_pk_fma_f32 v[40:41], v[38:39], v[44:45], v[40:41] op_sel_hi:[0,1,1]
	ds_read_b128 v[32:35], v91 offset:19840
	v_add_f32_dpp v97, v96, v96 row_half_mirror row_mask:0xf bank_mask:0xf bound_ctrl:1
	v_pk_fma_f32 v[42:43], v[38:39], v[46:47], v[42:43] op_sel_hi:[0,1,1]
	ds_read_b32 v36, v92 offset:20096
	v_add_f32_dpp v90, v97, v97 row_mirror row_mask:0xf bank_mask:0xf bound_ctrl:1
	ds_read_b128 v[28:31], v91 offset:19584
	v_pk_fma_f32 v[20:21], v[90:91], v[60:61], v[40:41] op_sel_hi:[0,1,1] neg_lo:[1,0,0] neg_hi:[1,0,0]
	v_pk_fma_f32 v[22:23], v[90:91], v[62:63], v[42:43] op_sel_hi:[0,1,1] neg_lo:[1,0,0] neg_hi:[1,0,0]
	ds_read_b128 v[40:43], v91 offset:20160
	ds_read_b128 v[60:63], v91 offset:20672
	s_waitcnt lgkmcnt(3)
	v_pk_mul_f32 v[32:33], v[20:21], v[32:33]
	v_pk_mul_f32 v[64:65], v[20:21], v[64:65]
	v_pk_fma_f32 v[32:33], v[22:23], v[34:35], v[32:33]
	v_pk_fma_f32 v[64:65], v[22:23], v[66:67], v[64:65]
	v_add_f32_e32 v34, v32, v33
	v_add_f32_e32 v245, v64, v65
	v_pk_fma_f32 v[12:13], v[20:21], v[12:13], v[20:21] neg_lo:[1,0,0] neg_hi:[1,0,0]
	v_add_f32_dpp v35, v34, v34 quad_perm:[1,0,3,2] row_mask:0xf bank_mask:0xf bound_ctrl:1
	v_pk_fma_f32 v[14:15], v[22:23], v[14:15], v[22:23] neg_lo:[1,0,0] neg_hi:[1,0,0]
	ds_read_b128 v[44:47], v91 offset:20416
	v_add_f32_dpp v34, v35, v35 quad_perm:[2,3,0,1] row_mask:0xf bank_mask:0xf bound_ctrl:1
	v_pk_fma_f32 v[12:13], v[36:37], v[16:17], v[12:13] op_sel_hi:[0,1,1]
	ds_read_b128 v[94:97], v91 offset:21184
	v_add_f32_dpp v35, v34, v34 row_half_mirror row_mask:0xf bank_mask:0xf bound_ctrl:1
	v_pk_fma_f32 v[14:15], v[36:37], v[18:19], v[14:15] op_sel_hi:[0,1,1]
	ds_read_b32 v38, v92 offset:21440
	v_add_f32_dpp v90, v35, v35 row_mirror row_mask:0xf bank_mask:0xf bound_ctrl:1
	ds_read_b128 v[64:67], v91 offset:20928
	v_pk_fma_f32 v[20:21], v[90:91], v[24:25], v[12:13] op_sel_hi:[0,1,1] neg_lo:[1,0,0] neg_hi:[1,0,0]
	v_pk_fma_f32 v[22:23], v[90:91], v[26:27], v[14:15] op_sel_hi:[0,1,1] neg_lo:[1,0,0] neg_hi:[1,0,0]
	s_waitcnt lgkmcnt(1)
	v_pk_mul_f32 v[94:95], v[20:21], v[94:95]
	v_pk_mul_f32 v[28:29], v[20:21], v[28:29]
	v_pk_fma_f32 v[94:95], v[22:23], v[96:97], v[94:95]
	v_pk_fma_f32 v[28:29], v[22:23], v[30:31], v[28:29]
	v_add_f32_e32 v96, v94, v95
	v_add_f32_e32 v246, v28, v29
	v_pk_fma_f32 v[40:41], v[20:21], v[40:41], v[20:21] neg_lo:[1,0,0] neg_hi:[1,0,0]
	v_add_f32_dpp v97, v96, v96 quad_perm:[1,0,3,2] row_mask:0xf bank_mask:0xf bound_ctrl:1
	v_pk_fma_f32 v[42:43], v[22:23], v[42:43], v[22:23] neg_lo:[1,0,0] neg_hi:[1,0,0]
	s_nop 0
	v_add_f32_dpp v96, v97, v97 quad_perm:[2,3,0,1] row_mask:0xf bank_mask:0xf bound_ctrl:1
	v_pk_fma_f32 v[40:41], v[38:39], v[44:45], v[40:41] op_sel_hi:[0,1,1]
	s_nop 0
	v_add_f32_dpp v97, v96, v96 row_half_mirror row_mask:0xf bank_mask:0xf bound_ctrl:1
	v_pk_fma_f32 v[42:43], v[38:39], v[46:47], v[42:43] op_sel_hi:[0,1,1]
	s_nop 0
	v_add_f32_dpp v90, v97, v97 row_mirror row_mask:0xf bank_mask:0xf bound_ctrl:1
	v_pk_fma_f32 v[20:21], v[90:91], v[60:61], v[40:41] op_sel_hi:[0,1,1] neg_lo:[1,0,0] neg_hi:[1,0,0]
	v_pk_fma_f32 v[22:23], v[90:91], v[62:63], v[42:43] op_sel_hi:[0,1,1] neg_lo:[1,0,0] neg_hi:[1,0,0]
	s_waitcnt lgkmcnt(0)
; #define DPP_ADD(v, ctrl) ((v) + __builtin_bit_cast(float, __builtin_amdgcn_update_dpp(0, __builtin_bit_cast(int, (v)), (ctrl), 0xf, 0xf, true)))
; #define SC_LSTORE(st_) { SC_S1(st_, 0, rg0) SC_S1(st_, 1, rg1) SC_S1(st_, 2, rg2) }
; __device__ __forceinline__ void rwkv_scan_unit(const Params& p, int unit, char* smem) {
;     ...
;         for (int u = 0; u < SCH; ++u) {
;             f32x4 ne = e4, nkd = kd4, nka = ka4, nr = r4, nkk = kk4; float nv = vv;
;             if (u + 1 < SCH) { const char* q = lb + (u + 1) * STEPB;
;                 ne = *(const f32x4*)(q); nkd = *(const f32x4*)(q + 256); nka = *(const f32x4*)(q + 512); nr = *(const f32x4*)(q + 768); nkk = *(const f32x4*)(q + 1024);
;                 nv = *(const float*)(vb + (u + 1) * STEPB); }
;             const f32x2 v2 = {vv, vv}, c2 = {c, c};
;             const f32x2 tA = __builtin_elementwise_fma(v2, (f32x2){kd4[0], kd4[1]}, __builtin_elementwise_fma(-sA, (f32x2){e4[0], e4[1]}, sA));
;             const f32x2 tB = __builtin_elementwise_fma(v2, (f32x2){kd4[2], kd4[3]}, __builtin_elementwise_fma(-sB, (f32x2){e4[2], e4[3]}, sB));
;             sA = __builtin_elementwise_fma(-c2, (f32x2){ka4[0], ka4[1]}, tA);
;             sB = __builtin_elementwise_fma(-c2, (f32x2){ka4[2], ka4[3]}, tB);
;             const f32x2 yv = __builtin_elementwise_fma(sB, (f32x2){r4[2], r4[3]}, sA * (f32x2){r4[0], r4[1]});
;             float y = yv[0] + yv[1];
;             if (u + 1 < SCH) {
;                 const f32x2 cv = __builtin_elementwise_fma(sB, (f32x2){nkk[2], nkk[3]}, sA * (f32x2){nkk[0], nkk[1]});
;                 float cn = cv[0] + cv[1];
;                 cn = DPP_ADD(cn, 0xB1);  y = DPP_ADD(y, 0xB1);
;                 cn = DPP_ADD(cn, 0x4E);  y = DPP_ADD(y, 0x4E);
;                 cn = DPP_ADD(cn, 0x141); y = DPP_ADD(y, 0x141);
;                 cn = DPP_ADD(cn, 0x140); y = DPP_ADD(y, 0x140);
;                 c = cn;
;             } else y = red16(y);
;             if (ks == 0) yl[u * 16] = y;
;             e4 = ne; kd4 = nkd; ka4 = nka; r4 = nr; kk4 = nkk; vv = nv;
;         }
;         s0 = sA[0]; s1 = sA[1]; s2 = sB[0]; s3 = sB[1];
;         __builtin_amdgcn_sched_barrier(0);
;         if (ci + 1 < NCH) { SC_LSTORE(((ci + 1) & 1) * STG) }
	v_pk_mul_f32 v[64:65], v[20:21], v[64:65]
	v_pk_fma_f32 v[64:65], v[22:23], v[66:67], v[64:65]
	s_nop 0
	v_add_f32_e32 v247, v64, v65
	s_mov_b32 s98, 0xaaaaaaaa
	s_mov_b32 s99, 0xaaaaaaaa
	s_mov_b32 s100, 0xcccccccc
	s_mov_b32 s101, 0xcccccccc
	v_add_f32_dpp v232, v232, v232 row_mirror row_mask:0xf bank_mask:0x3 bound_ctrl:1
	v_add_f32_dpp v233, v233, v233 row_mirror row_mask:0xf bank_mask:0x3 bound_ctrl:1
	v_add_f32_dpp v234, v234, v234 row_mirror row_mask:0xf bank_mask:0x3 bound_ctrl:1
	v_add_f32_dpp v235, v235, v235 row_mirror row_mask:0xf bank_mask:0x3 bound_ctrl:1
	v_add_f32_dpp v236, v236, v236 row_mirror row_mask:0xf bank_mask:0x3 bound_ctrl:1
	v_add_f32_dpp v237, v237, v237 row_mirror row_mask:0xf bank_mask:0x3 bound_ctrl:1
	v_add_f32_dpp v238, v238, v238 row_mirror row_mask:0xf bank_mask:0x3 bound_ctrl:1
	v_add_f32_dpp v239, v239, v239 row_mirror row_mask:0xf bank_mask:0x3 bound_ctrl:1
	v_add_f32_dpp v232, v240, v240 row_mirror row_mask:0xf bank_mask:0xc bound_ctrl:1
	v_add_f32_dpp v233, v241, v241 row_mirror row_mask:0xf bank_mask:0xc bound_ctrl:1
	v_add_f32_dpp v234, v242, v242 row_mirror row_mask:0xf bank_mask:0xc bound_ctrl:1
	v_add_f32_dpp v235, v243, v243 row_mirror row_mask:0xf bank_mask:0xc bound_ctrl:1
	v_add_f32_dpp v236, v244, v244 row_mirror row_mask:0xf bank_mask:0xc bound_ctrl:1
	v_add_f32_dpp v237, v245, v245 row_mirror row_mask:0xf bank_mask:0xc bound_ctrl:1
	v_add_f32_dpp v238, v246, v246 row_mirror row_mask:0xf bank_mask:0xc bound_ctrl:1
	v_add_f32_dpp v239, v247, v247 row_mirror row_mask:0xf bank_mask:0xc bound_ctrl:1
	v_add_f32_dpp v232, v232, v232 row_half_mirror row_mask:0xf bank_mask:0x5 bound_ctrl:1
	v_add_f32_dpp v233, v233, v233 row_half_mirror row_mask:0xf bank_mask:0x5 bound_ctrl:1
	v_add_f32_dpp v234, v234, v234 row_half_mirror row_mask:0xf bank_mask:0x5 bound_ctrl:1
	v_add_f32_dpp v235, v235, v235 row_half_mirror row_mask:0xf bank_mask:0x5 bound_ctrl:1
	v_add_f32_dpp v232, v236, v236 row_half_mirror row_mask:0xf bank_mask:0xa bound_ctrl:1
	v_add_f32_dpp v233, v237, v237 row_half_mirror row_mask:0xf bank_mask:0xa bound_ctrl:1
	v_add_f32_dpp v234, v238, v238 row_half_mirror row_mask:0xf bank_mask:0xa bound_ctrl:1
	v_add_f32_dpp v235, v239, v239 row_half_mirror row_mask:0xf bank_mask:0xa bound_ctrl:1
	v_cndmask_b32_e64 v240, v232, v234, s[100:101]
	v_cndmask_b32_e64 v241, v234, v232, s[100:101]
	v_cndmask_b32_e64 v242, v233, v235, s[100:101]
	v_cndmask_b32_e64 v243, v235, v233, s[100:101]
	s_nop 0
	v_add_f32_dpp v232, v241, v240 quad_perm:[2,3,0,1] row_mask:0xf bank_mask:0xf bound_ctrl:1
	v_add_f32_dpp v233, v243, v242 quad_perm:[2,3,0,1] row_mask:0xf bank_mask:0xf bound_ctrl:1
	s_nop 0
	v_cndmask_b32_e64 v240, v232, v233, s[98:99]
	v_cndmask_b32_e64 v241, v233, v232, s[98:99]
	v_add_u32_e32 v242, s52, v172
	s_nop 0
	v_add_f32_dpp v243, v241, v240 quad_perm:[1,0,3,2] row_mask:0xf bank_mask:0xf bound_ctrl:1
	ds_write_b32 v242, v243 offset:43008
	s_bitcmp1_b32 s64, 0
	s_cselect_b32 s0, 0x5400, 0
	s_waitcnt vmcnt(12)
	v_add3_u32 v16, s0, v74, v75
	v_cvt_f32_f16_sdwa v13, v0 dst_sel:DWORD dst_unused:UNUSED_PAD src0_sel:WORD_1
	v_cvt_f32_f16_e32 v12, v0
	v_cvt_f32_f16_sdwa v15, v1 dst_sel:DWORD dst_unused:UNUSED_PAD src0_sel:WORD_1
	v_cvt_f32_f16_e32 v14, v1
	ds_write_b128 v16, v[12:15]
	v_cvt_f32_f16_sdwa v13, v2 dst_sel:DWORD dst_unused:UNUSED_PAD src0_sel:WORD_1
	v_cvt_f32_f16_e32 v12, v2
	v_cvt_f32_f16_sdwa v15, v3 dst_sel:DWORD dst_unused:UNUSED_PAD src0_sel:WORD_1
	v_cvt_f32_f16_e32 v14, v3
	ds_write_b128 v16, v[12:15] offset:16
	v_add3_u32 v16, s0, v76, v77
	v_cvt_f32_f16_sdwa v13, v4 dst_sel:DWORD dst_unused:UNUSED_PAD src0_sel:WORD_1
	v_cvt_f32_f16_e32 v12, v4
	v_cvt_f32_f16_sdwa v15, v5 dst_sel:DWORD dst_unused:UNUSED_PAD src0_sel:WORD_1
	v_cvt_f32_f16_e32 v14, v5
	ds_write_b128 v16, v[12:15]
	v_cvt_f32_f16_sdwa v13, v6 dst_sel:DWORD dst_unused:UNUSED_PAD src0_sel:WORD_1
	v_cvt_f32_f16_e32 v12, v6
	v_cvt_f32_f16_sdwa v15, v7 dst_sel:DWORD dst_unused:UNUSED_PAD src0_sel:WORD_1
	v_cvt_f32_f16_e32 v14, v7
	ds_write_b128 v16, v[12:15] offset:16
	v_add3_u32 v16, s0, v78, v79
	v_cvt_f32_f16_sdwa v13, v8 dst_sel:DWORD dst_unused:UNUSED_PAD src0_sel:WORD_1
	v_cvt_f32_f16_e32 v12, v8
	v_cvt_f32_f16_sdwa v15, v9 dst_sel:DWORD dst_unused:UNUSED_PAD src0_sel:WORD_1
	v_cvt_f32_f16_e32 v14, v9
	ds_write_b128 v16, v[12:15]
	v_cvt_f32_f16_sdwa v13, v10 dst_sel:DWORD dst_unused:UNUSED_PAD src0_sel:WORD_1
	v_cvt_f32_f16_e32 v12, v10
	v_cvt_f32_f16_sdwa v15, v11 dst_sel:DWORD dst_unused:UNUSED_PAD src0_sel:WORD_1
	v_cvt_f32_f16_e32 v14, v11
	ds_write_b128 v16, v[12:15] offset:16

; __device__ __forceinline__ void rwkv_scan_unit(const Params& p, int unit, char* smem) {
;     ...
;         const char* lb = smem + st + ks * 16;
;         const char* vb = smem + st + 1280 + rl * 4;
;         float* yl = (float*)(smem + YOFF + (ci & 1) * 1024) + rl;
;         f32x4 e4 = *(const f32x4*)(lb), kd4 = *(const f32x4*)(lb + 256), ka4 = *(const f32x4*)(lb + 512), r4 = *(const f32x4*)(lb + 768), kk4 = *(const f32x4*)(lb + 1024);
;         float vv = *(const float*)vb;
;         f32x2 sA = {s0, s1}, sB = {s2, s3};
;         float c;
;         { const f32x2 cv = sA * (f32x2){kk4[0], kk4[1]} + sB * (f32x2){kk4[2], kk4[3]}; c = red16(cv[0] + cv[1]); }
; #pragma unroll
;         for (int u = 0; u < SCH; ++u) {
;             f32x4 ne = e4, nkd = kd4, nka = ka4, nr = r4, nkk = kk4; float nv = vv;
;             if (u + 1 < SCH) { const char* q = lb + (u + 1) * STEPB;
;                 ne = *(const f32x4*)(q); nkd = *(const f32x4*)(q + 256); nka = *(const f32x4*)(q + 512); nr = *(const f32x4*)(q + 768); nkk = *(const f32x4*)(q + 1024);
;                 nv = *(const float*)(vb + (u + 1) * STEPB); }
;             const f32x2 v2 = {vv, vv}, c2 = {c, c};
;             const f32x2 tA = __builtin_elementwise_fma(v2, (f32x2){kd4[0], kd4[1]}, __builtin_elementwise_fma(-sA, (f32x2){e4[0], e4[1]}, sA));
;             const f32x2 tB = __builtin_elementwise_fma(v2, (f32x2){kd4[2], kd4[3]}, __builtin_elementwise_fma(-sB, (f32x2){e4[2], e4[3]}, sB));
;             sA = __builtin_elementwise_fma(-c2, (f32x2){ka4[0], ka4[1]}, tA);
;             sB = __builtin_elementwise_fma(-c2, (f32x2){ka4[2], ka4[3]}, tB);
;             const f32x2 yv = __builtin_elementwise_fma(sB, (f32x2){r4[2], r4[3]}, sA * (f32x2){r4[0], r4[1]});
;             float y = yv[0] + yv[1];
;             if (u + 1 < SCH) {
;                 const f32x2 cv = __builtin_elementwise_fma(sB, (f32x2){nkk[2], nkk[3]}, sA * (f32x2){nkk[0], nkk[1]});
;                 float cn = cv[0] + cv[1];
;                 cn = DPP_ADD(cn, 0xB1);  y = DPP_ADD(y, 0xB1);
;                 cn = DPP_ADD(cn, 0x4E);  y = DPP_ADD(y, 0x4E);
;                 cn = DPP_ADD(cn, 0x141); y = DPP_ADD(y, 0x141);
;                 cn = DPP_ADD(cn, 0x140); y = DPP_ADD(y, 0x140);
;                 c = cn;
;             } else y = red16(y);
;             if (ks == 0) yl[u * 16] = y;
.Lsc_p1_body:
	s_add_i32 s30, s64, -1
	s_and_b32 s30, s30, 1
	s_mul_i32 s52, s30, 0x5400
	v_or_b32_e32 v91, s52, v80
	v_add_u32_e32 v92, s52, v81
	ds_read_b128 v[32:35], v91 offset:1024
	ds_read_b128 v[12:15], v91 offset:0
	ds_read_b128 v[16:19], v91 offset:256
	ds_read_b32 v36, v92 offset:1280
	ds_read_b128 v[24:27], v91 offset:512
	ds_read_b128 v[28:31], v91 offset:768
	ds_read_b128 v[40:43], v91 offset:1344
	ds_read_b128 v[60:63], v91 offset:1856
	ds_read_b128 v[44:47], v91 offset:1600
	ds_read_b128 v[94:97], v91 offset:2368
	ds_read_b32 v38, v92 offset:2624
	ds_read_b128 v[64:67], v91 offset:2112
	s_lshl_b32 s52, s30, 10
	s_waitcnt lgkmcnt(11)
	v_pk_mul_f32 v[32:33], v[20:21], v[32:33]
	s_waitcnt lgkmcnt(10)
	v_pk_fma_f32 v[12:13], v[20:21], v[12:13], v[20:21] neg_lo:[1,0,0] neg_hi:[1,0,0]
	v_pk_fma_f32 v[32:33], v[22:23], v[34:35], v[32:33]
	v_pk_fma_f32 v[14:15], v[22:23], v[14:15], v[22:23] neg_lo:[1,0,0] neg_hi:[1,0,0]
	v_add_f32_e32 v34, v32, v33
	s_waitcnt lgkmcnt(8)
	v_pk_fma_f32 v[12:13], v[36:37], v[16:17], v[12:13] op_sel_hi:[0,1,1]
	v_pk_fma_f32 v[14:15], v[36:37], v[18:19], v[14:15] op_sel_hi:[0,1,1]
	v_add_f32_dpp v35, v34, v34 quad_perm:[1,0,3,2] row_mask:0xf bank_mask:0xf bound_ctrl:1
	s_nop 1
	v_add_f32_dpp v34, v35, v35 quad_perm:[2,3,0,1] row_mask:0xf bank_mask:0xf bound_ctrl:1
	s_nop 1
	v_add_f32_dpp v35, v34, v34 row_half_mirror row_mask:0xf bank_mask:0xf bound_ctrl:1
	s_nop 1
	v_add_f32_dpp v90, v35, v35 row_mirror row_mask:0xf bank_mask:0xf bound_ctrl:1
	ds_read_b128 v[16:19], v91 offset:2944
	ds_read_b128 v[32:35], v91 offset:3712
	ds_read_b32 v36, v92 offset:3968
	s_waitcnt lgkmcnt(10)
	v_pk_fma_f32 v[20:21], v[90:91], v[24:25], v[12:13] op_sel_hi:[0,1,1] neg_lo:[1,0,0] neg_hi:[1,0,0]
	v_pk_fma_f32 v[22:23], v[90:91], v[26:27], v[14:15] op_sel_hi:[0,1,1] neg_lo:[1,0,0] neg_hi:[1,0,0]
	ds_read_b128 v[12:15], v91 offset:2688
	ds_read_b128 v[24:27], v91 offset:3200
	s_waitcnt lgkmcnt(7)
	v_pk_mul_f32 v[94:95], v[20:21], v[94:95]
	v_pk_mul_f32 v[28:29], v[20:21], v[28:29]
	v_pk_fma_f32 v[94:95], v[22:23], v[96:97], v[94:95]
	v_pk_fma_f32 v[28:29], v[22:23], v[30:31], v[28:29]
	v_add_f32_e32 v96, v94, v95
	v_add_f32_e32 v232, v28, v29
	v_pk_fma_f32 v[40:41], v[20:21], v[40:41], v[20:21] neg_lo:[1,0,0] neg_hi:[1,0,0]
	v_add_f32_dpp v97, v96, v96 quad_perm:[1,0,3,2] row_mask:0xf bank_mask:0xf bound_ctrl:1
	v_pk_fma_f32 v[42:43], v[22:23], v[42:43], v[22:23] neg_lo:[1,0,0] neg_hi:[1,0,0]
	s_nop 0
	v_add_f32_dpp v96, v97, v97 quad_perm:[2,3,0,1] row_mask:0xf bank_mask:0xf bound_ctrl:1
	s_waitcnt lgkmcnt(6)
	v_pk_fma_f32 v[40:41], v[38:39], v[44:45], v[40:41] op_sel_hi:[0,1,1]
	s_nop 0
	v_add_f32_dpp v97, v96, v96 row_half_mirror row_mask:0xf bank_mask:0xf bound_ctrl:1
	v_pk_fma_f32 v[42:43], v[38:39], v[46:47], v[42:43] op_sel_hi:[0,1,1]
	s_nop 0
	v_add_f32_dpp v90, v97, v97 row_mirror row_mask:0xf bank_mask:0xf bound_ctrl:1
	ds_read_b128 v[28:31], v91 offset:3456
	v_pk_fma_f32 v[20:21], v[90:91], v[60:61], v[40:41] op_sel_hi:[0,1,1] neg_lo:[1,0,0] neg_hi:[1,0,0]
	v_pk_fma_f32 v[22:23], v[90:91], v[62:63], v[42:43] op_sel_hi:[0,1,1] neg_lo:[1,0,0] neg_hi:[1,0,0]
	ds_read_b128 v[40:43], v91 offset:4032
	ds_read_b128 v[60:63], v91 offset:4544
	s_waitcnt lgkmcnt(4)
	v_pk_mul_f32 v[32:33], v[20:21], v[32:33]
	v_pk_mul_f32 v[64:65], v[20:21], v[64:65]
	v_pk_fma_f32 v[32:33], v[22:23], v[34:35], v[32:33]
	v_pk_fma_f32 v[64:65], v[22:23], v[66:67], v[64:65]
	v_add_f32_e32 v34, v32, v33
	v_add_f32_e32 v233, v64, v65
	v_pk_fma_f32 v[12:13], v[20:21], v[12:13], v[20:21] neg_lo:[1,0,0] neg_hi:[1,0,0]
	v_add_f32_dpp v35, v34, v34 quad_perm:[1,0,3,2] row_mask:0xf bank_mask:0xf bound_ctrl:1
	v_pk_fma_f32 v[14:15], v[22:23], v[14:15], v[22:23] neg_lo:[1,0,0] neg_hi:[1,0,0]
	ds_read_b128 v[44:47], v91 offset:4288
	v_add_f32_dpp v34, v35, v35 quad_perm:[2,3,0,1] row_mask:0xf bank_mask:0xf bound_ctrl:1
	v_pk_fma_f32 v[12:13], v[36:37], v[16:17], v[12:13] op_sel_hi:[0,1,1]
	ds_read_b128 v[94:97], v91 offset:5056
	v_add_f32_dpp v35, v34, v34 row_half_mirror row_mask:0xf bank_mask:0xf bound_ctrl:1
	v_pk_fma_f32 v[14:15], v[36:37], v[18:19], v[14:15] op_sel_hi:[0,1,1]
	ds_read_b32 v38, v92 offset:5312
	v_add_f32_dpp v90, v35, v35 row_mirror row_mask:0xf bank_mask:0xf bound_ctrl:1
	ds_read_b128 v[64:67], v91 offset:4800
	s_waitcnt lgkmcnt(7)
	v_pk_fma_f32 v[20:21], v[90:91], v[24:25], v[12:13] op_sel_hi:[0,1,1] neg_lo:[1,0,0] neg_hi:[1,0,0]
	v_pk_fma_f32 v[22:23], v[90:91], v[26:27], v[14:15] op_sel_hi:[0,1,1] neg_lo:[1,0,0] neg_hi:[1,0,0]
	ds_read_b128 v[12:15], v91 offset:5376
	ds_read_b128 v[24:27], v91 offset:5888
	s_waitcnt lgkmcnt(3)
	v_pk_mul_f32 v[94:95], v[20:21], v[94:95]
	v_pk_mul_f32 v[28:29], v[20:21], v[28:29]
	v_pk_fma_f32 v[94:95], v[22:23], v[96:97], v[94:95]
	v_pk_fma_f32 v[28:29], v[22:23], v[30:31], v[28:29]
	v_add_f32_e32 v96, v94, v95
	v_add_f32_e32 v234, v28, v29
	v_pk_fma_f32 v[40:41], v[20:21], v[40:41], v[20:21] neg_lo:[1,0,0] neg_hi:[1,0,0]
	v_add_f32_dpp v97, v96, v96 quad_perm:[1,0,3,2] row_mask:0xf bank_mask:0xf bound_ctrl:1
	v_pk_fma_f32 v[42:43], v[22:23], v[42:43], v[22:23] neg_lo:[1,0,0] neg_hi:[1,0,0]
	ds_read_b128 v[16:19], v91 offset:5632
	v_add_f32_dpp v96, v97, v97 quad_perm:[2,3,0,1] row_mask:0xf bank_mask:0xf bound_ctrl:1
	v_pk_fma_f32 v[40:41], v[38:39], v[44:45], v[40:41] op_sel_hi:[0,1,1]
	ds_read_b128 v[32:35], v91 offset:6400
	v_add_f32_dpp v97, v96, v96 row_half_mirror row_mask:0xf bank_mask:0xf bound_ctrl:1
	v_pk_fma_f32 v[42:43], v[38:39], v[46:47], v[42:43] op_sel_hi:[0,1,1]
	ds_read_b32 v36, v92 offset:6656
	v_add_f32_dpp v90, v97, v97 row_mirror row_mask:0xf bank_mask:0xf bound_ctrl:1
	ds_read_b128 v[28:31], v91 offset:6144
	v_pk_fma_f32 v[20:21], v[90:91], v[60:61], v[40:41] op_sel_hi:[0,1,1] neg_lo:[1,0,0] neg_hi:[1,0,0]
	v_pk_fma_f32 v[22:23], v[90:91], v[62:63], v[42:43] op_sel_hi:[0,1,1] neg_lo:[1,0,0] neg_hi:[1,0,0]
	ds_read_b128 v[40:43], v91 offset:6720
	ds_read_b128 v[60:63], v91 offset:7232
	s_waitcnt lgkmcnt(3)
; __device__ __forceinline__ void rwkv_scan_unit(const Params& p, int unit, char* smem) {
;     ...
;         const char* lb = smem + st + ks * 16;
;         const char* vb = smem + st + 1280 + rl * 4;
;         float* yl = (float*)(smem + YOFF + (ci & 1) * 1024) + rl;
;         f32x4 e4 = *(const f32x4*)(lb), kd4 = *(const f32x4*)(lb + 256), ka4 = *(const f32x4*)(lb + 512), r4 = *(const f32x4*)(lb + 768), kk4 = *(const f32x4*)(lb + 1024);
;         float vv = *(const float*)vb;
;         f32x2 sA = {s0, s1}, sB = {s2, s3};
;         float c;
;         { const f32x2 cv = sA * (f32x2){kk4[0], kk4[1]} + sB * (f32x2){kk4[2], kk4[3]}; c = red16(cv[0] + cv[1]); }
; #pragma unroll
;         for (int u = 0; u < SCH; ++u) {
;             f32x4 ne = e4, nkd = kd4, nka = ka4, nr = r4, nkk = kk4; float nv = vv;
;             if (u + 1 < SCH) { const char* q = lb + (u + 1) * STEPB;
;                 ne = *(const f32x4*)(q); nkd = *(const f32x4*)(q + 256); nka = *(const f32x4*)(q + 512); nr = *(const f32x4*)(q + 768); nkk = *(const f32x4*)(q + 1024);
;                 nv = *(const float*)(vb + (u + 1) * STEPB); }
;             const f32x2 v2 = {vv, vv}, c2 = {c, c};
;             const f32x2 tA = __builtin_elementwise_fma(v2, (f32x2){kd4[0], kd4[1]}, __builtin_elementwise_fma(-sA, (f32x2){e4[0], e4[1]}, sA));
;             const f32x2 tB = __builtin_elementwise_fma(v2, (f32x2){kd4[2], kd4[3]}, __builtin_elementwise_fma(-sB, (f32x2){e4[2], e4[3]}, sB));
;             sA = __builtin_elementwise_fma(-c2, (f32x2){ka4[0], ka4[1]}, tA);
;             sB = __builtin_elementwise_fma(-c2, (f32x2){ka4[2], ka4[3]}, tB);
;             const f32x2 yv = __builtin_elementwise_fma(sB, (f32x2){r4[2], r4[3]}, sA * (f32x2){r4[0], r4[1]});
;             float y = yv[0] + yv[1];
;             if (u + 1 < SCH) {
;                 const f32x2 cv = __builtin_elementwise_fma(sB, (f32x2){nkk[2], nkk[3]}, sA * (f32x2){nkk[0], nkk[1]});
;                 float cn = cv[0] + cv[1];
;                 cn = DPP_ADD(cn, 0xB1);  y = DPP_ADD(y, 0xB1);
;                 cn = DPP_ADD(cn, 0x4E);  y = DPP_ADD(y, 0x4E);
;                 cn = DPP_ADD(cn, 0x141); y = DPP_ADD(y, 0x141);
;                 cn = DPP_ADD(cn, 0x140); y = DPP_ADD(y, 0x140);
;                 c = cn;
;             } else y = red16(y);
;             if (ks == 0) yl[u * 16] = y;
	v_pk_mul_f32 v[32:33], v[20:21], v[32:33]
	v_pk_mul_f32 v[64:65], v[20:21], v[64:65]
	v_pk_fma_f32 v[32:33], v[22:23], v[34:35], v[32:33]
	v_pk_fma_f32 v[64:65], v[22:23], v[66:67], v[64:65]
	v_add_f32_e32 v34, v32, v33
	v_add_f32_e32 v235, v64, v65
	v_pk_fma_f32 v[12:13], v[20:21], v[12:13], v[20:21] neg_lo:[1,0,0] neg_hi:[1,0,0]
	v_add_f32_dpp v35, v34, v34 quad_perm:[1,0,3,2] row_mask:0xf bank_mask:0xf bound_ctrl:1
	v_pk_fma_f32 v[14:15], v[22:23], v[14:15], v[22:23] neg_lo:[1,0,0] neg_hi:[1,0,0]
	ds_read_b128 v[44:47], v91 offset:6976
	v_add_f32_dpp v34, v35, v35 quad_perm:[2,3,0,1] row_mask:0xf bank_mask:0xf bound_ctrl:1
	v_pk_fma_f32 v[12:13], v[36:37], v[16:17], v[12:13] op_sel_hi:[0,1,1]
	ds_read_b128 v[94:97], v91 offset:7744
	v_add_f32_dpp v35, v34, v34 row_half_mirror row_mask:0xf bank_mask:0xf bound_ctrl:1
	v_pk_fma_f32 v[14:15], v[36:37], v[18:19], v[14:15] op_sel_hi:[0,1,1]
	ds_read_b32 v38, v92 offset:8000
	v_add_f32_dpp v90, v35, v35 row_mirror row_mask:0xf bank_mask:0xf bound_ctrl:1
	ds_read_b128 v[64:67], v91 offset:7488
	v_pk_fma_f32 v[20:21], v[90:91], v[24:25], v[12:13] op_sel_hi:[0,1,1] neg_lo:[1,0,0] neg_hi:[1,0,0]
	v_pk_fma_f32 v[22:23], v[90:91], v[26:27], v[14:15] op_sel_hi:[0,1,1] neg_lo:[1,0,0] neg_hi:[1,0,0]
	ds_read_b128 v[12:15], v91 offset:8064
	ds_read_b128 v[24:27], v91 offset:8576
	s_waitcnt lgkmcnt(3)
	v_pk_mul_f32 v[94:95], v[20:21], v[94:95]
	v_pk_mul_f32 v[28:29], v[20:21], v[28:29]
	v_pk_fma_f32 v[94:95], v[22:23], v[96:97], v[94:95]
	v_pk_fma_f32 v[28:29], v[22:23], v[30:31], v[28:29]
	v_add_f32_e32 v96, v94, v95
	v_add_f32_e32 v236, v28, v29
	v_pk_fma_f32 v[40:41], v[20:21], v[40:41], v[20:21] neg_lo:[1,0,0] neg_hi:[1,0,0]
	v_add_f32_dpp v97, v96, v96 quad_perm:[1,0,3,2] row_mask:0xf bank_mask:0xf bound_ctrl:1
	v_pk_fma_f32 v[42:43], v[22:23], v[42:43], v[22:23] neg_lo:[1,0,0] neg_hi:[1,0,0]
	ds_read_b128 v[16:19], v91 offset:8320
	v_add_f32_dpp v96, v97, v97 quad_perm:[2,3,0,1] row_mask:0xf bank_mask:0xf bound_ctrl:1
	v_pk_fma_f32 v[40:41], v[38:39], v[44:45], v[40:41] op_sel_hi:[0,1,1]
	ds_read_b128 v[32:35], v91 offset:9088
	v_add_f32_dpp v97, v96, v96 row_half_mirror row_mask:0xf bank_mask:0xf bound_ctrl:1
	v_pk_fma_f32 v[42:43], v[38:39], v[46:47], v[42:43] op_sel_hi:[0,1,1]
	ds_read_b32 v36, v92 offset:9344
	v_add_f32_dpp v90, v97, v97 row_mirror row_mask:0xf bank_mask:0xf bound_ctrl:1
	ds_read_b128 v[28:31], v91 offset:8832
	v_pk_fma_f32 v[20:21], v[90:91], v[60:61], v[40:41] op_sel_hi:[0,1,1] neg_lo:[1,0,0] neg_hi:[1,0,0]
	v_pk_fma_f32 v[22:23], v[90:91], v[62:63], v[42:43] op_sel_hi:[0,1,1] neg_lo:[1,0,0] neg_hi:[1,0,0]
	ds_read_b128 v[40:43], v91 offset:9408
	ds_read_b128 v[60:63], v91 offset:9920
	s_waitcnt lgkmcnt(3)
	v_pk_mul_f32 v[32:33], v[20:21], v[32:33]
	v_pk_mul_f32 v[64:65], v[20:21], v[64:65]
	v_pk_fma_f32 v[32:33], v[22:23], v[34:35], v[32:33]
	v_pk_fma_f32 v[64:65], v[22:23], v[66:67], v[64:65]
	v_add_f32_e32 v34, v32, v33
	v_add_f32_e32 v237, v64, v65
	v_pk_fma_f32 v[12:13], v[20:21], v[12:13], v[20:21] neg_lo:[1,0,0] neg_hi:[1,0,0]
	v_add_f32_dpp v35, v34, v34 quad_perm:[1,0,3,2] row_mask:0xf bank_mask:0xf bound_ctrl:1
	v_pk_fma_f32 v[14:15], v[22:23], v[14:15], v[22:23] neg_lo:[1,0,0] neg_hi:[1,0,0]
	ds_read_b128 v[44:47], v91 offset:9664
	v_add_f32_dpp v34, v35, v35 quad_perm:[2,3,0,1] row_mask:0xf bank_mask:0xf bound_ctrl:1
	v_pk_fma_f32 v[12:13], v[36:37], v[16:17], v[12:13] op_sel_hi:[0,1,1]
	ds_read_b128 v[94:97], v91 offset:10432
	v_add_f32_dpp v35, v34, v34 row_half_mirror row_mask:0xf bank_mask:0xf bound_ctrl:1
	v_pk_fma_f32 v[14:15], v[36:37], v[18:19], v[14:15] op_sel_hi:[0,1,1]
	ds_read_b32 v38, v92 offset:10688
	v_add_f32_dpp v90, v35, v35 row_mirror row_mask:0xf bank_mask:0xf bound_ctrl:1
	ds_read_b128 v[64:67], v91 offset:10176
	v_pk_fma_f32 v[20:21], v[90:91], v[24:25], v[12:13] op_sel_hi:[0,1,1] neg_lo:[1,0,0] neg_hi:[1,0,0]
	v_pk_fma_f32 v[22:23], v[90:91], v[26:27], v[14:15] op_sel_hi:[0,1,1] neg_lo:[1,0,0] neg_hi:[1,0,0]
	ds_read_b128 v[12:15], v91 offset:10752
	ds_read_b128 v[24:27], v91 offset:11264
	s_waitcnt lgkmcnt(3)
	v_pk_mul_f32 v[94:95], v[20:21], v[94:95]
	v_pk_mul_f32 v[28:29], v[20:21], v[28:29]
	v_pk_fma_f32 v[94:95], v[22:23], v[96:97], v[94:95]
	v_pk_fma_f32 v[28:29], v[22:23], v[30:31], v[28:29]
	v_add_f32_e32 v96, v94, v95
	v_add_f32_e32 v238, v28, v29
	v_pk_fma_f32 v[40:41], v[20:21], v[40:41], v[20:21] neg_lo:[1,0,0] neg_hi:[1,0,0]
	v_add_f32_dpp v97, v96, v96 quad_perm:[1,0,3,2] row_mask:0xf bank_mask:0xf bound_ctrl:1
	v_pk_fma_f32 v[42:43], v[22:23], v[42:43], v[22:23] neg_lo:[1,0,0] neg_hi:[1,0,0]
	ds_read_b128 v[16:19], v91 offset:11008
	v_add_f32_dpp v96, v97, v97 quad_perm:[2,3,0,1] row_mask:0xf bank_mask:0xf bound_ctrl:1
	v_pk_fma_f32 v[40:41], v[38:39], v[44:45], v[40:41] op_sel_hi:[0,1,1]
	ds_read_b128 v[32:35], v91 offset:11776
	v_add_f32_dpp v97, v96, v96 row_half_mirror row_mask:0xf bank_mask:0xf bound_ctrl:1
	v_pk_fma_f32 v[42:43], v[38:39], v[46:47], v[42:43] op_sel_hi:[0,1,1]
	ds_read_b32 v36, v92 offset:12032
	v_add_f32_dpp v90, v97, v97 row_mirror row_mask:0xf bank_mask:0xf bound_ctrl:1
	ds_read_b128 v[28:31], v91 offset:11520
	v_pk_fma_f32 v[20:21], v[90:91], v[60:61], v[40:41] op_sel_hi:[0,1,1] neg_lo:[1,0,0] neg_hi:[1,0,0]
	v_pk_fma_f32 v[22:23], v[90:91], v[62:63], v[42:43] op_sel_hi:[0,1,1] neg_lo:[1,0,0] neg_hi:[1,0,0]
	ds_read_b128 v[40:43], v91 offset:12096
	ds_read_b128 v[60:63], v91 offset:12608
	s_waitcnt lgkmcnt(3)
; __device__ __forceinline__ void rwkv_scan_unit(const Params& p, int unit, char* smem) {
;     ...
;         const char* lb = smem + st + ks * 16;
;         const char* vb = smem + st + 1280 + rl * 4;
;         float* yl = (float*)(smem + YOFF + (ci & 1) * 1024) + rl;
;         f32x4 e4 = *(const f32x4*)(lb), kd4 = *(const f32x4*)(lb + 256), ka4 = *(const f32x4*)(lb + 512), r4 = *(const f32x4*)(lb + 768), kk4 = *(const f32x4*)(lb + 1024);
;         float vv = *(const float*)vb;
;         f32x2 sA = {s0, s1}, sB = {s2, s3};
;         float c;
;         { const f32x2 cv = sA * (f32x2){kk4[0], kk4[1]} + sB * (f32x2){kk4[2], kk4[3]}; c = red16(cv[0] + cv[1]); }
; #pragma unroll
;         for (int u = 0; u < SCH; ++u) {
;             f32x4 ne = e4, nkd = kd4, nka = ka4, nr = r4, nkk = kk4; float nv = vv;
;             if (u + 1 < SCH) { const char* q = lb + (u + 1) * STEPB;
;                 ne = *(const f32x4*)(q); nkd = *(const f32x4*)(q + 256); nka = *(const f32x4*)(q + 512); nr = *(const f32x4*)(q + 768); nkk = *(const f32x4*)(q + 1024);
;                 nv = *(const float*)(vb + (u + 1) * STEPB); }
;             const f32x2 v2 = {vv, vv}, c2 = {c, c};
;             const f32x2 tA = __builtin_elementwise_fma(v2, (f32x2){kd4[0], kd4[1]}, __builtin_elementwise_fma(-sA, (f32x2){e4[0], e4[1]}, sA));
;             const f32x2 tB = __builtin_elementwise_fma(v2, (f32x2){kd4[2], kd4[3]}, __builtin_elementwise_fma(-sB, (f32x2){e4[2], e4[3]}, sB));
;             sA = __builtin_elementwise_fma(-c2, (f32x2){ka4[0], ka4[1]}, tA);
;             sB = __builtin_elementwise_fma(-c2, (f32x2){ka4[2], ka4[3]}, tB);
;             const f32x2 yv = __builtin_elementwise_fma(sB, (f32x2){r4[2], r4[3]}, sA * (f32x2){r4[0], r4[1]});
;             float y = yv[0] + yv[1];
;             if (u + 1 < SCH) {
;                 const f32x2 cv = __builtin_elementwise_fma(sB, (f32x2){nkk[2], nkk[3]}, sA * (f32x2){nkk[0], nkk[1]});
;                 float cn = cv[0] + cv[1];
;                 cn = DPP_ADD(cn, 0xB1);  y = DPP_ADD(y, 0xB1);
;                 cn = DPP_ADD(cn, 0x4E);  y = DPP_ADD(y, 0x4E);
;                 cn = DPP_ADD(cn, 0x141); y = DPP_ADD(y, 0x141);
;                 cn = DPP_ADD(cn, 0x140); y = DPP_ADD(y, 0x140);
;                 c = cn;
;             } else y = red16(y);
;             if (ks == 0) yl[u * 16] = y;
	v_pk_mul_f32 v[32:33], v[20:21], v[32:33]
	v_pk_mul_f32 v[64:65], v[20:21], v[64:65]
	v_pk_fma_f32 v[32:33], v[22:23], v[34:35], v[32:33]
	v_pk_fma_f32 v[64:65], v[22:23], v[66:67], v[64:65]
	v_add_f32_e32 v34, v32, v33
	v_add_f32_e32 v239, v64, v65
	v_pk_fma_f32 v[12:13], v[20:21], v[12:13], v[20:21] neg_lo:[1,0,0] neg_hi:[1,0,0]
	v_add_f32_dpp v35, v34, v34 quad_perm:[1,0,3,2] row_mask:0xf bank_mask:0xf bound_ctrl:1
	v_pk_fma_f32 v[14:15], v[22:23], v[14:15], v[22:23] neg_lo:[1,0,0] neg_hi:[1,0,0]
	ds_read_b128 v[44:47], v91 offset:12352
	v_add_f32_dpp v34, v35, v35 quad_perm:[2,3,0,1] row_mask:0xf bank_mask:0xf bound_ctrl:1
	v_pk_fma_f32 v[12:13], v[36:37], v[16:17], v[12:13] op_sel_hi:[0,1,1]
	ds_read_b128 v[94:97], v91 offset:13120
	v_add_f32_dpp v35, v34, v34 row_half_mirror row_mask:0xf bank_mask:0xf bound_ctrl:1
	v_pk_fma_f32 v[14:15], v[36:37], v[18:19], v[14:15] op_sel_hi:[0,1,1]
	ds_read_b32 v38, v92 offset:13376
	v_add_f32_dpp v90, v35, v35 row_mirror row_mask:0xf bank_mask:0xf bound_ctrl:1
	ds_read_b128 v[64:67], v91 offset:12864
	v_pk_fma_f32 v[20:21], v[90:91], v[24:25], v[12:13] op_sel_hi:[0,1,1] neg_lo:[1,0,0] neg_hi:[1,0,0]
	v_pk_fma_f32 v[22:23], v[90:91], v[26:27], v[14:15] op_sel_hi:[0,1,1] neg_lo:[1,0,0] neg_hi:[1,0,0]
	ds_read_b128 v[12:15], v91 offset:13440
	ds_read_b128 v[24:27], v91 offset:13952
	s_waitcnt lgkmcnt(3)
	v_pk_mul_f32 v[94:95], v[20:21], v[94:95]
	v_pk_mul_f32 v[28:29], v[20:21], v[28:29]
	v_pk_fma_f32 v[94:95], v[22:23], v[96:97], v[94:95]
	v_pk_fma_f32 v[28:29], v[22:23], v[30:31], v[28:29]
	v_add_f32_e32 v96, v94, v95
	v_add_f32_e32 v240, v28, v29
	v_pk_fma_f32 v[40:41], v[20:21], v[40:41], v[20:21] neg_lo:[1,0,0] neg_hi:[1,0,0]
	v_add_f32_dpp v97, v96, v96 quad_perm:[1,0,3,2] row_mask:0xf bank_mask:0xf bound_ctrl:1
	v_pk_fma_f32 v[42:43], v[22:23], v[42:43], v[22:23] neg_lo:[1,0,0] neg_hi:[1,0,0]
	ds_read_b128 v[16:19], v91 offset:13696
	v_add_f32_dpp v96, v97, v97 quad_perm:[2,3,0,1] row_mask:0xf bank_mask:0xf bound_ctrl:1
	v_pk_fma_f32 v[40:41], v[38:39], v[44:45], v[40:41] op_sel_hi:[0,1,1]
	ds_read_b128 v[32:35], v91 offset:14464
	v_add_f32_dpp v97, v96, v96 row_half_mirror row_mask:0xf bank_mask:0xf bound_ctrl:1
	v_pk_fma_f32 v[42:43], v[38:39], v[46:47], v[42:43] op_sel_hi:[0,1,1]
	ds_read_b32 v36, v92 offset:14720
	v_add_f32_dpp v90, v97, v97 row_mirror row_mask:0xf bank_mask:0xf bound_ctrl:1
	ds_read_b128 v[28:31], v91 offset:14208
	v_pk_fma_f32 v[20:21], v[90:91], v[60:61], v[40:41] op_sel_hi:[0,1,1] neg_lo:[1,0,0] neg_hi:[1,0,0]
	v_pk_fma_f32 v[22:23], v[90:91], v[62:63], v[42:43] op_sel_hi:[0,1,1] neg_lo:[1,0,0] neg_hi:[1,0,0]
	ds_read_b128 v[40:43], v91 offset:14784
	ds_read_b128 v[60:63], v91 offset:15296
	s_waitcnt lgkmcnt(3)
	v_pk_mul_f32 v[32:33], v[20:21], v[32:33]
	v_pk_mul_f32 v[64:65], v[20:21], v[64:65]
	v_pk_fma_f32 v[32:33], v[22:23], v[34:35], v[32:33]
	v_pk_fma_f32 v[64:65], v[22:23], v[66:67], v[64:65]
	v_add_f32_e32 v34, v32, v33
	v_add_f32_e32 v241, v64, v65
	v_pk_fma_f32 v[12:13], v[20:21], v[12:13], v[20:21] neg_lo:[1,0,0] neg_hi:[1,0,0]
	v_add_f32_dpp v35, v34, v34 quad_perm:[1,0,3,2] row_mask:0xf bank_mask:0xf bound_ctrl:1
	v_pk_fma_f32 v[14:15], v[22:23], v[14:15], v[22:23] neg_lo:[1,0,0] neg_hi:[1,0,0]
	ds_read_b128 v[44:47], v91 offset:15040
	v_add_f32_dpp v34, v35, v35 quad_perm:[2,3,0,1] row_mask:0xf bank_mask:0xf bound_ctrl:1
	v_pk_fma_f32 v[12:13], v[36:37], v[16:17], v[12:13] op_sel_hi:[0,1,1]
	ds_read_b128 v[94:97], v91 offset:15808
	v_add_f32_dpp v35, v34, v34 row_half_mirror row_mask:0xf bank_mask:0xf bound_ctrl:1
	v_pk_fma_f32 v[14:15], v[36:37], v[18:19], v[14:15] op_sel_hi:[0,1,1]
	ds_read_b32 v38, v92 offset:16064
	v_add_f32_dpp v90, v35, v35 row_mirror row_mask:0xf bank_mask:0xf bound_ctrl:1
	ds_read_b128 v[64:67], v91 offset:15552
	v_pk_fma_f32 v[20:21], v[90:91], v[24:25], v[12:13] op_sel_hi:[0,1,1] neg_lo:[1,0,0] neg_hi:[1,0,0]
	v_pk_fma_f32 v[22:23], v[90:91], v[26:27], v[14:15] op_sel_hi:[0,1,1] neg_lo:[1,0,0] neg_hi:[1,0,0]
	ds_read_b128 v[12:15], v91 offset:16128
	ds_read_b128 v[24:27], v91 offset:16640
	s_waitcnt lgkmcnt(3)
	v_pk_mul_f32 v[94:95], v[20:21], v[94:95]
	v_pk_mul_f32 v[28:29], v[20:21], v[28:29]
	v_pk_fma_f32 v[94:95], v[22:23], v[96:97], v[94:95]
	v_pk_fma_f32 v[28:29], v[22:23], v[30:31], v[28:29]
	v_add_f32_e32 v96, v94, v95
	v_add_f32_e32 v242, v28, v29
	v_pk_fma_f32 v[40:41], v[20:21], v[40:41], v[20:21] neg_lo:[1,0,0] neg_hi:[1,0,0]
	v_add_f32_dpp v97, v96, v96 quad_perm:[1,0,3,2] row_mask:0xf bank_mask:0xf bound_ctrl:1
	v_pk_fma_f32 v[42:43], v[22:23], v[42:43], v[22:23] neg_lo:[1,0,0] neg_hi:[1,0,0]
	ds_read_b128 v[16:19], v91 offset:16384
	v_add_f32_dpp v96, v97, v97 quad_perm:[2,3,0,1] row_mask:0xf bank_mask:0xf bound_ctrl:1
	v_pk_fma_f32 v[40:41], v[38:39], v[44:45], v[40:41] op_sel_hi:[0,1,1]
	ds_read_b128 v[32:35], v91 offset:17152
	v_add_f32_dpp v97, v96, v96 row_half_mirror row_mask:0xf bank_mask:0xf bound_ctrl:1
	v_pk_fma_f32 v[42:43], v[38:39], v[46:47], v[42:43] op_sel_hi:[0,1,1]
	ds_read_b32 v36, v92 offset:17408
	v_add_f32_dpp v90, v97, v97 row_mirror row_mask:0xf bank_mask:0xf bound_ctrl:1
	ds_read_b128 v[28:31], v91 offset:16896
	v_pk_fma_f32 v[20:21], v[90:91], v[60:61], v[40:41] op_sel_hi:[0,1,1] neg_lo:[1,0,0] neg_hi:[1,0,0]
	v_pk_fma_f32 v[22:23], v[90:91], v[62:63], v[42:43] op_sel_hi:[0,1,1] neg_lo:[1,0,0] neg_hi:[1,0,0]
	ds_read_b128 v[40:43], v91 offset:17472
	ds_read_b128 v[60:63], v91 offset:17984
	s_waitcnt lgkmcnt(3)
; __device__ __forceinline__ void rwkv_scan_unit(const Params& p, int unit, char* smem) {
;     ...
;         const char* lb = smem + st + ks * 16;
;         const char* vb = smem + st + 1280 + rl * 4;
;         float* yl = (float*)(smem + YOFF + (ci & 1) * 1024) + rl;
;         f32x4 e4 = *(const f32x4*)(lb), kd4 = *(const f32x4*)(lb + 256), ka4 = *(const f32x4*)(lb + 512), r4 = *(const f32x4*)(lb + 768), kk4 = *(const f32x4*)(lb + 1024);
;         float vv = *(const float*)vb;
;         f32x2 sA = {s0, s1}, sB = {s2, s3};
;         float c;
;         { const f32x2 cv = sA * (f32x2){kk4[0], kk4[1]} + sB * (f32x2){kk4[2], kk4[3]}; c = red16(cv[0] + cv[1]); }
; #pragma unroll
;         for (int u = 0; u < SCH; ++u) {
;             f32x4 ne = e4, nkd = kd4, nka = ka4, nr = r4, nkk = kk4; float nv = vv;
;             if (u + 1 < SCH) { const char* q = lb + (u + 1) * STEPB;
;                 ne = *(const f32x4*)(q); nkd = *(const f32x4*)(q + 256); nka = *(const f32x4*)(q + 512); nr = *(const f32x4*)(q + 768); nkk = *(const f32x4*)(q + 1024);
;                 nv = *(const float*)(vb + (u + 1) * STEPB); }
;             const f32x2 v2 = {vv, vv}, c2 = {c, c};
;             const f32x2 tA = __builtin_elementwise_fma(v2, (f32x2){kd4[0], kd4[1]}, __builtin_elementwise_fma(-sA, (f32x2){e4[0], e4[1]}, sA));
;             const f32x2 tB = __builtin_elementwise_fma(v2, (f32x2){kd4[2], kd4[3]}, __builtin_elementwise_fma(-sB, (f32x2){e4[2], e4[3]}, sB));
;             sA = __builtin_elementwise_fma(-c2, (f32x2){ka4[0], ka4[1]}, tA);
;             sB = __builtin_elementwise_fma(-c2, (f32x2){ka4[2], ka4[3]}, tB);
;             const f32x2 yv = __builtin_elementwise_fma(sB, (f32x2){r4[2], r4[3]}, sA * (f32x2){r4[0], r4[1]});
;             float y = yv[0] + yv[1];
;             if (u + 1 < SCH) {
;                 const f32x2 cv = __builtin_elementwise_fma(sB, (f32x2){nkk[2], nkk[3]}, sA * (f32x2){nkk[0], nkk[1]});
;                 float cn = cv[0] + cv[1];
;                 cn = DPP_ADD(cn, 0xB1);  y = DPP_ADD(y, 0xB1);
;                 cn = DPP_ADD(cn, 0x4E);  y = DPP_ADD(y, 0x4E);
;                 cn = DPP_ADD(cn, 0x141); y = DPP_ADD(y, 0x141);
;                 cn = DPP_ADD(cn, 0x140); y = DPP_ADD(y, 0x140);
;                 c = cn;
;             } else y = red16(y);
;             if (ks == 0) yl[u * 16] = y;
	v_pk_mul_f32 v[32:33], v[20:21], v[32:33]
	v_pk_mul_f32 v[64:65], v[20:21], v[64:65]
	v_pk_fma_f32 v[32:33], v[22:23], v[34:35], v[32:33]
	v_pk_fma_f32 v[64:65], v[22:23], v[66:67], v[64:65]
	v_add_f32_e32 v34, v32, v33
	v_add_f32_e32 v243, v64, v65
	v_pk_fma_f32 v[12:13], v[20:21], v[12:13], v[20:21] neg_lo:[1,0,0] neg_hi:[1,0,0]
	v_add_f32_dpp v35, v34, v34 quad_perm:[1,0,3,2] row_mask:0xf bank_mask:0xf bound_ctrl:1
	v_pk_fma_f32 v[14:15], v[22:23], v[14:15], v[22:23] neg_lo:[1,0,0] neg_hi:[1,0,0]
	ds_read_b128 v[44:47], v91 offset:17728
	v_add_f32_dpp v34, v35, v35 quad_perm:[2,3,0,1] row_mask:0xf bank_mask:0xf bound_ctrl:1
	v_pk_fma_f32 v[12:13], v[36:37], v[16:17], v[12:13] op_sel_hi:[0,1,1]
	ds_read_b128 v[94:97], v91 offset:18496
	v_add_f32_dpp v35, v34, v34 row_half_mirror row_mask:0xf bank_mask:0xf bound_ctrl:1
	v_pk_fma_f32 v[14:15], v[36:37], v[18:19], v[14:15] op_sel_hi:[0,1,1]
	ds_read_b32 v38, v92 offset:18752
	v_add_f32_dpp v90, v35, v35 row_mirror row_mask:0xf bank_mask:0xf bound_ctrl:1
	ds_read_b128 v[64:67], v91 offset:18240
	v_pk_fma_f32 v[20:21], v[90:91], v[24:25], v[12:13] op_sel_hi:[0,1,1] neg_lo:[1,0,0] neg_hi:[1,0,0]
	v_pk_fma_f32 v[22:23], v[90:91], v[26:27], v[14:15] op_sel_hi:[0,1,1] neg_lo:[1,0,0] neg_hi:[1,0,0]
	ds_read_b128 v[12:15], v91 offset:18816
	ds_read_b128 v[24:27], v91 offset:19328
	s_waitcnt lgkmcnt(3)
	v_pk_mul_f32 v[94:95], v[20:21], v[94:95]
	v_pk_mul_f32 v[28:29], v[20:21], v[28:29]
	v_pk_fma_f32 v[94:95], v[22:23], v[96:97], v[94:95]
	v_pk_fma_f32 v[28:29], v[22:23], v[30:31], v[28:29]
	v_add_f32_e32 v96, v94, v95
	v_add_f32_e32 v244, v28, v29
	v_pk_fma_f32 v[40:41], v[20:21], v[40:41], v[20:21] neg_lo:[1,0,0] neg_hi:[1,0,0]
	v_add_f32_dpp v97, v96, v96 quad_perm:[1,0,3,2] row_mask:0xf bank_mask:0xf bound_ctrl:1
	v_pk_fma_f32 v[42:43], v[22:23], v[42:43], v[22:23] neg_lo:[1,0,0] neg_hi:[1,0,0]
	ds_read_b128 v[16:19], v91 offset:19072
	v_add_f32_dpp v96, v97, v97 quad_perm:[2,3,0,1] row_mask:0xf bank_mask:0xf bound_ctrl:1
	v_pk_fma_f32 v[40:41], v[38:39], v[44:45], v[40:41] op_sel_hi:[0,1,1]
	ds_read_b128 v[32:35], v91 offset:19840
	v_add_f32_dpp v97, v96, v96 row_half_mirror row_mask:0xf bank_mask:0xf bound_ctrl:1
	v_pk_fma_f32 v[42:43], v[38:39], v[46:47], v[42:43] op_sel_hi:[0,1,1]
	ds_read_b32 v36, v92 offset:20096
	v_add_f32_dpp v90, v97, v97 row_mirror row_mask:0xf bank_mask:0xf bound_ctrl:1
	ds_read_b128 v[28:31], v91 offset:19584
	v_pk_fma_f32 v[20:21], v[90:91], v[60:61], v[40:41] op_sel_hi:[0,1,1] neg_lo:[1,0,0] neg_hi:[1,0,0]
	v_pk_fma_f32 v[22:23], v[90:91], v[62:63], v[42:43] op_sel_hi:[0,1,1] neg_lo:[1,0,0] neg_hi:[1,0,0]
	ds_read_b128 v[40:43], v91 offset:20160
	ds_read_b128 v[60:63], v91 offset:20672
	s_waitcnt lgkmcnt(3)
	v_pk_mul_f32 v[32:33], v[20:21], v[32:33]
	v_pk_mul_f32 v[64:65], v[20:21], v[64:65]
	v_pk_fma_f32 v[32:33], v[22:23], v[34:35], v[32:33]
	v_pk_fma_f32 v[64:65], v[22:23], v[66:67], v[64:65]
	v_add_f32_e32 v34, v32, v33
	v_add_f32_e32 v245, v64, v65
	v_pk_fma_f32 v[12:13], v[20:21], v[12:13], v[20:21] neg_lo:[1,0,0] neg_hi:[1,0,0]
	v_add_f32_dpp v35, v34, v34 quad_perm:[1,0,3,2] row_mask:0xf bank_mask:0xf bound_ctrl:1
	v_pk_fma_f32 v[14:15], v[22:23], v[14:15], v[22:23] neg_lo:[1,0,0] neg_hi:[1,0,0]
	ds_read_b128 v[44:47], v91 offset:20416
	v_add_f32_dpp v34, v35, v35 quad_perm:[2,3,0,1] row_mask:0xf bank_mask:0xf bound_ctrl:1
	v_pk_fma_f32 v[12:13], v[36:37], v[16:17], v[12:13] op_sel_hi:[0,1,1]
	ds_read_b128 v[94:97], v91 offset:21184
	v_add_f32_dpp v35, v34, v34 row_half_mirror row_mask:0xf bank_mask:0xf bound_ctrl:1
	v_pk_fma_f32 v[14:15], v[36:37], v[18:19], v[14:15] op_sel_hi:[0,1,1]
	ds_read_b32 v38, v92 offset:21440
	v_add_f32_dpp v90, v35, v35 row_mirror row_mask:0xf bank_mask:0xf bound_ctrl:1
	ds_read_b128 v[64:67], v91 offset:20928
	v_pk_fma_f32 v[20:21], v[90:91], v[24:25], v[12:13] op_sel_hi:[0,1,1] neg_lo:[1,0,0] neg_hi:[1,0,0]
	v_pk_fma_f32 v[22:23], v[90:91], v[26:27], v[14:15] op_sel_hi:[0,1,1] neg_lo:[1,0,0] neg_hi:[1,0,0]
	s_waitcnt lgkmcnt(1)
	v_pk_mul_f32 v[94:95], v[20:21], v[94:95]
	v_pk_mul_f32 v[28:29], v[20:21], v[28:29]
	v_pk_fma_f32 v[94:95], v[22:23], v[96:97], v[94:95]
	v_pk_fma_f32 v[28:29], v[22:23], v[30:31], v[28:29]
	v_add_f32_e32 v96, v94, v95
	v_add_f32_e32 v246, v28, v29
	v_pk_fma_f32 v[40:41], v[20:21], v[40:41], v[20:21] neg_lo:[1,0,0] neg_hi:[1,0,0]
	v_add_f32_dpp v97, v96, v96 quad_perm:[1,0,3,2] row_mask:0xf bank_mask:0xf bound_ctrl:1
	v_pk_fma_f32 v[42:43], v[22:23], v[42:43], v[22:23] neg_lo:[1,0,0] neg_hi:[1,0,0]
	s_nop 0
	v_add_f32_dpp v96, v97, v97 quad_perm:[2,3,0,1] row_mask:0xf bank_mask:0xf bound_ctrl:1
	v_pk_fma_f32 v[40:41], v[38:39], v[44:45], v[40:41] op_sel_hi:[0,1,1]
	s_nop 0
	v_add_f32_dpp v97, v96, v96 row_half_mirror row_mask:0xf bank_mask:0xf bound_ctrl:1
	v_pk_fma_f32 v[42:43], v[38:39], v[46:47], v[42:43] op_sel_hi:[0,1,1]
	s_nop 0
	v_add_f32_dpp v90, v97, v97 row_mirror row_mask:0xf bank_mask:0xf bound_ctrl:1
	v_pk_fma_f32 v[20:21], v[90:91], v[60:61], v[40:41] op_sel_hi:[0,1,1] neg_lo:[1,0,0] neg_hi:[1,0,0]
	v_pk_fma_f32 v[22:23], v[90:91], v[62:63], v[42:43] op_sel_hi:[0,1,1] neg_lo:[1,0,0] neg_hi:[1,0,0]
	s_waitcnt lgkmcnt(0)
; #define DPP_ADD(v, ctrl) ((v) + __builtin_bit_cast(float, __builtin_amdgcn_update_dpp(0, __builtin_bit_cast(int, (v)), (ctrl), 0xf, 0xf, true)))
; #define SC_LSTORE(st_) { SC_S1(st_, 0, rg0) SC_S1(st_, 1, rg1) SC_S1(st_, 2, rg2) }
; __device__ __forceinline__ void rwkv_scan_unit(const Params& p, int unit, char* smem) {
;     ...
;         for (int u = 0; u < SCH; ++u) {
;             f32x4 ne = e4, nkd = kd4, nka = ka4, nr = r4, nkk = kk4; float nv = vv;
;             if (u + 1 < SCH) { const char* q = lb + (u + 1) * STEPB;
;                 ne = *(const f32x4*)(q); nkd = *(const f32x4*)(q + 256); nka = *(const f32x4*)(q + 512); nr = *(const f32x4*)(q + 768); nkk = *(const f32x4*)(q + 1024);
;                 nv = *(const float*)(vb + (u + 1) * STEPB); }
;             const f32x2 v2 = {vv, vv}, c2 = {c, c};
;             const f32x2 tA = __builtin_elementwise_fma(v2, (f32x2){kd4[0], kd4[1]}, __builtin_elementwise_fma(-sA, (f32x2){e4[0], e4[1]}, sA));
;             const f32x2 tB = __builtin_elementwise_fma(v2, (f32x2){kd4[2], kd4[3]}, __builtin_elementwise_fma(-sB, (f32x2){e4[2], e4[3]}, sB));
;             sA = __builtin_elementwise_fma(-c2, (f32x2){ka4[0], ka4[1]}, tA);
;             sB = __builtin_elementwise_fma(-c2, (f32x2){ka4[2], ka4[3]}, tB);
;             const f32x2 yv = __builtin_elementwise_fma(sB, (f32x2){r4[2], r4[3]}, sA * (f32x2){r4[0], r4[1]});
;             float y = yv[0] + yv[1];
;             if (u + 1 < SCH) {
;                 const f32x2 cv = __builtin_elementwise_fma(sB, (f32x2){nkk[2], nkk[3]}, sA * (f32x2){nkk[0], nkk[1]});
;                 float cn = cv[0] + cv[1];
;                 cn = DPP_ADD(cn, 0xB1);  y = DPP_ADD(y, 0xB1);
;                 cn = DPP_ADD(cn, 0x4E);  y = DPP_ADD(y, 0x4E);
;                 cn = DPP_ADD(cn, 0x141); y = DPP_ADD(y, 0x141);
;                 cn = DPP_ADD(cn, 0x140); y = DPP_ADD(y, 0x140);
;                 c = cn;
;             } else y = red16(y);
;             if (ks == 0) yl[u * 16] = y;
;             e4 = ne; kd4 = nkd; ka4 = nka; r4 = nr; kk4 = nkk; vv = nv;
;         }
;         s0 = sA[0]; s1 = sA[1]; s2 = sB[0]; s3 = sB[1];
;         __builtin_amdgcn_sched_barrier(0);
;         if (ci + 1 < NCH) { SC_LSTORE(((ci + 1) & 1) * STG) }
	v_pk_mul_f32 v[64:65], v[20:21], v[64:65]
	v_pk_fma_f32 v[64:65], v[22:23], v[66:67], v[64:65]
	s_nop 0
	v_add_f32_e32 v247, v64, v65
	s_mov_b32 s98, 0xaaaaaaaa
	s_mov_b32 s99, 0xaaaaaaaa
	s_mov_b32 s100, 0xcccccccc
	s_mov_b32 s101, 0xcccccccc
	v_add_f32_dpp v232, v232, v232 row_mirror row_mask:0xf bank_mask:0x3 bound_ctrl:1
	v_add_f32_dpp v233, v233, v233 row_mirror row_mask:0xf bank_mask:0x3 bound_ctrl:1
	v_add_f32_dpp v234, v234, v234 row_mirror row_mask:0xf bank_mask:0x3 bound_ctrl:1
	v_add_f32_dpp v235, v235, v235 row_mirror row_mask:0xf bank_mask:0x3 bound_ctrl:1
	v_add_f32_dpp v236, v236, v236 row_mirror row_mask:0xf bank_mask:0x3 bound_ctrl:1
	v_add_f32_dpp v237, v237, v237 row_mirror row_mask:0xf bank_mask:0x3 bound_ctrl:1
	v_add_f32_dpp v238, v238, v238 row_mirror row_mask:0xf bank_mask:0x3 bound_ctrl:1
	v_add_f32_dpp v239, v239, v239 row_mirror row_mask:0xf bank_mask:0x3 bound_ctrl:1
	v_add_f32_dpp v232, v240, v240 row_mirror row_mask:0xf bank_mask:0xc bound_ctrl:1
	v_add_f32_dpp v233, v241, v241 row_mirror row_mask:0xf bank_mask:0xc bound_ctrl:1
	v_add_f32_dpp v234, v242, v242 row_mirror row_mask:0xf bank_mask:0xc bound_ctrl:1
	v_add_f32_dpp v235, v243, v243 row_mirror row_mask:0xf bank_mask:0xc bound_ctrl:1
	v_add_f32_dpp v236, v244, v244 row_mirror row_mask:0xf bank_mask:0xc bound_ctrl:1
	v_add_f32_dpp v237, v245, v245 row_mirror row_mask:0xf bank_mask:0xc bound_ctrl:1
	v_add_f32_dpp v238, v246, v246 row_mirror row_mask:0xf bank_mask:0xc bound_ctrl:1
	v_add_f32_dpp v239, v247, v247 row_mirror row_mask:0xf bank_mask:0xc bound_ctrl:1
	v_add_f32_dpp v232, v232, v232 row_half_mirror row_mask:0xf bank_mask:0x5 bound_ctrl:1
	v_add_f32_dpp v233, v233, v233 row_half_mirror row_mask:0xf bank_mask:0x5 bound_ctrl:1
	v_add_f32_dpp v234, v234, v234 row_half_mirror row_mask:0xf bank_mask:0x5 bound_ctrl:1
	v_add_f32_dpp v235, v235, v235 row_half_mirror row_mask:0xf bank_mask:0x5 bound_ctrl:1
	v_add_f32_dpp v232, v236, v236 row_half_mirror row_mask:0xf bank_mask:0xa bound_ctrl:1
	v_add_f32_dpp v233, v237, v237 row_half_mirror row_mask:0xf bank_mask:0xa bound_ctrl:1
	v_add_f32_dpp v234, v238, v238 row_half_mirror row_mask:0xf bank_mask:0xa bound_ctrl:1
	v_add_f32_dpp v235, v239, v239 row_half_mirror row_mask:0xf bank_mask:0xa bound_ctrl:1
	v_cndmask_b32_e64 v240, v232, v234, s[100:101]
	v_cndmask_b32_e64 v241, v234, v232, s[100:101]
	v_cndmask_b32_e64 v242, v233, v235, s[100:101]
	v_cndmask_b32_e64 v243, v235, v233, s[100:101]
	s_nop 0
	v_add_f32_dpp v232, v241, v240 quad_perm:[2,3,0,1] row_mask:0xf bank_mask:0xf bound_ctrl:1
	v_add_f32_dpp v233, v243, v242 quad_perm:[2,3,0,1] row_mask:0xf bank_mask:0xf bound_ctrl:1
	s_nop 0
	v_cndmask_b32_e64 v240, v232, v233, s[98:99]
	v_cndmask_b32_e64 v241, v233, v232, s[98:99]
	v_add_u32_e32 v242, s52, v172
	s_nop 0
	v_add_f32_dpp v243, v241, v240 quad_perm:[1,0,3,2] row_mask:0xf bank_mask:0xf bound_ctrl:1
	ds_write_b32 v242, v243 offset:43008
	s_bitcmp1_b32 s64, 0
	s_cselect_b32 s0, 0x5400, 0
	s_waitcnt vmcnt(12)
	v_add3_u32 v16, s0, v74, v75
	v_cvt_f32_f16_sdwa v13, v140 dst_sel:DWORD dst_unused:UNUSED_PAD src0_sel:WORD_1
	v_cvt_f32_f16_e32 v12, v140
	v_cvt_f32_f16_sdwa v15, v141 dst_sel:DWORD dst_unused:UNUSED_PAD src0_sel:WORD_1
	v_cvt_f32_f16_e32 v14, v141
	ds_write_b128 v16, v[12:15]
	v_cvt_f32_f16_sdwa v13, v142 dst_sel:DWORD dst_unused:UNUSED_PAD src0_sel:WORD_1
	v_cvt_f32_f16_e32 v12, v142
	v_cvt_f32_f16_sdwa v15, v143 dst_sel:DWORD dst_unused:UNUSED_PAD src0_sel:WORD_1
	v_cvt_f32_f16_e32 v14, v143
	ds_write_b128 v16, v[12:15] offset:16
	v_add3_u32 v16, s0, v76, v77
	v_cvt_f32_f16_sdwa v13, v144 dst_sel:DWORD dst_unused:UNUSED_PAD src0_sel:WORD_1
	v_cvt_f32_f16_e32 v12, v144
	v_cvt_f32_f16_sdwa v15, v145 dst_sel:DWORD dst_unused:UNUSED_PAD src0_sel:WORD_1
	v_cvt_f32_f16_e32 v14, v145
	ds_write_b128 v16, v[12:15]
	v_cvt_f32_f16_sdwa v13, v146 dst_sel:DWORD dst_unused:UNUSED_PAD src0_sel:WORD_1
	v_cvt_f32_f16_e32 v12, v146
	v_cvt_f32_f16_sdwa v15, v147 dst_sel:DWORD dst_unused:UNUSED_PAD src0_sel:WORD_1
	v_cvt_f32_f16_e32 v14, v147
	ds_write_b128 v16, v[12:15] offset:16
	v_add3_u32 v16, s0, v78, v79
	v_cvt_f32_f16_sdwa v13, v148 dst_sel:DWORD dst_unused:UNUSED_PAD src0_sel:WORD_1
	v_cvt_f32_f16_e32 v12, v148
	v_cvt_f32_f16_sdwa v15, v149 dst_sel:DWORD dst_unused:UNUSED_PAD src0_sel:WORD_1
	v_cvt_f32_f16_e32 v14, v149
	ds_write_b128 v16, v[12:15]
	v_cvt_f32_f16_sdwa v13, v150 dst_sel:DWORD dst_unused:UNUSED_PAD src0_sel:WORD_1
	v_cvt_f32_f16_e32 v12, v150
	v_cvt_f32_f16_sdwa v15, v151 dst_sel:DWORD dst_unused:UNUSED_PAD src0_sel:WORD_1
	v_cvt_f32_f16_e32 v14, v151
	ds_write_b128 v16, v[12:15] offset:16

; __device__ __forceinline__ void rwkv_scan_unit(const Params& p, int unit, char* smem) {
;     ...
;         const char* lb = smem + st + ks * 16;
;         const char* vb = smem + st + 1280 + rl * 4;
;         float* yl = (float*)(smem + YOFF + (ci & 1) * 1024) + rl;
;         f32x4 e4 = *(const f32x4*)(lb), kd4 = *(const f32x4*)(lb + 256), ka4 = *(const f32x4*)(lb + 512), r4 = *(const f32x4*)(lb + 768), kk4 = *(const f32x4*)(lb + 1024);
;         float vv = *(const float*)vb;
;         f32x2 sA = {s0, s1}, sB = {s2, s3};
;         float c;
;         { const f32x2 cv = sA * (f32x2){kk4[0], kk4[1]} + sB * (f32x2){kk4[2], kk4[3]}; c = red16(cv[0] + cv[1]); }
; #pragma unroll
;         for (int u = 0; u < SCH; ++u) {
;             f32x4 ne = e4, nkd = kd4, nka = ka4, nr = r4, nkk = kk4; float nv = vv;
;             if (u + 1 < SCH) { const char* q = lb + (u + 1) * STEPB;
;                 ne = *(const f32x4*)(q); nkd = *(const f32x4*)(q + 256); nka = *(const f32x4*)(q + 512); nr = *(const f32x4*)(q + 768); nkk = *(const f32x4*)(q + 1024);
;                 nv = *(const float*)(vb + (u + 1) * STEPB); }
;             const f32x2 v2 = {vv, vv}, c2 = {c, c};
;             const f32x2 tA = __builtin_elementwise_fma(v2, (f32x2){kd4[0], kd4[1]}, __builtin_elementwise_fma(-sA, (f32x2){e4[0], e4[1]}, sA));
;             const f32x2 tB = __builtin_elementwise_fma(v2, (f32x2){kd4[2], kd4[3]}, __builtin_elementwise_fma(-sB, (f32x2){e4[2], e4[3]}, sB));
;             sA = __builtin_elementwise_fma(-c2, (f32x2){ka4[0], ka4[1]}, tA);
;             sB = __builtin_elementwise_fma(-c2, (f32x2){ka4[2], ka4[3]}, tB);
;             const f32x2 yv = __builtin_elementwise_fma(sB, (f32x2){r4[2], r4[3]}, sA * (f32x2){r4[0], r4[1]});
;             float y = yv[0] + yv[1];
;             if (u + 1 < SCH) {
;                 const f32x2 cv = __builtin_elementwise_fma(sB, (f32x2){nkk[2], nkk[3]}, sA * (f32x2){nkk[0], nkk[1]});
;                 float cn = cv[0] + cv[1];
;                 cn = DPP_ADD(cn, 0xB1);  y = DPP_ADD(y, 0xB1);
;                 cn = DPP_ADD(cn, 0x4E);  y = DPP_ADD(y, 0x4E);
;                 cn = DPP_ADD(cn, 0x141); y = DPP_ADD(y, 0x141);
;                 cn = DPP_ADD(cn, 0x140); y = DPP_ADD(y, 0x140);
;                 c = cn;
;             } else y = red16(y);
;             if (ks == 0) yl[u * 16] = y;
.Lsc_p2_body:
	s_add_i32 s30, s64, -1
	s_and_b32 s30, s30, 1
	s_mul_i32 s52, s30, 0x5400
	v_or_b32_e32 v91, s52, v80
	v_add_u32_e32 v92, s52, v81
	ds_read_b128 v[32:35], v91 offset:1024
	ds_read_b128 v[12:15], v91 offset:0
	ds_read_b128 v[16:19], v91 offset:256
	ds_read_b32 v36, v92 offset:1280
	ds_read_b128 v[24:27], v91 offset:512
	ds_read_b128 v[28:31], v91 offset:768
	ds_read_b128 v[40:43], v91 offset:1344
	ds_read_b128 v[60:63], v91 offset:1856
	ds_read_b128 v[44:47], v91 offset:1600
	ds_read_b128 v[94:97], v91 offset:2368
	ds_read_b32 v38, v92 offset:2624
	ds_read_b128 v[64:67], v91 offset:2112
	s_lshl_b32 s52, s30, 10
	s_waitcnt lgkmcnt(11)
	v_pk_mul_f32 v[32:33], v[20:21], v[32:33]
	s_waitcnt lgkmcnt(10)
	v_pk_fma_f32 v[12:13], v[20:21], v[12:13], v[20:21] neg_lo:[1,0,0] neg_hi:[1,0,0]
	v_pk_fma_f32 v[32:33], v[22:23], v[34:35], v[32:33]
	v_pk_fma_f32 v[14:15], v[22:23], v[14:15], v[22:23] neg_lo:[1,0,0] neg_hi:[1,0,0]
	v_add_f32_e32 v34, v32, v33
	s_waitcnt lgkmcnt(8)
	v_pk_fma_f32 v[12:13], v[36:37], v[16:17], v[12:13] op_sel_hi:[0,1,1]
	v_pk_fma_f32 v[14:15], v[36:37], v[18:19], v[14:15] op_sel_hi:[0,1,1]
	v_add_f32_dpp v35, v34, v34 quad_perm:[1,0,3,2] row_mask:0xf bank_mask:0xf bound_ctrl:1
	s_nop 1
	v_add_f32_dpp v34, v35, v35 quad_perm:[2,3,0,1] row_mask:0xf bank_mask:0xf bound_ctrl:1
	s_nop 1
	v_add_f32_dpp v35, v34, v34 row_half_mirror row_mask:0xf bank_mask:0xf bound_ctrl:1
	s_nop 1
	v_add_f32_dpp v90, v35, v35 row_mirror row_mask:0xf bank_mask:0xf bound_ctrl:1
	ds_read_b128 v[16:19], v91 offset:2944
	ds_read_b128 v[32:35], v91 offset:3712
	ds_read_b32 v36, v92 offset:3968
	s_waitcnt lgkmcnt(10)
	v_pk_fma_f32 v[20:21], v[90:91], v[24:25], v[12:13] op_sel_hi:[0,1,1] neg_lo:[1,0,0] neg_hi:[1,0,0]
	v_pk_fma_f32 v[22:23], v[90:91], v[26:27], v[14:15] op_sel_hi:[0,1,1] neg_lo:[1,0,0] neg_hi:[1,0,0]
	ds_read_b128 v[12:15], v91 offset:2688
	ds_read_b128 v[24:27], v91 offset:3200
	s_waitcnt lgkmcnt(7)
	v_pk_mul_f32 v[94:95], v[20:21], v[94:95]
	v_pk_mul_f32 v[28:29], v[20:21], v[28:29]
	v_pk_fma_f32 v[94:95], v[22:23], v[96:97], v[94:95]
	v_pk_fma_f32 v[28:29], v[22:23], v[30:31], v[28:29]
	v_add_f32_e32 v96, v94, v95
	v_add_f32_e32 v232, v28, v29
	v_pk_fma_f32 v[40:41], v[20:21], v[40:41], v[20:21] neg_lo:[1,0,0] neg_hi:[1,0,0]
	v_add_f32_dpp v97, v96, v96 quad_perm:[1,0,3,2] row_mask:0xf bank_mask:0xf bound_ctrl:1
	v_pk_fma_f32 v[42:43], v[22:23], v[42:43], v[22:23] neg_lo:[1,0,0] neg_hi:[1,0,0]
	s_nop 0
	v_add_f32_dpp v96, v97, v97 quad_perm:[2,3,0,1] row_mask:0xf bank_mask:0xf bound_ctrl:1
	s_waitcnt lgkmcnt(6)
	v_pk_fma_f32 v[40:41], v[38:39], v[44:45], v[40:41] op_sel_hi:[0,1,1]
	s_nop 0
	v_add_f32_dpp v97, v96, v96 row_half_mirror row_mask:0xf bank_mask:0xf bound_ctrl:1
	v_pk_fma_f32 v[42:43], v[38:39], v[46:47], v[42:43] op_sel_hi:[0,1,1]
	s_nop 0
	v_add_f32_dpp v90, v97, v97 row_mirror row_mask:0xf bank_mask:0xf bound_ctrl:1
	ds_read_b128 v[28:31], v91 offset:3456
	v_pk_fma_f32 v[20:21], v[90:91], v[60:61], v[40:41] op_sel_hi:[0,1,1] neg_lo:[1,0,0] neg_hi:[1,0,0]
	v_pk_fma_f32 v[22:23], v[90:91], v[62:63], v[42:43] op_sel_hi:[0,1,1] neg_lo:[1,0,0] neg_hi:[1,0,0]
	ds_read_b128 v[40:43], v91 offset:4032
	ds_read_b128 v[60:63], v91 offset:4544
	s_waitcnt lgkmcnt(4)
	v_pk_mul_f32 v[32:33], v[20:21], v[32:33]
	v_pk_mul_f32 v[64:65], v[20:21], v[64:65]
	v_pk_fma_f32 v[32:33], v[22:23], v[34:35], v[32:33]
	v_pk_fma_f32 v[64:65], v[22:23], v[66:67], v[64:65]
	v_add_f32_e32 v34, v32, v33
	v_add_f32_e32 v233, v64, v65
	v_pk_fma_f32 v[12:13], v[20:21], v[12:13], v[20:21] neg_lo:[1,0,0] neg_hi:[1,0,0]
	v_add_f32_dpp v35, v34, v34 quad_perm:[1,0,3,2] row_mask:0xf bank_mask:0xf bound_ctrl:1
	v_pk_fma_f32 v[14:15], v[22:23], v[14:15], v[22:23] neg_lo:[1,0,0] neg_hi:[1,0,0]
	ds_read_b128 v[44:47], v91 offset:4288
	v_add_f32_dpp v34, v35, v35 quad_perm:[2,3,0,1] row_mask:0xf bank_mask:0xf bound_ctrl:1
	v_pk_fma_f32 v[12:13], v[36:37], v[16:17], v[12:13] op_sel_hi:[0,1,1]
	ds_read_b128 v[94:97], v91 offset:5056
	v_add_f32_dpp v35, v34, v34 row_half_mirror row_mask:0xf bank_mask:0xf bound_ctrl:1
	v_pk_fma_f32 v[14:15], v[36:37], v[18:19], v[14:15] op_sel_hi:[0,1,1]
	ds_read_b32 v38, v92 offset:5312
	v_add_f32_dpp v90, v35, v35 row_mirror row_mask:0xf bank_mask:0xf bound_ctrl:1
	ds_read_b128 v[64:67], v91 offset:4800
	s_waitcnt lgkmcnt(7)
	v_pk_fma_f32 v[20:21], v[90:91], v[24:25], v[12:13] op_sel_hi:[0,1,1] neg_lo:[1,0,0] neg_hi:[1,0,0]
	v_pk_fma_f32 v[22:23], v[90:91], v[26:27], v[14:15] op_sel_hi:[0,1,1] neg_lo:[1,0,0] neg_hi:[1,0,0]
	ds_read_b128 v[12:15], v91 offset:5376
	ds_read_b128 v[24:27], v91 offset:5888
	s_waitcnt lgkmcnt(3)
	v_pk_mul_f32 v[94:95], v[20:21], v[94:95]
	v_pk_mul_f32 v[28:29], v[20:21], v[28:29]
	v_pk_fma_f32 v[94:95], v[22:23], v[96:97], v[94:95]
	v_pk_fma_f32 v[28:29], v[22:23], v[30:31], v[28:29]
	v_add_f32_e32 v96, v94, v95
	v_add_f32_e32 v234, v28, v29
	v_pk_fma_f32 v[40:41], v[20:21], v[40:41], v[20:21] neg_lo:[1,0,0] neg_hi:[1,0,0]
	v_add_f32_dpp v97, v96, v96 quad_perm:[1,0,3,2] row_mask:0xf bank_mask:0xf bound_ctrl:1
	v_pk_fma_f32 v[42:43], v[22:23], v[42:43], v[22:23] neg_lo:[1,0,0] neg_hi:[1,0,0]
	ds_read_b128 v[16:19], v91 offset:5632
	v_add_f32_dpp v96, v97, v97 quad_perm:[2,3,0,1] row_mask:0xf bank_mask:0xf bound_ctrl:1
	v_pk_fma_f32 v[40:41], v[38:39], v[44:45], v[40:41] op_sel_hi:[0,1,1]
	ds_read_b128 v[32:35], v91 offset:6400
	v_add_f32_dpp v97, v96, v96 row_half_mirror row_mask:0xf bank_mask:0xf bound_ctrl:1
	v_pk_fma_f32 v[42:43], v[38:39], v[46:47], v[42:43] op_sel_hi:[0,1,1]
	ds_read_b32 v36, v92 offset:6656
	v_add_f32_dpp v90, v97, v97 row_mirror row_mask:0xf bank_mask:0xf bound_ctrl:1
	ds_read_b128 v[28:31], v91 offset:6144
	v_pk_fma_f32 v[20:21], v[90:91], v[60:61], v[40:41] op_sel_hi:[0,1,1] neg_lo:[1,0,0] neg_hi:[1,0,0]
	v_pk_fma_f32 v[22:23], v[90:91], v[62:63], v[42:43] op_sel_hi:[0,1,1] neg_lo:[1,0,0] neg_hi:[1,0,0]
	ds_read_b128 v[40:43], v91 offset:6720
	ds_read_b128 v[60:63], v91 offset:7232
	s_waitcnt lgkmcnt(3)
; __device__ __forceinline__ void rwkv_scan_unit(const Params& p, int unit, char* smem) {
;     ...
;         const char* lb = smem + st + ks * 16;
;         const char* vb = smem + st + 1280 + rl * 4;
;         float* yl = (float*)(smem + YOFF + (ci & 1) * 1024) + rl;
;         f32x4 e4 = *(const f32x4*)(lb), kd4 = *(const f32x4*)(lb + 256), ka4 = *(const f32x4*)(lb + 512), r4 = *(const f32x4*)(lb + 768), kk4 = *(const f32x4*)(lb + 1024);
;         float vv = *(const float*)vb;
;         f32x2 sA = {s0, s1}, sB = {s2, s3};
;         float c;
;         { const f32x2 cv = sA * (f32x2){kk4[0], kk4[1]} + sB * (f32x2){kk4[2], kk4[3]}; c = red16(cv[0] + cv[1]); }
; #pragma unroll
;         for (int u = 0; u < SCH; ++u) {
;             f32x4 ne = e4, nkd = kd4, nka = ka4, nr = r4, nkk = kk4; float nv = vv;
;             if (u + 1 < SCH) { const char* q = lb + (u + 1) * STEPB;
;                 ne = *(const f32x4*)(q); nkd = *(const f32x4*)(q + 256); nka = *(const f32x4*)(q + 512); nr = *(const f32x4*)(q + 768); nkk = *(const f32x4*)(q + 1024);
;                 nv = *(const float*)(vb + (u + 1) * STEPB); }
;             const f32x2 v2 = {vv, vv}, c2 = {c, c};
;             const f32x2 tA = __builtin_elementwise_fma(v2, (f32x2){kd4[0], kd4[1]}, __builtin_elementwise_fma(-sA, (f32x2){e4[0], e4[1]}, sA));
;             const f32x2 tB = __builtin_elementwise_fma(v2, (f32x2){kd4[2], kd4[3]}, __builtin_elementwise_fma(-sB, (f32x2){e4[2], e4[3]}, sB));
;             sA = __builtin_elementwise_fma(-c2, (f32x2){ka4[0], ka4[1]}, tA);
;             sB = __builtin_elementwise_fma(-c2, (f32x2){ka4[2], ka4[3]}, tB);
;             const f32x2 yv = __builtin_elementwise_fma(sB, (f32x2){r4[2], r4[3]}, sA * (f32x2){r4[0], r4[1]});
;             float y = yv[0] + yv[1];
;             if (u + 1 < SCH) {
;                 const f32x2 cv = __builtin_elementwise_fma(sB, (f32x2){nkk[2], nkk[3]}, sA * (f32x2){nkk[0], nkk[1]});
;                 float cn = cv[0] + cv[1];
;                 cn = DPP_ADD(cn, 0xB1);  y = DPP_ADD(y, 0xB1);
;                 cn = DPP_ADD(cn, 0x4E);  y = DPP_ADD(y, 0x4E);
;                 cn = DPP_ADD(cn, 0x141); y = DPP_ADD(y, 0x141);
;                 cn = DPP_ADD(cn, 0x140); y = DPP_ADD(y, 0x140);
;                 c = cn;
;             } else y = red16(y);
;             if (ks == 0) yl[u * 16] = y;
	v_pk_mul_f32 v[32:33], v[20:21], v[32:33]
	v_pk_mul_f32 v[64:65], v[20:21], v[64:65]
	v_pk_fma_f32 v[32:33], v[22:23], v[34:35], v[32:33]
	v_pk_fma_f32 v[64:65], v[22:23], v[66:67], v[64:65]
	v_add_f32_e32 v34, v32, v33
	v_add_f32_e32 v235, v64, v65
	v_pk_fma_f32 v[12:13], v[20:21], v[12:13], v[20:21] neg_lo:[1,0,0] neg_hi:[1,0,0]
	v_add_f32_dpp v35, v34, v34 quad_perm:[1,0,3,2] row_mask:0xf bank_mask:0xf bound_ctrl:1
	v_pk_fma_f32 v[14:15], v[22:23], v[14:15], v[22:23] neg_lo:[1,0,0] neg_hi:[1,0,0]
	ds_read_b128 v[44:47], v91 offset:6976
	v_add_f32_dpp v34, v35, v35 quad_perm:[2,3,0,1] row_mask:0xf bank_mask:0xf bound_ctrl:1
	v_pk_fma_f32 v[12:13], v[36:37], v[16:17], v[12:13] op_sel_hi:[0,1,1]
	ds_read_b128 v[94:97], v91 offset:7744
	v_add_f32_dpp v35, v34, v34 row_half_mirror row_mask:0xf bank_mask:0xf bound_ctrl:1
	v_pk_fma_f32 v[14:15], v[36:37], v[18:19], v[14:15] op_sel_hi:[0,1,1]
	ds_read_b32 v38, v92 offset:8000
	v_add_f32_dpp v90, v35, v35 row_mirror row_mask:0xf bank_mask:0xf bound_ctrl:1
	ds_read_b128 v[64:67], v91 offset:7488
	v_pk_fma_f32 v[20:21], v[90:91], v[24:25], v[12:13] op_sel_hi:[0,1,1] neg_lo:[1,0,0] neg_hi:[1,0,0]
	v_pk_fma_f32 v[22:23], v[90:91], v[26:27], v[14:15] op_sel_hi:[0,1,1] neg_lo:[1,0,0] neg_hi:[1,0,0]
	ds_read_b128 v[12:15], v91 offset:8064
	ds_read_b128 v[24:27], v91 offset:8576
	s_waitcnt lgkmcnt(3)
	v_pk_mul_f32 v[94:95], v[20:21], v[94:95]
	v_pk_mul_f32 v[28:29], v[20:21], v[28:29]
	v_pk_fma_f32 v[94:95], v[22:23], v[96:97], v[94:95]
	v_pk_fma_f32 v[28:29], v[22:23], v[30:31], v[28:29]
	v_add_f32_e32 v96, v94, v95
	v_add_f32_e32 v236, v28, v29
	v_pk_fma_f32 v[40:41], v[20:21], v[40:41], v[20:21] neg_lo:[1,0,0] neg_hi:[1,0,0]
	v_add_f32_dpp v97, v96, v96 quad_perm:[1,0,3,2] row_mask:0xf bank_mask:0xf bound_ctrl:1
	v_pk_fma_f32 v[42:43], v[22:23], v[42:43], v[22:23] neg_lo:[1,0,0] neg_hi:[1,0,0]
	ds_read_b128 v[16:19], v91 offset:8320
	v_add_f32_dpp v96, v97, v97 quad_perm:[2,3,0,1] row_mask:0xf bank_mask:0xf bound_ctrl:1
	v_pk_fma_f32 v[40:41], v[38:39], v[44:45], v[40:41] op_sel_hi:[0,1,1]
	ds_read_b128 v[32:35], v91 offset:9088
	v_add_f32_dpp v97, v96, v96 row_half_mirror row_mask:0xf bank_mask:0xf bound_ctrl:1
	v_pk_fma_f32 v[42:43], v[38:39], v[46:47], v[42:43] op_sel_hi:[0,1,1]
	ds_read_b32 v36, v92 offset:9344
	v_add_f32_dpp v90, v97, v97 row_mirror row_mask:0xf bank_mask:0xf bound_ctrl:1
	ds_read_b128 v[28:31], v91 offset:8832
	v_pk_fma_f32 v[20:21], v[90:91], v[60:61], v[40:41] op_sel_hi:[0,1,1] neg_lo:[1,0,0] neg_hi:[1,0,0]
	v_pk_fma_f32 v[22:23], v[90:91], v[62:63], v[42:43] op_sel_hi:[0,1,1] neg_lo:[1,0,0] neg_hi:[1,0,0]
	ds_read_b128 v[40:43], v91 offset:9408
	ds_read_b128 v[60:63], v91 offset:9920
	s_waitcnt lgkmcnt(3)
	v_pk_mul_f32 v[32:33], v[20:21], v[32:33]
	v_pk_mul_f32 v[64:65], v[20:21], v[64:65]
	v_pk_fma_f32 v[32:33], v[22:23], v[34:35], v[32:33]
	v_pk_fma_f32 v[64:65], v[22:23], v[66:67], v[64:65]
	v_add_f32_e32 v34, v32, v33
	v_add_f32_e32 v237, v64, v65
	v_pk_fma_f32 v[12:13], v[20:21], v[12:13], v[20:21] neg_lo:[1,0,0] neg_hi:[1,0,0]
	v_add_f32_dpp v35, v34, v34 quad_perm:[1,0,3,2] row_mask:0xf bank_mask:0xf bound_ctrl:1
	v_pk_fma_f32 v[14:15], v[22:23], v[14:15], v[22:23] neg_lo:[1,0,0] neg_hi:[1,0,0]
	ds_read_b128 v[44:47], v91 offset:9664
	v_add_f32_dpp v34, v35, v35 quad_perm:[2,3,0,1] row_mask:0xf bank_mask:0xf bound_ctrl:1
	v_pk_fma_f32 v[12:13], v[36:37], v[16:17], v[12:13] op_sel_hi:[0,1,1]
	ds_read_b128 v[94:97], v91 offset:10432
	v_add_f32_dpp v35, v34, v34 row_half_mirror row_mask:0xf bank_mask:0xf bound_ctrl:1
	v_pk_fma_f32 v[14:15], v[36:37], v[18:19], v[14:15] op_sel_hi:[0,1,1]
	ds_read_b32 v38, v92 offset:10688
	v_add_f32_dpp v90, v35, v35 row_mirror row_mask:0xf bank_mask:0xf bound_ctrl:1
	ds_read_b128 v[64:67], v91 offset:10176
	v_pk_fma_f32 v[20:21], v[90:91], v[24:25], v[12:13] op_sel_hi:[0,1,1] neg_lo:[1,0,0] neg_hi:[1,0,0]
	v_pk_fma_f32 v[22:23], v[90:91], v[26:27], v[14:15] op_sel_hi:[0,1,1] neg_lo:[1,0,0] neg_hi:[1,0,0]
	ds_read_b128 v[12:15], v91 offset:10752
	ds_read_b128 v[24:27], v91 offset:11264
	s_waitcnt lgkmcnt(3)
	v_pk_mul_f32 v[94:95], v[20:21], v[94:95]
	v_pk_mul_f32 v[28:29], v[20:21], v[28:29]
	v_pk_fma_f32 v[94:95], v[22:23], v[96:97], v[94:95]
	v_pk_fma_f32 v[28:29], v[22:23], v[30:31], v[28:29]
	v_add_f32_e32 v96, v94, v95
	v_add_f32_e32 v238, v28, v29
	v_pk_fma_f32 v[40:41], v[20:21], v[40:41], v[20:21] neg_lo:[1,0,0] neg_hi:[1,0,0]
	v_add_f32_dpp v97, v96, v96 quad_perm:[1,0,3,2] row_mask:0xf bank_mask:0xf bound_ctrl:1
	v_pk_fma_f32 v[42:43], v[22:23], v[42:43], v[22:23] neg_lo:[1,0,0] neg_hi:[1,0,0]
	ds_read_b128 v[16:19], v91 offset:11008
	v_add_f32_dpp v96, v97, v97 quad_perm:[2,3,0,1] row_mask:0xf bank_mask:0xf bound_ctrl:1
	v_pk_fma_f32 v[40:41], v[38:39], v[44:45], v[40:41] op_sel_hi:[0,1,1]
	ds_read_b128 v[32:35], v91 offset:11776
	v_add_f32_dpp v97, v96, v96 row_half_mirror row_mask:0xf bank_mask:0xf bound_ctrl:1
	v_pk_fma_f32 v[42:43], v[38:39], v[46:47], v[42:43] op_sel_hi:[0,1,1]
	ds_read_b32 v36, v92 offset:12032
	v_add_f32_dpp v90, v97, v97 row_mirror row_mask:0xf bank_mask:0xf bound_ctrl:1
	ds_read_b128 v[28:31], v91 offset:11520
	v_pk_fma_f32 v[20:21], v[90:91], v[60:61], v[40:41] op_sel_hi:[0,1,1] neg_lo:[1,0,0] neg_hi:[1,0,0]
	v_pk_fma_f32 v[22:23], v[90:91], v[62:63], v[42:43] op_sel_hi:[0,1,1] neg_lo:[1,0,0] neg_hi:[1,0,0]
	ds_read_b128 v[40:43], v91 offset:12096
	ds_read_b128 v[60:63], v91 offset:12608
	s_waitcnt lgkmcnt(3)
; __device__ __forceinline__ void rwkv_scan_unit(const Params& p, int unit, char* smem) {
;     ...
;         const char* lb = smem + st + ks * 16;
;         const char* vb = smem + st + 1280 + rl * 4;
;         float* yl = (float*)(smem + YOFF + (ci & 1) * 1024) + rl;
;         f32x4 e4 = *(const f32x4*)(lb), kd4 = *(const f32x4*)(lb + 256), ka4 = *(const f32x4*)(lb + 512), r4 = *(const f32x4*)(lb + 768), kk4 = *(const f32x4*)(lb + 1024);
;         float vv = *(const float*)vb;
;         f32x2 sA = {s0, s1}, sB = {s2, s3};
;         float c;
;         { const f32x2 cv = sA * (f32x2){kk4[0], kk4[1]} + sB * (f32x2){kk4[2], kk4[3]}; c = red16(cv[0] + cv[1]); }
; #pragma unroll
;         for (int u = 0; u < SCH; ++u) {
;             f32x4 ne = e4, nkd = kd4, nka = ka4, nr = r4, nkk = kk4; float nv = vv;
;             if (u + 1 < SCH) { const char* q = lb + (u + 1) * STEPB;
;                 ne = *(const f32x4*)(q); nkd = *(const f32x4*)(q + 256); nka = *(const f32x4*)(q + 512); nr = *(const f32x4*)(q + 768); nkk = *(const f32x4*)(q + 1024);
;                 nv = *(const float*)(vb + (u + 1) * STEPB); }
;             const f32x2 v2 = {vv, vv}, c2 = {c, c};
;             const f32x2 tA = __builtin_elementwise_fma(v2, (f32x2){kd4[0], kd4[1]}, __builtin_elementwise_fma(-sA, (f32x2){e4[0], e4[1]}, sA));
;             const f32x2 tB = __builtin_elementwise_fma(v2, (f32x2){kd4[2], kd4[3]}, __builtin_elementwise_fma(-sB, (f32x2){e4[2], e4[3]}, sB));
;             sA = __builtin_elementwise_fma(-c2, (f32x2){ka4[0], ka4[1]}, tA);
;             sB = __builtin_elementwise_fma(-c2, (f32x2){ka4[2], ka4[3]}, tB);
;             const f32x2 yv = __builtin_elementwise_fma(sB, (f32x2){r4[2], r4[3]}, sA * (f32x2){r4[0], r4[1]});
;             float y = yv[0] + yv[1];
;             if (u + 1 < SCH) {
;                 const f32x2 cv = __builtin_elementwise_fma(sB, (f32x2){nkk[2], nkk[3]}, sA * (f32x2){nkk[0], nkk[1]});
;                 float cn = cv[0] + cv[1];
;                 cn = DPP_ADD(cn, 0xB1);  y = DPP_ADD(y, 0xB1);
;                 cn = DPP_ADD(cn, 0x4E);  y = DPP_ADD(y, 0x4E);
;                 cn = DPP_ADD(cn, 0x141); y = DPP_ADD(y, 0x141);
;                 cn = DPP_ADD(cn, 0x140); y = DPP_ADD(y, 0x140);
;                 c = cn;
;             } else y = red16(y);
;             if (ks == 0) yl[u * 16] = y;
	v_pk_mul_f32 v[32:33], v[20:21], v[32:33]
	v_pk_mul_f32 v[64:65], v[20:21], v[64:65]
	v_pk_fma_f32 v[32:33], v[22:23], v[34:35], v[32:33]
	v_pk_fma_f32 v[64:65], v[22:23], v[66:67], v[64:65]
	v_add_f32_e32 v34, v32, v33
	v_add_f32_e32 v239, v64, v65
	v_pk_fma_f32 v[12:13], v[20:21], v[12:13], v[20:21] neg_lo:[1,0,0] neg_hi:[1,0,0]
	v_add_f32_dpp v35, v34, v34 quad_perm:[1,0,3,2] row_mask:0xf bank_mask:0xf bound_ctrl:1
	v_pk_fma_f32 v[14:15], v[22:23], v[14:15], v[22:23] neg_lo:[1,0,0] neg_hi:[1,0,0]
	ds_read_b128 v[44:47], v91 offset:12352
	v_add_f32_dpp v34, v35, v35 quad_perm:[2,3,0,1] row_mask:0xf bank_mask:0xf bound_ctrl:1
	v_pk_fma_f32 v[12:13], v[36:37], v[16:17], v[12:13] op_sel_hi:[0,1,1]
	ds_read_b128 v[94:97], v91 offset:13120
	v_add_f32_dpp v35, v34, v34 row_half_mirror row_mask:0xf bank_mask:0xf bound_ctrl:1
	v_pk_fma_f32 v[14:15], v[36:37], v[18:19], v[14:15] op_sel_hi:[0,1,1]
	ds_read_b32 v38, v92 offset:13376
	v_add_f32_dpp v90, v35, v35 row_mirror row_mask:0xf bank_mask:0xf bound_ctrl:1
	ds_read_b128 v[64:67], v91 offset:12864
	v_pk_fma_f32 v[20:21], v[90:91], v[24:25], v[12:13] op_sel_hi:[0,1,1] neg_lo:[1,0,0] neg_hi:[1,0,0]
	v_pk_fma_f32 v[22:23], v[90:91], v[26:27], v[14:15] op_sel_hi:[0,1,1] neg_lo:[1,0,0] neg_hi:[1,0,0]
	ds_read_b128 v[12:15], v91 offset:13440
	ds_read_b128 v[24:27], v91 offset:13952
	s_waitcnt lgkmcnt(3)
	v_pk_mul_f32 v[94:95], v[20:21], v[94:95]
	v_pk_mul_f32 v[28:29], v[20:21], v[28:29]
	v_pk_fma_f32 v[94:95], v[22:23], v[96:97], v[94:95]
	v_pk_fma_f32 v[28:29], v[22:23], v[30:31], v[28:29]
	v_add_f32_e32 v96, v94, v95
	v_add_f32_e32 v240, v28, v29
	v_pk_fma_f32 v[40:41], v[20:21], v[40:41], v[20:21] neg_lo:[1,0,0] neg_hi:[1,0,0]
	v_add_f32_dpp v97, v96, v96 quad_perm:[1,0,3,2] row_mask:0xf bank_mask:0xf bound_ctrl:1
	v_pk_fma_f32 v[42:43], v[22:23], v[42:43], v[22:23] neg_lo:[1,0,0] neg_hi:[1,0,0]
	ds_read_b128 v[16:19], v91 offset:13696
	v_add_f32_dpp v96, v97, v97 quad_perm:[2,3,0,1] row_mask:0xf bank_mask:0xf bound_ctrl:1
	v_pk_fma_f32 v[40:41], v[38:39], v[44:45], v[40:41] op_sel_hi:[0,1,1]
	ds_read_b128 v[32:35], v91 offset:14464
	v_add_f32_dpp v97, v96, v96 row_half_mirror row_mask:0xf bank_mask:0xf bound_ctrl:1
	v_pk_fma_f32 v[42:43], v[38:39], v[46:47], v[42:43] op_sel_hi:[0,1,1]
	ds_read_b32 v36, v92 offset:14720
	v_add_f32_dpp v90, v97, v97 row_mirror row_mask:0xf bank_mask:0xf bound_ctrl:1
	ds_read_b128 v[28:31], v91 offset:14208
	v_pk_fma_f32 v[20:21], v[90:91], v[60:61], v[40:41] op_sel_hi:[0,1,1] neg_lo:[1,0,0] neg_hi:[1,0,0]
	v_pk_fma_f32 v[22:23], v[90:91], v[62:63], v[42:43] op_sel_hi:[0,1,1] neg_lo:[1,0,0] neg_hi:[1,0,0]
	ds_read_b128 v[40:43], v91 offset:14784
	ds_read_b128 v[60:63], v91 offset:15296
	s_waitcnt lgkmcnt(3)
	v_pk_mul_f32 v[32:33], v[20:21], v[32:33]
	v_pk_mul_f32 v[64:65], v[20:21], v[64:65]
	v_pk_fma_f32 v[32:33], v[22:23], v[34:35], v[32:33]
	v_pk_fma_f32 v[64:65], v[22:23], v[66:67], v[64:65]
	v_add_f32_e32 v34, v32, v33
	v_add_f32_e32 v241, v64, v65
	v_pk_fma_f32 v[12:13], v[20:21], v[12:13], v[20:21] neg_lo:[1,0,0] neg_hi:[1,0,0]
	v_add_f32_dpp v35, v34, v34 quad_perm:[1,0,3,2] row_mask:0xf bank_mask:0xf bound_ctrl:1
	v_pk_fma_f32 v[14:15], v[22:23], v[14:15], v[22:23] neg_lo:[1,0,0] neg_hi:[1,0,0]
	ds_read_b128 v[44:47], v91 offset:15040
	v_add_f32_dpp v34, v35, v35 quad_perm:[2,3,0,1] row_mask:0xf bank_mask:0xf bound_ctrl:1
	v_pk_fma_f32 v[12:13], v[36:37], v[16:17], v[12:13] op_sel_hi:[0,1,1]
	ds_read_b128 v[94:97], v91 offset:15808
	v_add_f32_dpp v35, v34, v34 row_half_mirror row_mask:0xf bank_mask:0xf bound_ctrl:1
	v_pk_fma_f32 v[14:15], v[36:37], v[18:19], v[14:15] op_sel_hi:[0,1,1]
	ds_read_b32 v38, v92 offset:16064
	v_add_f32_dpp v90, v35, v35 row_mirror row_mask:0xf bank_mask:0xf bound_ctrl:1
	ds_read_b128 v[64:67], v91 offset:15552
	v_pk_fma_f32 v[20:21], v[90:91], v[24:25], v[12:13] op_sel_hi:[0,1,1] neg_lo:[1,0,0] neg_hi:[1,0,0]
	v_pk_fma_f32 v[22:23], v[90:91], v[26:27], v[14:15] op_sel_hi:[0,1,1] neg_lo:[1,0,0] neg_hi:[1,0,0]
	ds_read_b128 v[12:15], v91 offset:16128
	ds_read_b128 v[24:27], v91 offset:16640
	s_waitcnt lgkmcnt(3)
	v_pk_mul_f32 v[94:95], v[20:21], v[94:95]
	v_pk_mul_f32 v[28:29], v[20:21], v[28:29]
	v_pk_fma_f32 v[94:95], v[22:23], v[96:97], v[94:95]
	v_pk_fma_f32 v[28:29], v[22:23], v[30:31], v[28:29]
	v_add_f32_e32 v96, v94, v95
	v_add_f32_e32 v242, v28, v29
	v_pk_fma_f32 v[40:41], v[20:21], v[40:41], v[20:21] neg_lo:[1,0,0] neg_hi:[1,0,0]
	v_add_f32_dpp v97, v96, v96 quad_perm:[1,0,3,2] row_mask:0xf bank_mask:0xf bound_ctrl:1
	v_pk_fma_f32 v[42:43], v[22:23], v[42:43], v[22:23] neg_lo:[1,0,0] neg_hi:[1,0,0]
	ds_read_b128 v[16:19], v91 offset:16384
	v_add_f32_dpp v96, v97, v97 quad_perm:[2,3,0,1] row_mask:0xf bank_mask:0xf bound_ctrl:1
	v_pk_fma_f32 v[40:41], v[38:39], v[44:45], v[40:41] op_sel_hi:[0,1,1]
	ds_read_b128 v[32:35], v91 offset:17152
	v_add_f32_dpp v97, v96, v96 row_half_mirror row_mask:0xf bank_mask:0xf bound_ctrl:1
	v_pk_fma_f32 v[42:43], v[38:39], v[46:47], v[42:43] op_sel_hi:[0,1,1]
	ds_read_b32 v36, v92 offset:17408
	v_add_f32_dpp v90, v97, v97 row_mirror row_mask:0xf bank_mask:0xf bound_ctrl:1
	ds_read_b128 v[28:31], v91 offset:16896
	v_pk_fma_f32 v[20:21], v[90:91], v[60:61], v[40:41] op_sel_hi:[0,1,1] neg_lo:[1,0,0] neg_hi:[1,0,0]
	v_pk_fma_f32 v[22:23], v[90:91], v[62:63], v[42:43] op_sel_hi:[0,1,1] neg_lo:[1,0,0] neg_hi:[1,0,0]
	ds_read_b128 v[40:43], v91 offset:17472
	ds_read_b128 v[60:63], v91 offset:17984
	s_waitcnt lgkmcnt(3)
; __device__ __forceinline__ void rwkv_scan_unit(const Params& p, int unit, char* smem) {
;     ...
;         const char* lb = smem + st + ks * 16;
;         const char* vb = smem + st + 1280 + rl * 4;
;         float* yl = (float*)(smem + YOFF + (ci & 1) * 1024) + rl;
;         f32x4 e4 = *(const f32x4*)(lb), kd4 = *(const f32x4*)(lb + 256), ka4 = *(const f32x4*)(lb + 512), r4 = *(const f32x4*)(lb + 768), kk4 = *(const f32x4*)(lb + 1024);
;         float vv = *(const float*)vb;
;         f32x2 sA = {s0, s1}, sB = {s2, s3};
;         float c;
;         { const f32x2 cv = sA * (f32x2){kk4[0], kk4[1]} + sB * (f32x2){kk4[2], kk4[3]}; c = red16(cv[0] + cv[1]); }
; #pragma unroll
;         for (int u = 0; u < SCH; ++u) {
;             f32x4 ne = e4, nkd = kd4, nka = ka4, nr = r4, nkk = kk4; float nv = vv;
;             if (u + 1 < SCH) { const char* q = lb + (u + 1) * STEPB;
;                 ne = *(const f32x4*)(q); nkd = *(const f32x4*)(q + 256); nka = *(const f32x4*)(q + 512); nr = *(const f32x4*)(q + 768); nkk = *(const f32x4*)(q + 1024);
;                 nv = *(const float*)(vb + (u + 1) * STEPB); }
;             const f32x2 v2 = {vv, vv}, c2 = {c, c};
;             const f32x2 tA = __builtin_elementwise_fma(v2, (f32x2){kd4[0], kd4[1]}, __builtin_elementwise_fma(-sA, (f32x2){e4[0], e4[1]}, sA));
;             const f32x2 tB = __builtin_elementwise_fma(v2, (f32x2){kd4[2], kd4[3]}, __builtin_elementwise_fma(-sB, (f32x2){e4[2], e4[3]}, sB));
;             sA = __builtin_elementwise_fma(-c2, (f32x2){ka4[0], ka4[1]}, tA);
;             sB = __builtin_elementwise_fma(-c2, (f32x2){ka4[2], ka4[3]}, tB);
;             const f32x2 yv = __builtin_elementwise_fma(sB, (f32x2){r4[2], r4[3]}, sA * (f32x2){r4[0], r4[1]});
;             float y = yv[0] + yv[1];
;             if (u + 1 < SCH) {
;                 const f32x2 cv = __builtin_elementwise_fma(sB, (f32x2){nkk[2], nkk[3]}, sA * (f32x2){nkk[0], nkk[1]});
;                 float cn = cv[0] + cv[1];
;                 cn = DPP_ADD(cn, 0xB1);  y = DPP_ADD(y, 0xB1);
;                 cn = DPP_ADD(cn, 0x4E);  y = DPP_ADD(y, 0x4E);
;                 cn = DPP_ADD(cn, 0x141); y = DPP_ADD(y, 0x141);
;                 cn = DPP_ADD(cn, 0x140); y = DPP_ADD(y, 0x140);
;                 c = cn;
;             } else y = red16(y);
;             if (ks == 0) yl[u * 16] = y;
	v_pk_mul_f32 v[32:33], v[20:21], v[32:33]
	v_pk_mul_f32 v[64:65], v[20:21], v[64:65]
	v_pk_fma_f32 v[32:33], v[22:23], v[34:35], v[32:33]
	v_pk_fma_f32 v[64:65], v[22:23], v[66:67], v[64:65]
	v_add_f32_e32 v34, v32, v33
	v_add_f32_e32 v243, v64, v65
	v_pk_fma_f32 v[12:13], v[20:21], v[12:13], v[20:21] neg_lo:[1,0,0] neg_hi:[1,0,0]
	v_add_f32_dpp v35, v34, v34 quad_perm:[1,0,3,2] row_mask:0xf bank_mask:0xf bound_ctrl:1
	v_pk_fma_f32 v[14:15], v[22:23], v[14:15], v[22:23] neg_lo:[1,0,0] neg_hi:[1,0,0]
	ds_read_b128 v[44:47], v91 offset:17728
	v_add_f32_dpp v34, v35, v35 quad_perm:[2,3,0,1] row_mask:0xf bank_mask:0xf bound_ctrl:1
	v_pk_fma_f32 v[12:13], v[36:37], v[16:17], v[12:13] op_sel_hi:[0,1,1]
	ds_read_b128 v[94:97], v91 offset:18496
	v_add_f32_dpp v35, v34, v34 row_half_mirror row_mask:0xf bank_mask:0xf bound_ctrl:1
	v_pk_fma_f32 v[14:15], v[36:37], v[18:19], v[14:15] op_sel_hi:[0,1,1]
	ds_read_b32 v38, v92 offset:18752
	v_add_f32_dpp v90, v35, v35 row_mirror row_mask:0xf bank_mask:0xf bound_ctrl:1
	ds_read_b128 v[64:67], v91 offset:18240
	v_pk_fma_f32 v[20:21], v[90:91], v[24:25], v[12:13] op_sel_hi:[0,1,1] neg_lo:[1,0,0] neg_hi:[1,0,0]
	v_pk_fma_f32 v[22:23], v[90:91], v[26:27], v[14:15] op_sel_hi:[0,1,1] neg_lo:[1,0,0] neg_hi:[1,0,0]
	ds_read_b128 v[12:15], v91 offset:18816
	ds_read_b128 v[24:27], v91 offset:19328
	s_waitcnt lgkmcnt(3)
	v_pk_mul_f32 v[94:95], v[20:21], v[94:95]
	v_pk_mul_f32 v[28:29], v[20:21], v[28:29]
	v_pk_fma_f32 v[94:95], v[22:23], v[96:97], v[94:95]
	v_pk_fma_f32 v[28:29], v[22:23], v[30:31], v[28:29]
	v_add_f32_e32 v96, v94, v95
	v_add_f32_e32 v244, v28, v29
	v_pk_fma_f32 v[40:41], v[20:21], v[40:41], v[20:21] neg_lo:[1,0,0] neg_hi:[1,0,0]
	v_add_f32_dpp v97, v96, v96 quad_perm:[1,0,3,2] row_mask:0xf bank_mask:0xf bound_ctrl:1
	v_pk_fma_f32 v[42:43], v[22:23], v[42:43], v[22:23] neg_lo:[1,0,0] neg_hi:[1,0,0]
	ds_read_b128 v[16:19], v91 offset:19072
	v_add_f32_dpp v96, v97, v97 quad_perm:[2,3,0,1] row_mask:0xf bank_mask:0xf bound_ctrl:1
	v_pk_fma_f32 v[40:41], v[38:39], v[44:45], v[40:41] op_sel_hi:[0,1,1]
	ds_read_b128 v[32:35], v91 offset:19840
	v_add_f32_dpp v97, v96, v96 row_half_mirror row_mask:0xf bank_mask:0xf bound_ctrl:1
	v_pk_fma_f32 v[42:43], v[38:39], v[46:47], v[42:43] op_sel_hi:[0,1,1]
	ds_read_b32 v36, v92 offset:20096
	v_add_f32_dpp v90, v97, v97 row_mirror row_mask:0xf bank_mask:0xf bound_ctrl:1
	ds_read_b128 v[28:31], v91 offset:19584
	v_pk_fma_f32 v[20:21], v[90:91], v[60:61], v[40:41] op_sel_hi:[0,1,1] neg_lo:[1,0,0] neg_hi:[1,0,0]
	v_pk_fma_f32 v[22:23], v[90:91], v[62:63], v[42:43] op_sel_hi:[0,1,1] neg_lo:[1,0,0] neg_hi:[1,0,0]
	ds_read_b128 v[40:43], v91 offset:20160
	ds_read_b128 v[60:63], v91 offset:20672
	s_waitcnt lgkmcnt(3)
	v_pk_mul_f32 v[32:33], v[20:21], v[32:33]
	v_pk_mul_f32 v[64:65], v[20:21], v[64:65]
	v_pk_fma_f32 v[32:33], v[22:23], v[34:35], v[32:33]
	v_pk_fma_f32 v[64:65], v[22:23], v[66:67], v[64:65]
	v_add_f32_e32 v34, v32, v33
	v_add_f32_e32 v245, v64, v65
	v_pk_fma_f32 v[12:13], v[20:21], v[12:13], v[20:21] neg_lo:[1,0,0] neg_hi:[1,0,0]
	v_add_f32_dpp v35, v34, v34 quad_perm:[1,0,3,2] row_mask:0xf bank_mask:0xf bound_ctrl:1
	v_pk_fma_f32 v[14:15], v[22:23], v[14:15], v[22:23] neg_lo:[1,0,0] neg_hi:[1,0,0]
	ds_read_b128 v[44:47], v91 offset:20416
	v_add_f32_dpp v34, v35, v35 quad_perm:[2,3,0,1] row_mask:0xf bank_mask:0xf bound_ctrl:1
	v_pk_fma_f32 v[12:13], v[36:37], v[16:17], v[12:13] op_sel_hi:[0,1,1]
	ds_read_b128 v[94:97], v91 offset:21184
	v_add_f32_dpp v35, v34, v34 row_half_mirror row_mask:0xf bank_mask:0xf bound_ctrl:1
	v_pk_fma_f32 v[14:15], v[36:37], v[18:19], v[14:15] op_sel_hi:[0,1,1]
	ds_read_b32 v38, v92 offset:21440
	v_add_f32_dpp v90, v35, v35 row_mirror row_mask:0xf bank_mask:0xf bound_ctrl:1
	ds_read_b128 v[64:67], v91 offset:20928
	v_pk_fma_f32 v[20:21], v[90:91], v[24:25], v[12:13] op_sel_hi:[0,1,1] neg_lo:[1,0,0] neg_hi:[1,0,0]
	v_pk_fma_f32 v[22:23], v[90:91], v[26:27], v[14:15] op_sel_hi:[0,1,1] neg_lo:[1,0,0] neg_hi:[1,0,0]
	s_waitcnt lgkmcnt(1)
	v_pk_mul_f32 v[94:95], v[20:21], v[94:95]
	v_pk_mul_f32 v[28:29], v[20:21], v[28:29]
	v_pk_fma_f32 v[94:95], v[22:23], v[96:97], v[94:95]
	v_pk_fma_f32 v[28:29], v[22:23], v[30:31], v[28:29]
	v_add_f32_e32 v96, v94, v95
	v_add_f32_e32 v246, v28, v29
	v_pk_fma_f32 v[40:41], v[20:21], v[40:41], v[20:21] neg_lo:[1,0,0] neg_hi:[1,0,0]
	v_add_f32_dpp v97, v96, v96 quad_perm:[1,0,3,2] row_mask:0xf bank_mask:0xf bound_ctrl:1
	v_pk_fma_f32 v[42:43], v[22:23], v[42:43], v[22:23] neg_lo:[1,0,0] neg_hi:[1,0,0]
	s_nop 0
	v_add_f32_dpp v96, v97, v97 quad_perm:[2,3,0,1] row_mask:0xf bank_mask:0xf bound_ctrl:1
	v_pk_fma_f32 v[40:41], v[38:39], v[44:45], v[40:41] op_sel_hi:[0,1,1]
	s_nop 0
	v_add_f32_dpp v97, v96, v96 row_half_mirror row_mask:0xf bank_mask:0xf bound_ctrl:1
	v_pk_fma_f32 v[42:43], v[38:39], v[46:47], v[42:43] op_sel_hi:[0,1,1]
	s_nop 0
	v_add_f32_dpp v90, v97, v97 row_mirror row_mask:0xf bank_mask:0xf bound_ctrl:1
	v_pk_fma_f32 v[20:21], v[90:91], v[60:61], v[40:41] op_sel_hi:[0,1,1] neg_lo:[1,0,0] neg_hi:[1,0,0]
	v_pk_fma_f32 v[22:23], v[90:91], v[62:63], v[42:43] op_sel_hi:[0,1,1] neg_lo:[1,0,0] neg_hi:[1,0,0]
	s_waitcnt lgkmcnt(0)
; #define DPP_ADD(v, ctrl) ((v) + __builtin_bit_cast(float, __builtin_amdgcn_update_dpp(0, __builtin_bit_cast(int, (v)), (ctrl), 0xf, 0xf, true)))
; #define SC_LSTORE(st_) { SC_S1(st_, 0, rg0) SC_S1(st_, 1, rg1) SC_S1(st_, 2, rg2) }
; __device__ __forceinline__ void rwkv_scan_unit(const Params& p, int unit, char* smem) {
;     ...
;             float y = yv[0] + yv[1];
;             if (u + 1 < SCH) {
;                 const f32x2 cv = __builtin_elementwise_fma(sB, (f32x2){nkk[2], nkk[3]}, sA * (f32x2){nkk[0], nkk[1]});
;                 float cn = cv[0] + cv[1];
;                 cn = DPP_ADD(cn, 0xB1);  y = DPP_ADD(y, 0xB1);
;                 cn = DPP_ADD(cn, 0x4E);  y = DPP_ADD(y, 0x4E);
;                 cn = DPP_ADD(cn, 0x141); y = DPP_ADD(y, 0x141);
;                 cn = DPP_ADD(cn, 0x140); y = DPP_ADD(y, 0x140);
;                 c = cn;
;             } else y = red16(y);
;             if (ks == 0) yl[u * 16] = y;
;             e4 = ne; kd4 = nkd; ka4 = nka; r4 = nr; kk4 = nkk; vv = nv;
;         }
;         s0 = sA[0]; s1 = sA[1]; s2 = sB[0]; s3 = sB[1];
;         __builtin_amdgcn_sched_barrier(0);
;         if (ci + 1 < NCH) { SC_LSTORE(((ci + 1) & 1) * STG) }
	v_pk_mul_f32 v[64:65], v[20:21], v[64:65]
	v_pk_fma_f32 v[64:65], v[22:23], v[66:67], v[64:65]
	s_nop 0
	v_add_f32_e32 v247, v64, v65
	s_mov_b32 s98, 0xaaaaaaaa
	s_mov_b32 s99, 0xaaaaaaaa
	s_mov_b32 s100, 0xcccccccc
	s_mov_b32 s101, 0xcccccccc
	v_add_f32_dpp v232, v232, v232 row_mirror row_mask:0xf bank_mask:0x3 bound_ctrl:1
	v_add_f32_dpp v233, v233, v233 row_mirror row_mask:0xf bank_mask:0x3 bound_ctrl:1
	v_add_f32_dpp v234, v234, v234 row_mirror row_mask:0xf bank_mask:0x3 bound_ctrl:1
	v_add_f32_dpp v235, v235, v235 row_mirror row_mask:0xf bank_mask:0x3 bound_ctrl:1
	v_add_f32_dpp v236, v236, v236 row_mirror row_mask:0xf bank_mask:0x3 bound_ctrl:1
	v_add_f32_dpp v237, v237, v237 row_mirror row_mask:0xf bank_mask:0x3 bound_ctrl:1
	v_add_f32_dpp v238, v238, v238 row_mirror row_mask:0xf bank_mask:0x3 bound_ctrl:1
	v_add_f32_dpp v239, v239, v239 row_mirror row_mask:0xf bank_mask:0x3 bound_ctrl:1
	v_add_f32_dpp v232, v240, v240 row_mirror row_mask:0xf bank_mask:0xc bound_ctrl:1
	v_add_f32_dpp v233, v241, v241 row_mirror row_mask:0xf bank_mask:0xc bound_ctrl:1
	v_add_f32_dpp v234, v242, v242 row_mirror row_mask:0xf bank_mask:0xc bound_ctrl:1
	v_add_f32_dpp v235, v243, v243 row_mirror row_mask:0xf bank_mask:0xc bound_ctrl:1
	v_add_f32_dpp v236, v244, v244 row_mirror row_mask:0xf bank_mask:0xc bound_ctrl:1
	v_add_f32_dpp v237, v245, v245 row_mirror row_mask:0xf bank_mask:0xc bound_ctrl:1
	v_add_f32_dpp v238, v246, v246 row_mirror row_mask:0xf bank_mask:0xc bound_ctrl:1
	v_add_f32_dpp v239, v247, v247 row_mirror row_mask:0xf bank_mask:0xc bound_ctrl:1
	v_add_f32_dpp v232, v232, v232 row_half_mirror row_mask:0xf bank_mask:0x5 bound_ctrl:1
	v_add_f32_dpp v233, v233, v233 row_half_mirror row_mask:0xf bank_mask:0x5 bound_ctrl:1
	v_add_f32_dpp v234, v234, v234 row_half_mirror row_mask:0xf bank_mask:0x5 bound_ctrl:1
	v_add_f32_dpp v235, v235, v235 row_half_mirror row_mask:0xf bank_mask:0x5 bound_ctrl:1
	v_add_f32_dpp v232, v236, v236 row_half_mirror row_mask:0xf bank_mask:0xa bound_ctrl:1
	v_add_f32_dpp v233, v237, v237 row_half_mirror row_mask:0xf bank_mask:0xa bound_ctrl:1
	v_add_f32_dpp v234, v238, v238 row_half_mirror row_mask:0xf bank_mask:0xa bound_ctrl:1
	v_add_f32_dpp v235, v239, v239 row_half_mirror row_mask:0xf bank_mask:0xa bound_ctrl:1
	v_cndmask_b32_e64 v240, v232, v234, s[100:101]
	v_cndmask_b32_e64 v241, v234, v232, s[100:101]
	v_cndmask_b32_e64 v242, v233, v235, s[100:101]
	v_cndmask_b32_e64 v243, v235, v233, s[100:101]
	s_nop 0
	v_add_f32_dpp v232, v241, v240 quad_perm:[2,3,0,1] row_mask:0xf bank_mask:0xf bound_ctrl:1
	v_add_f32_dpp v233, v243, v242 quad_perm:[2,3,0,1] row_mask:0xf bank_mask:0xf bound_ctrl:1
	s_nop 0
	v_cndmask_b32_e64 v240, v232, v233, s[98:99]
	v_cndmask_b32_e64 v241, v233, v232, s[98:99]
	v_add_u32_e32 v242, s52, v172
	s_nop 0
	v_add_f32_dpp v243, v241, v240 quad_perm:[1,0,3,2] row_mask:0xf bank_mask:0xf bound_ctrl:1
	ds_write_b32 v242, v243 offset:43008
	s_bitcmp1_b32 s64, 0
	s_cselect_b32 s0, 0x5400, 0
	s_waitcnt vmcnt(12)
	v_add3_u32 v16, s0, v74, v75
	v_cvt_f32_f16_sdwa v13, v124 dst_sel:DWORD dst_unused:UNUSED_PAD src0_sel:WORD_1
	v_cvt_f32_f16_e32 v12, v124
	v_cvt_f32_f16_sdwa v15, v125 dst_sel:DWORD dst_unused:UNUSED_PAD src0_sel:WORD_1
	v_cvt_f32_f16_e32 v14, v125
	ds_write_b128 v16, v[12:15]
	v_cvt_f32_f16_sdwa v13, v126 dst_sel:DWORD dst_unused:UNUSED_PAD src0_sel:WORD_1
	v_cvt_f32_f16_e32 v12, v126
	v_cvt_f32_f16_sdwa v15, v127 dst_sel:DWORD dst_unused:UNUSED_PAD src0_sel:WORD_1
	v_cvt_f32_f16_e32 v14, v127
	ds_write_b128 v16, v[12:15] offset:16
	v_add3_u32 v16, s0, v76, v77
	v_cvt_f32_f16_sdwa v13, v128 dst_sel:DWORD dst_unused:UNUSED_PAD src0_sel:WORD_1
	v_cvt_f32_f16_e32 v12, v128
	v_cvt_f32_f16_sdwa v15, v129 dst_sel:DWORD dst_unused:UNUSED_PAD src0_sel:WORD_1
	v_cvt_f32_f16_e32 v14, v129
	ds_write_b128 v16, v[12:15]
	v_cvt_f32_f16_sdwa v13, v130 dst_sel:DWORD dst_unused:UNUSED_PAD src0_sel:WORD_1
	v_cvt_f32_f16_e32 v12, v130
	v_cvt_f32_f16_sdwa v15, v131 dst_sel:DWORD dst_unused:UNUSED_PAD src0_sel:WORD_1
	v_cvt_f32_f16_e32 v14, v131
	ds_write_b128 v16, v[12:15] offset:16
	v_add3_u32 v16, s0, v78, v79
	v_cvt_f32_f16_sdwa v13, v132 dst_sel:DWORD dst_unused:UNUSED_PAD src0_sel:WORD_1
	v_cvt_f32_f16_e32 v12, v132
	v_cvt_f32_f16_sdwa v15, v133 dst_sel:DWORD dst_unused:UNUSED_PAD src0_sel:WORD_1
	v_cvt_f32_f16_e32 v14, v133
	ds_write_b128 v16, v[12:15]
	v_cvt_f32_f16_sdwa v13, v134 dst_sel:DWORD dst_unused:UNUSED_PAD src0_sel:WORD_1
	v_cvt_f32_f16_e32 v12, v134
	v_cvt_f32_f16_sdwa v15, v135 dst_sel:DWORD dst_unused:UNUSED_PAD src0_sel:WORD_1
	v_cvt_f32_f16_e32 v14, v135
	ds_write_b128 v16, v[12:15] offset:16

; #define DPP_ADD(v, ctrl) ((v) + __builtin_bit_cast(float, __builtin_amdgcn_update_dpp(0, __builtin_bit_cast(int, (v)), (ctrl), 0xf, 0xf, true)))
; __device__ __forceinline__ void rwkv_scan_unit(const Params& p, int unit, char* smem) {
;     ...
;         for (int u = 0; u < SCH; ++u) {
;             f32x4 ne = e4, nkd = kd4, nka = ka4, nr = r4, nkk = kk4; float nv = vv;
;             if (u + 1 < SCH) { const char* q = lb + (u + 1) * STEPB;
;                 ne = *(const f32x4*)(q); nkd = *(const f32x4*)(q + 256); nka = *(const f32x4*)(q + 512); nr = *(const f32x4*)(q + 768); nkk = *(const f32x4*)(q + 1024);
;                 nv = *(const float*)(vb + (u + 1) * STEPB); }
;             const f32x2 v2 = {vv, vv}, c2 = {c, c};
;             const f32x2 tA = __builtin_elementwise_fma(v2, (f32x2){kd4[0], kd4[1]}, __builtin_elementwise_fma(-sA, (f32x2){e4[0], e4[1]}, sA));
;             const f32x2 tB = __builtin_elementwise_fma(v2, (f32x2){kd4[2], kd4[3]}, __builtin_elementwise_fma(-sB, (f32x2){e4[2], e4[3]}, sB));
;             sA = __builtin_elementwise_fma(-c2, (f32x2){ka4[0], ka4[1]}, tA);
;             sB = __builtin_elementwise_fma(-c2, (f32x2){ka4[2], ka4[3]}, tB);
;             const f32x2 yv = __builtin_elementwise_fma(sB, (f32x2){r4[2], r4[3]}, sA * (f32x2){r4[0], r4[1]});
;             float y = yv[0] + yv[1];
;             if (u + 1 < SCH) {
;                 const f32x2 cv = __builtin_elementwise_fma(sB, (f32x2){nkk[2], nkk[3]}, sA * (f32x2){nkk[0], nkk[1]});
;                 float cn = cv[0] + cv[1];
;                 cn = DPP_ADD(cn, 0xB1);  y = DPP_ADD(y, 0xB1);
;                 cn = DPP_ADD(cn, 0x4E);  y = DPP_ADD(y, 0x4E);
;                 cn = DPP_ADD(cn, 0x141); y = DPP_ADD(y, 0x141);
;                 cn = DPP_ADD(cn, 0x140); y = DPP_ADD(y, 0x140);
;                 c = cn;
;             } else y = red16(y);
;             if (ks == 0) yl[u * 16] = y;
;             e4 = ne; kd4 = nkd; ka4 = nka; r4 = nr; kk4 = nkk; vv = nv;
;         }
.Lsc_p3_body:
	s_add_i32 s30, s64, -1
	s_and_b32 s30, s30, 1
	s_mul_i32 s52, s30, 0x5400
	v_or_b32_e32 v91, s52, v80
	v_add_u32_e32 v92, s52, v81
	ds_read_b128 v[32:35], v91 offset:1024
	ds_read_b128 v[12:15], v91 offset:0
	ds_read_b128 v[16:19], v91 offset:256
	ds_read_b32 v36, v92 offset:1280
	ds_read_b128 v[24:27], v91 offset:512
	ds_read_b128 v[28:31], v91 offset:768
	ds_read_b128 v[40:43], v91 offset:1344
	ds_read_b128 v[60:63], v91 offset:1856
	ds_read_b128 v[44:47], v91 offset:1600
	ds_read_b128 v[94:97], v91 offset:2368
	ds_read_b32 v38, v92 offset:2624
	ds_read_b128 v[64:67], v91 offset:2112
	s_lshl_b32 s52, s30, 10
	s_waitcnt lgkmcnt(11)
	v_pk_mul_f32 v[32:33], v[20:21], v[32:33]
	s_waitcnt lgkmcnt(10)
	v_pk_fma_f32 v[12:13], v[20:21], v[12:13], v[20:21] neg_lo:[1,0,0] neg_hi:[1,0,0]
	v_pk_fma_f32 v[32:33], v[22:23], v[34:35], v[32:33]
	v_pk_fma_f32 v[14:15], v[22:23], v[14:15], v[22:23] neg_lo:[1,0,0] neg_hi:[1,0,0]
	v_add_f32_e32 v34, v32, v33
	s_waitcnt lgkmcnt(8)
	v_pk_fma_f32 v[12:13], v[36:37], v[16:17], v[12:13] op_sel_hi:[0,1,1]
	v_pk_fma_f32 v[14:15], v[36:37], v[18:19], v[14:15] op_sel_hi:[0,1,1]
	v_add_f32_dpp v35, v34, v34 quad_perm:[1,0,3,2] row_mask:0xf bank_mask:0xf bound_ctrl:1
	s_nop 1
	v_add_f32_dpp v34, v35, v35 quad_perm:[2,3,0,1] row_mask:0xf bank_mask:0xf bound_ctrl:1
	s_nop 1
	v_add_f32_dpp v35, v34, v34 row_half_mirror row_mask:0xf bank_mask:0xf bound_ctrl:1
	s_nop 1
	v_add_f32_dpp v90, v35, v35 row_mirror row_mask:0xf bank_mask:0xf bound_ctrl:1
	ds_read_b128 v[16:19], v91 offset:2944
	ds_read_b128 v[32:35], v91 offset:3712
	ds_read_b32 v36, v92 offset:3968
	s_waitcnt lgkmcnt(10)
	v_pk_fma_f32 v[20:21], v[90:91], v[24:25], v[12:13] op_sel_hi:[0,1,1] neg_lo:[1,0,0] neg_hi:[1,0,0]
	v_pk_fma_f32 v[22:23], v[90:91], v[26:27], v[14:15] op_sel_hi:[0,1,1] neg_lo:[1,0,0] neg_hi:[1,0,0]
	ds_read_b128 v[12:15], v91 offset:2688
	ds_read_b128 v[24:27], v91 offset:3200
	s_waitcnt lgkmcnt(7)
	v_pk_mul_f32 v[94:95], v[20:21], v[94:95]
	v_pk_mul_f32 v[28:29], v[20:21], v[28:29]
	v_pk_fma_f32 v[94:95], v[22:23], v[96:97], v[94:95]
	v_pk_fma_f32 v[28:29], v[22:23], v[30:31], v[28:29]
	v_add_f32_e32 v96, v94, v95
	v_add_f32_e32 v232, v28, v29
	v_pk_fma_f32 v[40:41], v[20:21], v[40:41], v[20:21] neg_lo:[1,0,0] neg_hi:[1,0,0]
	v_add_f32_dpp v97, v96, v96 quad_perm:[1,0,3,2] row_mask:0xf bank_mask:0xf bound_ctrl:1
	v_pk_fma_f32 v[42:43], v[22:23], v[42:43], v[22:23] neg_lo:[1,0,0] neg_hi:[1,0,0]
	s_nop 0
	v_add_f32_dpp v96, v97, v97 quad_perm:[2,3,0,1] row_mask:0xf bank_mask:0xf bound_ctrl:1
	s_waitcnt lgkmcnt(6)
	v_pk_fma_f32 v[40:41], v[38:39], v[44:45], v[40:41] op_sel_hi:[0,1,1]
	s_nop 0
	v_add_f32_dpp v97, v96, v96 row_half_mirror row_mask:0xf bank_mask:0xf bound_ctrl:1
	v_pk_fma_f32 v[42:43], v[38:39], v[46:47], v[42:43] op_sel_hi:[0,1,1]
	s_nop 0
	v_add_f32_dpp v90, v97, v97 row_mirror row_mask:0xf bank_mask:0xf bound_ctrl:1
	ds_read_b128 v[28:31], v91 offset:3456
	v_pk_fma_f32 v[20:21], v[90:91], v[60:61], v[40:41] op_sel_hi:[0,1,1] neg_lo:[1,0,0] neg_hi:[1,0,0]
	v_pk_fma_f32 v[22:23], v[90:91], v[62:63], v[42:43] op_sel_hi:[0,1,1] neg_lo:[1,0,0] neg_hi:[1,0,0]
	ds_read_b128 v[40:43], v91 offset:4032
	ds_read_b128 v[60:63], v91 offset:4544
	s_waitcnt lgkmcnt(4)
	v_pk_mul_f32 v[32:33], v[20:21], v[32:33]
	v_pk_mul_f32 v[64:65], v[20:21], v[64:65]
	v_pk_fma_f32 v[32:33], v[22:23], v[34:35], v[32:33]
	v_pk_fma_f32 v[64:65], v[22:23], v[66:67], v[64:65]
	v_add_f32_e32 v34, v32, v33
	v_add_f32_e32 v233, v64, v65
	v_pk_fma_f32 v[12:13], v[20:21], v[12:13], v[20:21] neg_lo:[1,0,0] neg_hi:[1,0,0]
	v_add_f32_dpp v35, v34, v34 quad_perm:[1,0,3,2] row_mask:0xf bank_mask:0xf bound_ctrl:1
	v_pk_fma_f32 v[14:15], v[22:23], v[14:15], v[22:23] neg_lo:[1,0,0] neg_hi:[1,0,0]
	ds_read_b128 v[44:47], v91 offset:4288
	v_add_f32_dpp v34, v35, v35 quad_perm:[2,3,0,1] row_mask:0xf bank_mask:0xf bound_ctrl:1
	v_pk_fma_f32 v[12:13], v[36:37], v[16:17], v[12:13] op_sel_hi:[0,1,1]
	ds_read_b128 v[94:97], v91 offset:5056
	v_add_f32_dpp v35, v34, v34 row_half_mirror row_mask:0xf bank_mask:0xf bound_ctrl:1
	v_pk_fma_f32 v[14:15], v[36:37], v[18:19], v[14:15] op_sel_hi:[0,1,1]
	ds_read_b32 v38, v92 offset:5312
	v_add_f32_dpp v90, v35, v35 row_mirror row_mask:0xf bank_mask:0xf bound_ctrl:1
	ds_read_b128 v[64:67], v91 offset:4800
	s_waitcnt lgkmcnt(7)
	v_pk_fma_f32 v[20:21], v[90:91], v[24:25], v[12:13] op_sel_hi:[0,1,1] neg_lo:[1,0,0] neg_hi:[1,0,0]
	v_pk_fma_f32 v[22:23], v[90:91], v[26:27], v[14:15] op_sel_hi:[0,1,1] neg_lo:[1,0,0] neg_hi:[1,0,0]
	ds_read_b128 v[12:15], v91 offset:5376
	ds_read_b128 v[24:27], v91 offset:5888
	s_waitcnt lgkmcnt(3)
	v_pk_mul_f32 v[94:95], v[20:21], v[94:95]
	v_pk_mul_f32 v[28:29], v[20:21], v[28:29]
	v_pk_fma_f32 v[94:95], v[22:23], v[96:97], v[94:95]
	v_pk_fma_f32 v[28:29], v[22:23], v[30:31], v[28:29]
	v_add_f32_e32 v96, v94, v95
	v_add_f32_e32 v234, v28, v29
	v_pk_fma_f32 v[40:41], v[20:21], v[40:41], v[20:21] neg_lo:[1,0,0] neg_hi:[1,0,0]
	v_add_f32_dpp v97, v96, v96 quad_perm:[1,0,3,2] row_mask:0xf bank_mask:0xf bound_ctrl:1
	v_pk_fma_f32 v[42:43], v[22:23], v[42:43], v[22:23] neg_lo:[1,0,0] neg_hi:[1,0,0]
	ds_read_b128 v[16:19], v91 offset:5632
	v_add_f32_dpp v96, v97, v97 quad_perm:[2,3,0,1] row_mask:0xf bank_mask:0xf bound_ctrl:1
	v_pk_fma_f32 v[40:41], v[38:39], v[44:45], v[40:41] op_sel_hi:[0,1,1]
	ds_read_b128 v[32:35], v91 offset:6400
	v_add_f32_dpp v97, v96, v96 row_half_mirror row_mask:0xf bank_mask:0xf bound_ctrl:1
	v_pk_fma_f32 v[42:43], v[38:39], v[46:47], v[42:43] op_sel_hi:[0,1,1]
	ds_read_b32 v36, v92 offset:6656
	v_add_f32_dpp v90, v97, v97 row_mirror row_mask:0xf bank_mask:0xf bound_ctrl:1
	ds_read_b128 v[28:31], v91 offset:6144
	v_pk_fma_f32 v[20:21], v[90:91], v[60:61], v[40:41] op_sel_hi:[0,1,1] neg_lo:[1,0,0] neg_hi:[1,0,0]
	v_pk_fma_f32 v[22:23], v[90:91], v[62:63], v[42:43] op_sel_hi:[0,1,1] neg_lo:[1,0,0] neg_hi:[1,0,0]
	ds_read_b128 v[40:43], v91 offset:6720
	ds_read_b128 v[60:63], v91 offset:7232
	s_waitcnt lgkmcnt(3)
; #define DPP_ADD(v, ctrl) ((v) + __builtin_bit_cast(float, __builtin_amdgcn_update_dpp(0, __builtin_bit_cast(int, (v)), (ctrl), 0xf, 0xf, true)))
; __device__ __forceinline__ void rwkv_scan_unit(const Params& p, int unit, char* smem) {
;     ...
;         for (int u = 0; u < SCH; ++u) {
;             f32x4 ne = e4, nkd = kd4, nka = ka4, nr = r4, nkk = kk4; float nv = vv;
;             if (u + 1 < SCH) { const char* q = lb + (u + 1) * STEPB;
;                 ne = *(const f32x4*)(q); nkd = *(const f32x4*)(q + 256); nka = *(const f32x4*)(q + 512); nr = *(const f32x4*)(q + 768); nkk = *(const f32x4*)(q + 1024);
;                 nv = *(const float*)(vb + (u + 1) * STEPB); }
;             const f32x2 v2 = {vv, vv}, c2 = {c, c};
;             const f32x2 tA = __builtin_elementwise_fma(v2, (f32x2){kd4[0], kd4[1]}, __builtin_elementwise_fma(-sA, (f32x2){e4[0], e4[1]}, sA));
;             const f32x2 tB = __builtin_elementwise_fma(v2, (f32x2){kd4[2], kd4[3]}, __builtin_elementwise_fma(-sB, (f32x2){e4[2], e4[3]}, sB));
;             sA = __builtin_elementwise_fma(-c2, (f32x2){ka4[0], ka4[1]}, tA);
;             sB = __builtin_elementwise_fma(-c2, (f32x2){ka4[2], ka4[3]}, tB);
;             const f32x2 yv = __builtin_elementwise_fma(sB, (f32x2){r4[2], r4[3]}, sA * (f32x2){r4[0], r4[1]});
;             float y = yv[0] + yv[1];
;             if (u + 1 < SCH) {
;                 const f32x2 cv = __builtin_elementwise_fma(sB, (f32x2){nkk[2], nkk[3]}, sA * (f32x2){nkk[0], nkk[1]});
;                 float cn = cv[0] + cv[1];
;                 cn = DPP_ADD(cn, 0xB1);  y = DPP_ADD(y, 0xB1);
;                 cn = DPP_ADD(cn, 0x4E);  y = DPP_ADD(y, 0x4E);
;                 cn = DPP_ADD(cn, 0x141); y = DPP_ADD(y, 0x141);
;                 cn = DPP_ADD(cn, 0x140); y = DPP_ADD(y, 0x140);
;                 c = cn;
;             } else y = red16(y);
;             if (ks == 0) yl[u * 16] = y;
;             e4 = ne; kd4 = nkd; ka4 = nka; r4 = nr; kk4 = nkk; vv = nv;
;         }
	v_pk_mul_f32 v[32:33], v[20:21], v[32:33]
	v_pk_mul_f32 v[64:65], v[20:21], v[64:65]
	v_pk_fma_f32 v[32:33], v[22:23], v[34:35], v[32:33]
	v_pk_fma_f32 v[64:65], v[22:23], v[66:67], v[64:65]
	v_add_f32_e32 v34, v32, v33
	v_add_f32_e32 v235, v64, v65
	v_pk_fma_f32 v[12:13], v[20:21], v[12:13], v[20:21] neg_lo:[1,0,0] neg_hi:[1,0,0]
	v_add_f32_dpp v35, v34, v34 quad_perm:[1,0,3,2] row_mask:0xf bank_mask:0xf bound_ctrl:1
	v_pk_fma_f32 v[14:15], v[22:23], v[14:15], v[22:23] neg_lo:[1,0,0] neg_hi:[1,0,0]
	ds_read_b128 v[44:47], v91 offset:6976
	v_add_f32_dpp v34, v35, v35 quad_perm:[2,3,0,1] row_mask:0xf bank_mask:0xf bound_ctrl:1
	v_pk_fma_f32 v[12:13], v[36:37], v[16:17], v[12:13] op_sel_hi:[0,1,1]
	ds_read_b128 v[94:97], v91 offset:7744
	v_add_f32_dpp v35, v34, v34 row_half_mirror row_mask:0xf bank_mask:0xf bound_ctrl:1
	v_pk_fma_f32 v[14:15], v[36:37], v[18:19], v[14:15] op_sel_hi:[0,1,1]
	ds_read_b32 v38, v92 offset:8000
	v_add_f32_dpp v90, v35, v35 row_mirror row_mask:0xf bank_mask:0xf bound_ctrl:1
	ds_read_b128 v[64:67], v91 offset:7488
	v_pk_fma_f32 v[20:21], v[90:91], v[24:25], v[12:13] op_sel_hi:[0,1,1] neg_lo:[1,0,0] neg_hi:[1,0,0]
	v_pk_fma_f32 v[22:23], v[90:91], v[26:27], v[14:15] op_sel_hi:[0,1,1] neg_lo:[1,0,0] neg_hi:[1,0,0]
	ds_read_b128 v[12:15], v91 offset:8064
	ds_read_b128 v[24:27], v91 offset:8576
	s_waitcnt lgkmcnt(3)
	v_pk_mul_f32 v[94:95], v[20:21], v[94:95]
	v_pk_mul_f32 v[28:29], v[20:21], v[28:29]
	v_pk_fma_f32 v[94:95], v[22:23], v[96:97], v[94:95]
	v_pk_fma_f32 v[28:29], v[22:23], v[30:31], v[28:29]
	v_add_f32_e32 v96, v94, v95
	v_add_f32_e32 v236, v28, v29
	v_pk_fma_f32 v[40:41], v[20:21], v[40:41], v[20:21] neg_lo:[1,0,0] neg_hi:[1,0,0]
	v_add_f32_dpp v97, v96, v96 quad_perm:[1,0,3,2] row_mask:0xf bank_mask:0xf bound_ctrl:1
	v_pk_fma_f32 v[42:43], v[22:23], v[42:43], v[22:23] neg_lo:[1,0,0] neg_hi:[1,0,0]
	ds_read_b128 v[16:19], v91 offset:8320
	v_add_f32_dpp v96, v97, v97 quad_perm:[2,3,0,1] row_mask:0xf bank_mask:0xf bound_ctrl:1
	v_pk_fma_f32 v[40:41], v[38:39], v[44:45], v[40:41] op_sel_hi:[0,1,1]
	ds_read_b128 v[32:35], v91 offset:9088
	v_add_f32_dpp v97, v96, v96 row_half_mirror row_mask:0xf bank_mask:0xf bound_ctrl:1
	v_pk_fma_f32 v[42:43], v[38:39], v[46:47], v[42:43] op_sel_hi:[0,1,1]
	ds_read_b32 v36, v92 offset:9344
	v_add_f32_dpp v90, v97, v97 row_mirror row_mask:0xf bank_mask:0xf bound_ctrl:1
	ds_read_b128 v[28:31], v91 offset:8832
	v_pk_fma_f32 v[20:21], v[90:91], v[60:61], v[40:41] op_sel_hi:[0,1,1] neg_lo:[1,0,0] neg_hi:[1,0,0]
	v_pk_fma_f32 v[22:23], v[90:91], v[62:63], v[42:43] op_sel_hi:[0,1,1] neg_lo:[1,0,0] neg_hi:[1,0,0]
	ds_read_b128 v[40:43], v91 offset:9408
	ds_read_b128 v[60:63], v91 offset:9920
	s_waitcnt lgkmcnt(3)
	v_pk_mul_f32 v[32:33], v[20:21], v[32:33]
	v_pk_mul_f32 v[64:65], v[20:21], v[64:65]
	v_pk_fma_f32 v[32:33], v[22:23], v[34:35], v[32:33]
	v_pk_fma_f32 v[64:65], v[22:23], v[66:67], v[64:65]
	v_add_f32_e32 v34, v32, v33
	v_add_f32_e32 v237, v64, v65
	v_pk_fma_f32 v[12:13], v[20:21], v[12:13], v[20:21] neg_lo:[1,0,0] neg_hi:[1,0,0]
	v_add_f32_dpp v35, v34, v34 quad_perm:[1,0,3,2] row_mask:0xf bank_mask:0xf bound_ctrl:1
	v_pk_fma_f32 v[14:15], v[22:23], v[14:15], v[22:23] neg_lo:[1,0,0] neg_hi:[1,0,0]
	ds_read_b128 v[44:47], v91 offset:9664
	v_add_f32_dpp v34, v35, v35 quad_perm:[2,3,0,1] row_mask:0xf bank_mask:0xf bound_ctrl:1
	v_pk_fma_f32 v[12:13], v[36:37], v[16:17], v[12:13] op_sel_hi:[0,1,1]
	ds_read_b128 v[94:97], v91 offset:10432
	v_add_f32_dpp v35, v34, v34 row_half_mirror row_mask:0xf bank_mask:0xf bound_ctrl:1
	v_pk_fma_f32 v[14:15], v[36:37], v[18:19], v[14:15] op_sel_hi:[0,1,1]
	ds_read_b32 v38, v92 offset:10688
	v_add_f32_dpp v90, v35, v35 row_mirror row_mask:0xf bank_mask:0xf bound_ctrl:1
	ds_read_b128 v[64:67], v91 offset:10176
	v_pk_fma_f32 v[20:21], v[90:91], v[24:25], v[12:13] op_sel_hi:[0,1,1] neg_lo:[1,0,0] neg_hi:[1,0,0]
	v_pk_fma_f32 v[22:23], v[90:91], v[26:27], v[14:15] op_sel_hi:[0,1,1] neg_lo:[1,0,0] neg_hi:[1,0,0]
	ds_read_b128 v[12:15], v91 offset:10752
	ds_read_b128 v[24:27], v91 offset:11264
	s_waitcnt lgkmcnt(3)
	v_pk_mul_f32 v[94:95], v[20:21], v[94:95]
	v_pk_mul_f32 v[28:29], v[20:21], v[28:29]
	v_pk_fma_f32 v[94:95], v[22:23], v[96:97], v[94:95]
	v_pk_fma_f32 v[28:29], v[22:23], v[30:31], v[28:29]
	v_add_f32_e32 v96, v94, v95
	v_add_f32_e32 v238, v28, v29
	v_pk_fma_f32 v[40:41], v[20:21], v[40:41], v[20:21] neg_lo:[1,0,0] neg_hi:[1,0,0]
	v_add_f32_dpp v97, v96, v96 quad_perm:[1,0,3,2] row_mask:0xf bank_mask:0xf bound_ctrl:1
	v_pk_fma_f32 v[42:43], v[22:23], v[42:43], v[22:23] neg_lo:[1,0,0] neg_hi:[1,0,0]
	ds_read_b128 v[16:19], v91 offset:11008
	v_add_f32_dpp v96, v97, v97 quad_perm:[2,3,0,1] row_mask:0xf bank_mask:0xf bound_ctrl:1
	v_pk_fma_f32 v[40:41], v[38:39], v[44:45], v[40:41] op_sel_hi:[0,1,1]
	ds_read_b128 v[32:35], v91 offset:11776
	v_add_f32_dpp v97, v96, v96 row_half_mirror row_mask:0xf bank_mask:0xf bound_ctrl:1
	v_pk_fma_f32 v[42:43], v[38:39], v[46:47], v[42:43] op_sel_hi:[0,1,1]
	ds_read_b32 v36, v92 offset:12032
	v_add_f32_dpp v90, v97, v97 row_mirror row_mask:0xf bank_mask:0xf bound_ctrl:1
	ds_read_b128 v[28:31], v91 offset:11520
	v_pk_fma_f32 v[20:21], v[90:91], v[60:61], v[40:41] op_sel_hi:[0,1,1] neg_lo:[1,0,0] neg_hi:[1,0,0]
	v_pk_fma_f32 v[22:23], v[90:91], v[62:63], v[42:43] op_sel_hi:[0,1,1] neg_lo:[1,0,0] neg_hi:[1,0,0]
	ds_read_b128 v[40:43], v91 offset:12096
	ds_read_b128 v[60:63], v91 offset:12608
	s_waitcnt lgkmcnt(3)
; #define DPP_ADD(v, ctrl) ((v) + __builtin_bit_cast(float, __builtin_amdgcn_update_dpp(0, __builtin_bit_cast(int, (v)), (ctrl), 0xf, 0xf, true)))
; __device__ __forceinline__ void rwkv_scan_unit(const Params& p, int unit, char* smem) {
;     ...
;         for (int u = 0; u < SCH; ++u) {
;             f32x4 ne = e4, nkd = kd4, nka = ka4, nr = r4, nkk = kk4; float nv = vv;
;             if (u + 1 < SCH) { const char* q = lb + (u + 1) * STEPB;
;                 ne = *(const f32x4*)(q); nkd = *(const f32x4*)(q + 256); nka = *(const f32x4*)(q + 512); nr = *(const f32x4*)(q + 768); nkk = *(const f32x4*)(q + 1024);
;                 nv = *(const float*)(vb + (u + 1) * STEPB); }
;             const f32x2 v2 = {vv, vv}, c2 = {c, c};
;             const f32x2 tA = __builtin_elementwise_fma(v2, (f32x2){kd4[0], kd4[1]}, __builtin_elementwise_fma(-sA, (f32x2){e4[0], e4[1]}, sA));
;             const f32x2 tB = __builtin_elementwise_fma(v2, (f32x2){kd4[2], kd4[3]}, __builtin_elementwise_fma(-sB, (f32x2){e4[2], e4[3]}, sB));
;             sA = __builtin_elementwise_fma(-c2, (f32x2){ka4[0], ka4[1]}, tA);
;             sB = __builtin_elementwise_fma(-c2, (f32x2){ka4[2], ka4[3]}, tB);
;             const f32x2 yv = __builtin_elementwise_fma(sB, (f32x2){r4[2], r4[3]}, sA * (f32x2){r4[0], r4[1]});
;             float y = yv[0] + yv[1];
;             if (u + 1 < SCH) {
;                 const f32x2 cv = __builtin_elementwise_fma(sB, (f32x2){nkk[2], nkk[3]}, sA * (f32x2){nkk[0], nkk[1]});
;                 float cn = cv[0] + cv[1];
;                 cn = DPP_ADD(cn, 0xB1);  y = DPP_ADD(y, 0xB1);
;                 cn = DPP_ADD(cn, 0x4E);  y = DPP_ADD(y, 0x4E);
;                 cn = DPP_ADD(cn, 0x141); y = DPP_ADD(y, 0x141);
;                 cn = DPP_ADD(cn, 0x140); y = DPP_ADD(y, 0x140);
;                 c = cn;
;             } else y = red16(y);
;             if (ks == 0) yl[u * 16] = y;
;             e4 = ne; kd4 = nkd; ka4 = nka; r4 = nr; kk4 = nkk; vv = nv;
;         }
	v_pk_mul_f32 v[32:33], v[20:21], v[32:33]
	v_pk_mul_f32 v[64:65], v[20:21], v[64:65]
	v_pk_fma_f32 v[32:33], v[22:23], v[34:35], v[32:33]
	v_pk_fma_f32 v[64:65], v[22:23], v[66:67], v[64:65]
	v_add_f32_e32 v34, v32, v33
	v_add_f32_e32 v239, v64, v65
	v_pk_fma_f32 v[12:13], v[20:21], v[12:13], v[20:21] neg_lo:[1,0,0] neg_hi:[1,0,0]
	v_add_f32_dpp v35, v34, v34 quad_perm:[1,0,3,2] row_mask:0xf bank_mask:0xf bound_ctrl:1
	v_pk_fma_f32 v[14:15], v[22:23], v[14:15], v[22:23] neg_lo:[1,0,0] neg_hi:[1,0,0]
	ds_read_b128 v[44:47], v91 offset:12352
	v_add_f32_dpp v34, v35, v35 quad_perm:[2,3,0,1] row_mask:0xf bank_mask:0xf bound_ctrl:1
	v_pk_fma_f32 v[12:13], v[36:37], v[16:17], v[12:13] op_sel_hi:[0,1,1]
	ds_read_b128 v[94:97], v91 offset:13120
	v_add_f32_dpp v35, v34, v34 row_half_mirror row_mask:0xf bank_mask:0xf bound_ctrl:1
	v_pk_fma_f32 v[14:15], v[36:37], v[18:19], v[14:15] op_sel_hi:[0,1,1]
	ds_read_b32 v38, v92 offset:13376
	v_add_f32_dpp v90, v35, v35 row_mirror row_mask:0xf bank_mask:0xf bound_ctrl:1
	ds_read_b128 v[64:67], v91 offset:12864
	v_pk_fma_f32 v[20:21], v[90:91], v[24:25], v[12:13] op_sel_hi:[0,1,1] neg_lo:[1,0,0] neg_hi:[1,0,0]
	v_pk_fma_f32 v[22:23], v[90:91], v[26:27], v[14:15] op_sel_hi:[0,1,1] neg_lo:[1,0,0] neg_hi:[1,0,0]
	ds_read_b128 v[12:15], v91 offset:13440
	ds_read_b128 v[24:27], v91 offset:13952
	s_waitcnt lgkmcnt(3)
	v_pk_mul_f32 v[94:95], v[20:21], v[94:95]
	v_pk_mul_f32 v[28:29], v[20:21], v[28:29]
	v_pk_fma_f32 v[94:95], v[22:23], v[96:97], v[94:95]
	v_pk_fma_f32 v[28:29], v[22:23], v[30:31], v[28:29]
	v_add_f32_e32 v96, v94, v95
	v_add_f32_e32 v240, v28, v29
	v_pk_fma_f32 v[40:41], v[20:21], v[40:41], v[20:21] neg_lo:[1,0,0] neg_hi:[1,0,0]
	v_add_f32_dpp v97, v96, v96 quad_perm:[1,0,3,2] row_mask:0xf bank_mask:0xf bound_ctrl:1
	v_pk_fma_f32 v[42:43], v[22:23], v[42:43], v[22:23] neg_lo:[1,0,0] neg_hi:[1,0,0]
	ds_read_b128 v[16:19], v91 offset:13696
	v_add_f32_dpp v96, v97, v97 quad_perm:[2,3,0,1] row_mask:0xf bank_mask:0xf bound_ctrl:1
	v_pk_fma_f32 v[40:41], v[38:39], v[44:45], v[40:41] op_sel_hi:[0,1,1]
	ds_read_b128 v[32:35], v91 offset:14464
	v_add_f32_dpp v97, v96, v96 row_half_mirror row_mask:0xf bank_mask:0xf bound_ctrl:1
	v_pk_fma_f32 v[42:43], v[38:39], v[46:47], v[42:43] op_sel_hi:[0,1,1]
	ds_read_b32 v36, v92 offset:14720
	v_add_f32_dpp v90, v97, v97 row_mirror row_mask:0xf bank_mask:0xf bound_ctrl:1
	ds_read_b128 v[28:31], v91 offset:14208
	v_pk_fma_f32 v[20:21], v[90:91], v[60:61], v[40:41] op_sel_hi:[0,1,1] neg_lo:[1,0,0] neg_hi:[1,0,0]
	v_pk_fma_f32 v[22:23], v[90:91], v[62:63], v[42:43] op_sel_hi:[0,1,1] neg_lo:[1,0,0] neg_hi:[1,0,0]
	ds_read_b128 v[40:43], v91 offset:14784
	ds_read_b128 v[60:63], v91 offset:15296
	s_waitcnt lgkmcnt(3)
	v_pk_mul_f32 v[32:33], v[20:21], v[32:33]
	v_pk_mul_f32 v[64:65], v[20:21], v[64:65]
	v_pk_fma_f32 v[32:33], v[22:23], v[34:35], v[32:33]
	v_pk_fma_f32 v[64:65], v[22:23], v[66:67], v[64:65]
	v_add_f32_e32 v34, v32, v33
	v_add_f32_e32 v241, v64, v65
	v_pk_fma_f32 v[12:13], v[20:21], v[12:13], v[20:21] neg_lo:[1,0,0] neg_hi:[1,0,0]
	v_add_f32_dpp v35, v34, v34 quad_perm:[1,0,3,2] row_mask:0xf bank_mask:0xf bound_ctrl:1
	v_pk_fma_f32 v[14:15], v[22:23], v[14:15], v[22:23] neg_lo:[1,0,0] neg_hi:[1,0,0]
	ds_read_b128 v[44:47], v91 offset:15040
	v_add_f32_dpp v34, v35, v35 quad_perm:[2,3,0,1] row_mask:0xf bank_mask:0xf bound_ctrl:1
	v_pk_fma_f32 v[12:13], v[36:37], v[16:17], v[12:13] op_sel_hi:[0,1,1]
	ds_read_b128 v[94:97], v91 offset:15808
	v_add_f32_dpp v35, v34, v34 row_half_mirror row_mask:0xf bank_mask:0xf bound_ctrl:1
	v_pk_fma_f32 v[14:15], v[36:37], v[18:19], v[14:15] op_sel_hi:[0,1,1]
	ds_read_b32 v38, v92 offset:16064
	v_add_f32_dpp v90, v35, v35 row_mirror row_mask:0xf bank_mask:0xf bound_ctrl:1
	ds_read_b128 v[64:67], v91 offset:15552
	v_pk_fma_f32 v[20:21], v[90:91], v[24:25], v[12:13] op_sel_hi:[0,1,1] neg_lo:[1,0,0] neg_hi:[1,0,0]
	v_pk_fma_f32 v[22:23], v[90:91], v[26:27], v[14:15] op_sel_hi:[0,1,1] neg_lo:[1,0,0] neg_hi:[1,0,0]
	ds_read_b128 v[12:15], v91 offset:16128
	ds_read_b128 v[24:27], v91 offset:16640
	s_waitcnt lgkmcnt(3)
	v_pk_mul_f32 v[94:95], v[20:21], v[94:95]
	v_pk_mul_f32 v[28:29], v[20:21], v[28:29]
	v_pk_fma_f32 v[94:95], v[22:23], v[96:97], v[94:95]
	v_pk_fma_f32 v[28:29], v[22:23], v[30:31], v[28:29]
	v_add_f32_e32 v96, v94, v95
	v_add_f32_e32 v242, v28, v29
	v_pk_fma_f32 v[40:41], v[20:21], v[40:41], v[20:21] neg_lo:[1,0,0] neg_hi:[1,0,0]
	v_add_f32_dpp v97, v96, v96 quad_perm:[1,0,3,2] row_mask:0xf bank_mask:0xf bound_ctrl:1
	v_pk_fma_f32 v[42:43], v[22:23], v[42:43], v[22:23] neg_lo:[1,0,0] neg_hi:[1,0,0]
	ds_read_b128 v[16:19], v91 offset:16384
	v_add_f32_dpp v96, v97, v97 quad_perm:[2,3,0,1] row_mask:0xf bank_mask:0xf bound_ctrl:1
	v_pk_fma_f32 v[40:41], v[38:39], v[44:45], v[40:41] op_sel_hi:[0,1,1]
	ds_read_b128 v[32:35], v91 offset:17152
	v_add_f32_dpp v97, v96, v96 row_half_mirror row_mask:0xf bank_mask:0xf bound_ctrl:1
	v_pk_fma_f32 v[42:43], v[38:39], v[46:47], v[42:43] op_sel_hi:[0,1,1]
	ds_read_b32 v36, v92 offset:17408
	v_add_f32_dpp v90, v97, v97 row_mirror row_mask:0xf bank_mask:0xf bound_ctrl:1
	ds_read_b128 v[28:31], v91 offset:16896
	v_pk_fma_f32 v[20:21], v[90:91], v[60:61], v[40:41] op_sel_hi:[0,1,1] neg_lo:[1,0,0] neg_hi:[1,0,0]
	v_pk_fma_f32 v[22:23], v[90:91], v[62:63], v[42:43] op_sel_hi:[0,1,1] neg_lo:[1,0,0] neg_hi:[1,0,0]
	ds_read_b128 v[40:43], v91 offset:17472
	ds_read_b128 v[60:63], v91 offset:17984
	s_waitcnt lgkmcnt(3)
; #define DPP_ADD(v, ctrl) ((v) + __builtin_bit_cast(float, __builtin_amdgcn_update_dpp(0, __builtin_bit_cast(int, (v)), (ctrl), 0xf, 0xf, true)))
; __device__ __forceinline__ void rwkv_scan_unit(const Params& p, int unit, char* smem) {
;     ...
;         for (int u = 0; u < SCH; ++u) {
;             f32x4 ne = e4, nkd = kd4, nka = ka4, nr = r4, nkk = kk4; float nv = vv;
;             if (u + 1 < SCH) { const char* q = lb + (u + 1) * STEPB;
;                 ne = *(const f32x4*)(q); nkd = *(const f32x4*)(q + 256); nka = *(const f32x4*)(q + 512); nr = *(const f32x4*)(q + 768); nkk = *(const f32x4*)(q + 1024);
;                 nv = *(const float*)(vb + (u + 1) * STEPB); }
;             const f32x2 v2 = {vv, vv}, c2 = {c, c};
;             const f32x2 tA = __builtin_elementwise_fma(v2, (f32x2){kd4[0], kd4[1]}, __builtin_elementwise_fma(-sA, (f32x2){e4[0], e4[1]}, sA));
;             const f32x2 tB = __builtin_elementwise_fma(v2, (f32x2){kd4[2], kd4[3]}, __builtin_elementwise_fma(-sB, (f32x2){e4[2], e4[3]}, sB));
;             sA = __builtin_elementwise_fma(-c2, (f32x2){ka4[0], ka4[1]}, tA);
;             sB = __builtin_elementwise_fma(-c2, (f32x2){ka4[2], ka4[3]}, tB);
;             const f32x2 yv = __builtin_elementwise_fma(sB, (f32x2){r4[2], r4[3]}, sA * (f32x2){r4[0], r4[1]});
;             float y = yv[0] + yv[1];
;             if (u + 1 < SCH) {
;                 const f32x2 cv = __builtin_elementwise_fma(sB, (f32x2){nkk[2], nkk[3]}, sA * (f32x2){nkk[0], nkk[1]});
;                 float cn = cv[0] + cv[1];
;                 cn = DPP_ADD(cn, 0xB1);  y = DPP_ADD(y, 0xB1);
;                 cn = DPP_ADD(cn, 0x4E);  y = DPP_ADD(y, 0x4E);
;                 cn = DPP_ADD(cn, 0x141); y = DPP_ADD(y, 0x141);
;                 cn = DPP_ADD(cn, 0x140); y = DPP_ADD(y, 0x140);
;                 c = cn;
;             } else y = red16(y);
;             if (ks == 0) yl[u * 16] = y;
;             e4 = ne; kd4 = nkd; ka4 = nka; r4 = nr; kk4 = nkk; vv = nv;
;         }
	v_pk_mul_f32 v[32:33], v[20:21], v[32:33]
	v_pk_mul_f32 v[64:65], v[20:21], v[64:65]
	v_pk_fma_f32 v[32:33], v[22:23], v[34:35], v[32:33]
	v_pk_fma_f32 v[64:65], v[22:23], v[66:67], v[64:65]
	v_add_f32_e32 v34, v32, v33
	v_add_f32_e32 v243, v64, v65
	v_pk_fma_f32 v[12:13], v[20:21], v[12:13], v[20:21] neg_lo:[1,0,0] neg_hi:[1,0,0]
	v_add_f32_dpp v35, v34, v34 quad_perm:[1,0,3,2] row_mask:0xf bank_mask:0xf bound_ctrl:1
	v_pk_fma_f32 v[14:15], v[22:23], v[14:15], v[22:23] neg_lo:[1,0,0] neg_hi:[1,0,0]
	ds_read_b128 v[44:47], v91 offset:17728
	v_add_f32_dpp v34, v35, v35 quad_perm:[2,3,0,1] row_mask:0xf bank_mask:0xf bound_ctrl:1
	v_pk_fma_f32 v[12:13], v[36:37], v[16:17], v[12:13] op_sel_hi:[0,1,1]
	ds_read_b128 v[94:97], v91 offset:18496
	v_add_f32_dpp v35, v34, v34 row_half_mirror row_mask:0xf bank_mask:0xf bound_ctrl:1
	v_pk_fma_f32 v[14:15], v[36:37], v[18:19], v[14:15] op_sel_hi:[0,1,1]
	ds_read_b32 v38, v92 offset:18752
	v_add_f32_dpp v90, v35, v35 row_mirror row_mask:0xf bank_mask:0xf bound_ctrl:1
	ds_read_b128 v[64:67], v91 offset:18240
	v_pk_fma_f32 v[20:21], v[90:91], v[24:25], v[12:13] op_sel_hi:[0,1,1] neg_lo:[1,0,0] neg_hi:[1,0,0]
	v_pk_fma_f32 v[22:23], v[90:91], v[26:27], v[14:15] op_sel_hi:[0,1,1] neg_lo:[1,0,0] neg_hi:[1,0,0]
	ds_read_b128 v[12:15], v91 offset:18816
	ds_read_b128 v[24:27], v91 offset:19328
	s_waitcnt lgkmcnt(3)
	v_pk_mul_f32 v[94:95], v[20:21], v[94:95]
	v_pk_mul_f32 v[28:29], v[20:21], v[28:29]
	v_pk_fma_f32 v[94:95], v[22:23], v[96:97], v[94:95]
	v_pk_fma_f32 v[28:29], v[22:23], v[30:31], v[28:29]
	v_add_f32_e32 v96, v94, v95
	v_add_f32_e32 v244, v28, v29
	v_pk_fma_f32 v[40:41], v[20:21], v[40:41], v[20:21] neg_lo:[1,0,0] neg_hi:[1,0,0]
	v_add_f32_dpp v97, v96, v96 quad_perm:[1,0,3,2] row_mask:0xf bank_mask:0xf bound_ctrl:1
	v_pk_fma_f32 v[42:43], v[22:23], v[42:43], v[22:23] neg_lo:[1,0,0] neg_hi:[1,0,0]
	ds_read_b128 v[16:19], v91 offset:19072
	v_add_f32_dpp v96, v97, v97 quad_perm:[2,3,0,1] row_mask:0xf bank_mask:0xf bound_ctrl:1
	v_pk_fma_f32 v[40:41], v[38:39], v[44:45], v[40:41] op_sel_hi:[0,1,1]
	ds_read_b128 v[32:35], v91 offset:19840
	v_add_f32_dpp v97, v96, v96 row_half_mirror row_mask:0xf bank_mask:0xf bound_ctrl:1
	v_pk_fma_f32 v[42:43], v[38:39], v[46:47], v[42:43] op_sel_hi:[0,1,1]
	ds_read_b32 v36, v92 offset:20096
	v_add_f32_dpp v90, v97, v97 row_mirror row_mask:0xf bank_mask:0xf bound_ctrl:1
	ds_read_b128 v[28:31], v91 offset:19584
	v_pk_fma_f32 v[20:21], v[90:91], v[60:61], v[40:41] op_sel_hi:[0,1,1] neg_lo:[1,0,0] neg_hi:[1,0,0]
	v_pk_fma_f32 v[22:23], v[90:91], v[62:63], v[42:43] op_sel_hi:[0,1,1] neg_lo:[1,0,0] neg_hi:[1,0,0]
	ds_read_b128 v[40:43], v91 offset:20160
	ds_read_b128 v[60:63], v91 offset:20672
	s_waitcnt lgkmcnt(3)
	v_pk_mul_f32 v[32:33], v[20:21], v[32:33]
	v_pk_mul_f32 v[64:65], v[20:21], v[64:65]
	v_pk_fma_f32 v[32:33], v[22:23], v[34:35], v[32:33]
	v_pk_fma_f32 v[64:65], v[22:23], v[66:67], v[64:65]
	v_add_f32_e32 v34, v32, v33
	v_add_f32_e32 v245, v64, v65
	v_pk_fma_f32 v[12:13], v[20:21], v[12:13], v[20:21] neg_lo:[1,0,0] neg_hi:[1,0,0]
	v_add_f32_dpp v35, v34, v34 quad_perm:[1,0,3,2] row_mask:0xf bank_mask:0xf bound_ctrl:1
	v_pk_fma_f32 v[14:15], v[22:23], v[14:15], v[22:23] neg_lo:[1,0,0] neg_hi:[1,0,0]
	ds_read_b128 v[44:47], v91 offset:20416
	v_add_f32_dpp v34, v35, v35 quad_perm:[2,3,0,1] row_mask:0xf bank_mask:0xf bound_ctrl:1
	v_pk_fma_f32 v[12:13], v[36:37], v[16:17], v[12:13] op_sel_hi:[0,1,1]
	ds_read_b128 v[94:97], v91 offset:21184
	v_add_f32_dpp v35, v34, v34 row_half_mirror row_mask:0xf bank_mask:0xf bound_ctrl:1
	v_pk_fma_f32 v[14:15], v[36:37], v[18:19], v[14:15] op_sel_hi:[0,1,1]
	ds_read_b32 v38, v92 offset:21440
	v_add_f32_dpp v90, v35, v35 row_mirror row_mask:0xf bank_mask:0xf bound_ctrl:1
	ds_read_b128 v[64:67], v91 offset:20928
	v_pk_fma_f32 v[20:21], v[90:91], v[24:25], v[12:13] op_sel_hi:[0,1,1] neg_lo:[1,0,0] neg_hi:[1,0,0]
	v_pk_fma_f32 v[22:23], v[90:91], v[26:27], v[14:15] op_sel_hi:[0,1,1] neg_lo:[1,0,0] neg_hi:[1,0,0]
	s_waitcnt lgkmcnt(1)
	v_pk_mul_f32 v[94:95], v[20:21], v[94:95]
	v_pk_mul_f32 v[28:29], v[20:21], v[28:29]
	v_pk_fma_f32 v[94:95], v[22:23], v[96:97], v[94:95]
	v_pk_fma_f32 v[28:29], v[22:23], v[30:31], v[28:29]
	v_add_f32_e32 v96, v94, v95
	v_add_f32_e32 v246, v28, v29
	v_pk_fma_f32 v[40:41], v[20:21], v[40:41], v[20:21] neg_lo:[1,0,0] neg_hi:[1,0,0]
	v_add_f32_dpp v97, v96, v96 quad_perm:[1,0,3,2] row_mask:0xf bank_mask:0xf bound_ctrl:1
	v_pk_fma_f32 v[42:43], v[22:23], v[42:43], v[22:23] neg_lo:[1,0,0] neg_hi:[1,0,0]
	s_nop 0
	v_add_f32_dpp v96, v97, v97 quad_perm:[2,3,0,1] row_mask:0xf bank_mask:0xf bound_ctrl:1
	v_pk_fma_f32 v[40:41], v[38:39], v[44:45], v[40:41] op_sel_hi:[0,1,1]
	s_nop 0
	v_add_f32_dpp v97, v96, v96 row_half_mirror row_mask:0xf bank_mask:0xf bound_ctrl:1
	v_pk_fma_f32 v[42:43], v[38:39], v[46:47], v[42:43] op_sel_hi:[0,1,1]
	s_nop 0
	v_add_f32_dpp v90, v97, v97 row_mirror row_mask:0xf bank_mask:0xf bound_ctrl:1
	v_pk_fma_f32 v[20:21], v[90:91], v[60:61], v[40:41] op_sel_hi:[0,1,1] neg_lo:[1,0,0] neg_hi:[1,0,0]
	v_pk_fma_f32 v[22:23], v[90:91], v[62:63], v[42:43] op_sel_hi:[0,1,1] neg_lo:[1,0,0] neg_hi:[1,0,0]
	s_waitcnt lgkmcnt(0)
; #define DPP_ADD(v, ctrl) ((v) + __builtin_bit_cast(float, __builtin_amdgcn_update_dpp(0, __builtin_bit_cast(int, (v)), (ctrl), 0xf, 0xf, true)))
; #define SC_LSTORE(st_) { SC_S1(st_, 0, rg0) SC_S1(st_, 1, rg1) SC_S1(st_, 2, rg2) }
; __device__ __forceinline__ void rwkv_scan_unit(const Params& p, int unit, char* smem) {
;     ...
;             float y = yv[0] + yv[1];
;             if (u + 1 < SCH) {
;                 const f32x2 cv = __builtin_elementwise_fma(sB, (f32x2){nkk[2], nkk[3]}, sA * (f32x2){nkk[0], nkk[1]});
;                 float cn = cv[0] + cv[1];
;                 cn = DPP_ADD(cn, 0xB1);  y = DPP_ADD(y, 0xB1);
;                 cn = DPP_ADD(cn, 0x4E);  y = DPP_ADD(y, 0x4E);
;                 cn = DPP_ADD(cn, 0x141); y = DPP_ADD(y, 0x141);
;                 cn = DPP_ADD(cn, 0x140); y = DPP_ADD(y, 0x140);
;                 c = cn;
;             } else y = red16(y);
;             if (ks == 0) yl[u * 16] = y;
;             e4 = ne; kd4 = nkd; ka4 = nka; r4 = nr; kk4 = nkk; vv = nv;
;         }
;         s0 = sA[0]; s1 = sA[1]; s2 = sB[0]; s3 = sB[1];
;         __builtin_amdgcn_sched_barrier(0);
;         if (ci + 1 < NCH) { SC_LSTORE(((ci + 1) & 1) * STG) }
	v_pk_mul_f32 v[64:65], v[20:21], v[64:65]
	v_pk_fma_f32 v[64:65], v[22:23], v[66:67], v[64:65]
	s_nop 0
	v_add_f32_e32 v247, v64, v65
	s_mov_b32 s98, 0xaaaaaaaa
	s_mov_b32 s99, 0xaaaaaaaa
	s_mov_b32 s100, 0xcccccccc
	s_mov_b32 s101, 0xcccccccc
	v_add_f32_dpp v232, v232, v232 row_mirror row_mask:0xf bank_mask:0x3 bound_ctrl:1
	v_add_f32_dpp v233, v233, v233 row_mirror row_mask:0xf bank_mask:0x3 bound_ctrl:1
	v_add_f32_dpp v234, v234, v234 row_mirror row_mask:0xf bank_mask:0x3 bound_ctrl:1
	v_add_f32_dpp v235, v235, v235 row_mirror row_mask:0xf bank_mask:0x3 bound_ctrl:1
	v_add_f32_dpp v236, v236, v236 row_mirror row_mask:0xf bank_mask:0x3 bound_ctrl:1
	v_add_f32_dpp v237, v237, v237 row_mirror row_mask:0xf bank_mask:0x3 bound_ctrl:1
	v_add_f32_dpp v238, v238, v238 row_mirror row_mask:0xf bank_mask:0x3 bound_ctrl:1
	v_add_f32_dpp v239, v239, v239 row_mirror row_mask:0xf bank_mask:0x3 bound_ctrl:1
	v_add_f32_dpp v232, v240, v240 row_mirror row_mask:0xf bank_mask:0xc bound_ctrl:1
	v_add_f32_dpp v233, v241, v241 row_mirror row_mask:0xf bank_mask:0xc bound_ctrl:1
	v_add_f32_dpp v234, v242, v242 row_mirror row_mask:0xf bank_mask:0xc bound_ctrl:1
	v_add_f32_dpp v235, v243, v243 row_mirror row_mask:0xf bank_mask:0xc bound_ctrl:1
	v_add_f32_dpp v236, v244, v244 row_mirror row_mask:0xf bank_mask:0xc bound_ctrl:1
	v_add_f32_dpp v237, v245, v245 row_mirror row_mask:0xf bank_mask:0xc bound_ctrl:1
	v_add_f32_dpp v238, v246, v246 row_mirror row_mask:0xf bank_mask:0xc bound_ctrl:1
	v_add_f32_dpp v239, v247, v247 row_mirror row_mask:0xf bank_mask:0xc bound_ctrl:1
	v_add_f32_dpp v232, v232, v232 row_half_mirror row_mask:0xf bank_mask:0x5 bound_ctrl:1
	v_add_f32_dpp v233, v233, v233 row_half_mirror row_mask:0xf bank_mask:0x5 bound_ctrl:1
	v_add_f32_dpp v234, v234, v234 row_half_mirror row_mask:0xf bank_mask:0x5 bound_ctrl:1
	v_add_f32_dpp v235, v235, v235 row_half_mirror row_mask:0xf bank_mask:0x5 bound_ctrl:1
	v_add_f32_dpp v232, v236, v236 row_half_mirror row_mask:0xf bank_mask:0xa bound_ctrl:1
	v_add_f32_dpp v233, v237, v237 row_half_mirror row_mask:0xf bank_mask:0xa bound_ctrl:1
	v_add_f32_dpp v234, v238, v238 row_half_mirror row_mask:0xf bank_mask:0xa bound_ctrl:1
	v_add_f32_dpp v235, v239, v239 row_half_mirror row_mask:0xf bank_mask:0xa bound_ctrl:1
	v_cndmask_b32_e64 v240, v232, v234, s[100:101]
	v_cndmask_b32_e64 v241, v234, v232, s[100:101]
	v_cndmask_b32_e64 v242, v233, v235, s[100:101]
	v_cndmask_b32_e64 v243, v235, v233, s[100:101]
	s_nop 0
	v_add_f32_dpp v232, v241, v240 quad_perm:[2,3,0,1] row_mask:0xf bank_mask:0xf bound_ctrl:1
	v_add_f32_dpp v233, v243, v242 quad_perm:[2,3,0,1] row_mask:0xf bank_mask:0xf bound_ctrl:1
	s_nop 0
	v_cndmask_b32_e64 v240, v232, v233, s[98:99]
	v_cndmask_b32_e64 v241, v233, v232, s[98:99]
	v_add_u32_e32 v242, s52, v172
	s_nop 0
	v_add_f32_dpp v243, v241, v240 quad_perm:[1,0,3,2] row_mask:0xf bank_mask:0xf bound_ctrl:1
	ds_write_b32 v242, v243 offset:43008
	s_cmpk_eq_i32 s55, 0x10f0
	s_cbranch_scc1 .Lsc_p3_flush
	s_bitcmp1_b32 s64, 0
	s_cselect_b32 s0, 0x5400, 0
	s_waitcnt vmcnt(12)
	v_add3_u32 v16, s0, v74, v75
	v_cvt_f32_f16_sdwa v13, v160 dst_sel:DWORD dst_unused:UNUSED_PAD src0_sel:WORD_1
	v_cvt_f32_f16_e32 v12, v160
	v_cvt_f32_f16_sdwa v15, v161 dst_sel:DWORD dst_unused:UNUSED_PAD src0_sel:WORD_1
	v_cvt_f32_f16_e32 v14, v161
	ds_write_b128 v16, v[12:15]
	v_cvt_f32_f16_sdwa v13, v162 dst_sel:DWORD dst_unused:UNUSED_PAD src0_sel:WORD_1
	v_cvt_f32_f16_e32 v12, v162
	v_cvt_f32_f16_sdwa v15, v163 dst_sel:DWORD dst_unused:UNUSED_PAD src0_sel:WORD_1
	v_cvt_f32_f16_e32 v14, v163
	ds_write_b128 v16, v[12:15] offset:16
	v_add3_u32 v16, s0, v76, v77
	v_cvt_f32_f16_sdwa v13, v164 dst_sel:DWORD dst_unused:UNUSED_PAD src0_sel:WORD_1
	v_cvt_f32_f16_e32 v12, v164
	v_cvt_f32_f16_sdwa v15, v165 dst_sel:DWORD dst_unused:UNUSED_PAD src0_sel:WORD_1
	v_cvt_f32_f16_e32 v14, v165
	ds_write_b128 v16, v[12:15]
	v_cvt_f32_f16_sdwa v13, v166 dst_sel:DWORD dst_unused:UNUSED_PAD src0_sel:WORD_1
	v_cvt_f32_f16_e32 v12, v166
	v_cvt_f32_f16_sdwa v15, v167 dst_sel:DWORD dst_unused:UNUSED_PAD src0_sel:WORD_1
	v_cvt_f32_f16_e32 v14, v167
	ds_write_b128 v16, v[12:15] offset:16
	v_add3_u32 v16, s0, v78, v79
	v_cvt_f32_f16_sdwa v13, v168 dst_sel:DWORD dst_unused:UNUSED_PAD src0_sel:WORD_1
	v_cvt_f32_f16_e32 v12, v168
	v_cvt_f32_f16_sdwa v15, v169 dst_sel:DWORD dst_unused:UNUSED_PAD src0_sel:WORD_1
	v_cvt_f32_f16_e32 v14, v169
	ds_write_b128 v16, v[12:15]
	v_cvt_f32_f16_sdwa v13, v170 dst_sel:DWORD dst_unused:UNUSED_PAD src0_sel:WORD_1
	v_cvt_f32_f16_e32 v12, v170
	v_cvt_f32_f16_sdwa v15, v171 dst_sel:DWORD dst_unused:UNUSED_PAD src0_sel:WORD_1
	v_cvt_f32_f16_e32 v14, v171
	ds_write_b128 v16, v[12:15] offset:16
